# GEMM K-loops: additionally no priority drop/raise pair in the middle of each 32-MFMA block
# baseline (speedup 1.0000x reference)
.LBB0_122:
	ds_read_b128 v[152:155], v148
	ds_read_b128 v[156:159], v148 offset:1024
	ds_read_b128 v[160:163], v148 offset:2048
	ds_read_b128 v[164:167], v148 offset:3072
	ds_read_b128 v[168:171], v149
	ds_read_b128 v[172:175], v149 offset:1024
	ds_read_b128 v[176:179], v149 offset:2048
	ds_read_b128 v[180:183], v149 offset:3072
	s_add_u32 s44, s36, 0xfff80080
	s_addc_u32 s45, s37, -1
	s_cmp_eq_u32 s54, 28
	s_cselect_b32 s53, s25, s45
	s_cselect_b32 s52, s48, s44
	s_cselect_b32 s45, s23, s51
	s_cselect_b32 s44, s49, s50
	v_lshl_add_u64 v[216:217], s[36:37], 0, v[140:141]
	s_add_i32 m0, s18, 0xc000
	ds_read_b128 v[184:187], v150
	ds_read_b128 v[188:191], v150 offset:1024
	ds_read_b128 v[192:195], v150 offset:2048
	ds_read_b128 v[196:199], v150 offset:3072
	ds_read_b128 v[200:203], v150 offset:4096
	ds_read_b128 v[204:207], v150 offset:5120
	ds_read_b128 v[208:211], v150 offset:6144
	ds_read_b128 v[212:215], v150 offset:7168
	global_load_lds_dwordx4 v[216:217], off
	v_lshl_add_u64 v[216:217], s[36:37], 0, v[138:139]
	s_add_i32 m0, s18, 0xe000
	s_nop 0
	global_load_lds_dwordx4 v[216:217], off
	s_waitcnt vmcnt(8)
	s_waitcnt lgkmcnt(0)
	s_setprio 1
	s_barrier
	v_mfma_f32_16x16x32_bf16 v[126:129], v[152:155], v[184:187], v[126:129]
	v_mfma_f32_16x16x32_bf16 v[122:125], v[160:163], v[184:187], v[122:125]
	v_mfma_f32_16x16x32_bf16 v[110:113], v[152:155], v[192:195], v[110:113]
	v_mfma_f32_16x16x32_bf16 v[106:109], v[160:163], v[192:195], v[106:109]
	v_mfma_f32_16x16x32_bf16 v[94:97], v[152:155], v[200:203], v[94:97]
	v_mfma_f32_16x16x32_bf16 v[90:93], v[160:163], v[200:203], v[90:93]
	v_mfma_f32_16x16x32_bf16 v[78:81], v[152:155], v[208:211], v[78:81]
	v_mfma_f32_16x16x32_bf16 v[74:77], v[160:163], v[208:211], v[74:77]
	v_mfma_f32_16x16x32_bf16 v[126:129], v[156:159], v[188:191], v[126:129]
	v_mfma_f32_16x16x32_bf16 v[122:125], v[164:167], v[188:191], v[122:125]
	v_mfma_f32_16x16x32_bf16 v[110:113], v[156:159], v[196:199], v[110:113]
	v_mfma_f32_16x16x32_bf16 v[106:109], v[164:167], v[196:199], v[106:109]
	v_mfma_f32_16x16x32_bf16 v[94:97], v[156:159], v[204:207], v[94:97]
	v_mfma_f32_16x16x32_bf16 v[90:93], v[164:167], v[204:207], v[90:93]
	v_mfma_f32_16x16x32_bf16 v[78:81], v[156:159], v[212:215], v[78:81]
	v_mfma_f32_16x16x32_bf16 v[74:77], v[164:167], v[212:215], v[74:77]
	v_mfma_f32_16x16x32_bf16 v[118:121], v[168:171], v[184:187], v[118:121]
	v_mfma_f32_16x16x32_bf16 v[114:117], v[176:179], v[184:187], v[114:117]
	v_mfma_f32_16x16x32_bf16 v[102:105], v[168:171], v[192:195], v[102:105]
	v_mfma_f32_16x16x32_bf16 v[98:101], v[176:179], v[192:195], v[98:101]
	v_mfma_f32_16x16x32_bf16 v[86:89], v[168:171], v[200:203], v[86:89]
	v_mfma_f32_16x16x32_bf16 v[82:85], v[176:179], v[200:203], v[82:85]
	v_mfma_f32_16x16x32_bf16 v[70:73], v[168:171], v[208:211], v[70:73]
	v_mfma_f32_16x16x32_bf16 v[66:69], v[176:179], v[208:211], v[66:69]
	v_mfma_f32_16x16x32_bf16 v[118:121], v[172:175], v[188:191], v[118:121]
	v_mfma_f32_16x16x32_bf16 v[114:117], v[180:183], v[188:191], v[114:117]
	v_mfma_f32_16x16x32_bf16 v[102:105], v[172:175], v[196:199], v[102:105]
	v_mfma_f32_16x16x32_bf16 v[98:101], v[180:183], v[196:199], v[98:101]
	v_mfma_f32_16x16x32_bf16 v[86:89], v[172:175], v[204:207], v[86:89]
	v_mfma_f32_16x16x32_bf16 v[82:85], v[180:183], v[204:207], v[82:85]
	v_mfma_f32_16x16x32_bf16 v[70:73], v[172:175], v[212:215], v[70:73]
	v_mfma_f32_16x16x32_bf16 v[66:69], v[180:183], v[212:215], v[66:69]
	s_barrier
	s_setprio 0
	s_add_i32 s55, s42, s13
	v_lshl_add_u64 v[216:217], s[44:45], 0, v[134:135]
	s_mov_b32 m0, s55
	ds_read_b128 v[184:187], v150 offset:16384
	ds_read_b128 v[188:191], v150 offset:17408
	ds_read_b128 v[192:195], v150 offset:18432
	ds_read_b128 v[196:199], v150 offset:19456
	ds_read_b128 v[200:203], v150 offset:20480
	ds_read_b128 v[204:207], v150 offset:21504
	ds_read_b128 v[208:211], v150 offset:22528
	ds_read_b128 v[212:215], v150 offset:23552
	global_load_lds_dwordx4 v[216:217], off
	s_add_i32 m0, s55, 0x2000
	s_add_u32 s68, s44, 0x80000
	v_lshl_add_u64 v[218:219], s[44:45], 0, v[130:131]
	s_addc_u32 s69, s45, 0
	s_add_i32 s55, s43, s13
	global_load_lds_dwordx4 v[218:219], off
	v_lshl_add_u64 v[220:221], s[68:69], 0, v[134:135]
	s_mov_b32 m0, s55
	v_lshl_add_u64 v[222:223], s[52:53], 0, v[132:133]
	global_load_lds_dwordx4 v[220:221], off
	v_lshl_add_u64 v[220:221], s[68:69], 0, v[130:131]
	s_add_i32 m0, s55, 0x2000
	s_nop 0
	global_load_lds_dwordx4 v[220:221], off
	v_lshl_add_u64 v[220:221], s[52:53], 0, v[136:137]
	s_mov_b32 m0, s18
	s_nop 0
	global_load_lds_dwordx4 v[220:221], off
	s_mov_b32 m0, s19
	s_nop 0
	global_load_lds_dwordx4 v[222:223], off
	s_waitcnt vmcnt(8)
	s_waitcnt lgkmcnt(0)
	s_setprio 1
	s_barrier
	v_mfma_f32_16x16x32_bf16 v[62:65], v[152:155], v[184:187], v[62:65]
	v_mfma_f32_16x16x32_bf16 v[58:61], v[160:163], v[184:187], v[58:61]
	v_mfma_f32_16x16x32_bf16 v[46:49], v[152:155], v[192:195], v[46:49]
	v_mfma_f32_16x16x32_bf16 v[42:45], v[160:163], v[192:195], v[42:45]
	v_mfma_f32_16x16x32_bf16 v[30:33], v[152:155], v[200:203], v[30:33]
	v_mfma_f32_16x16x32_bf16 v[26:29], v[160:163], v[200:203], v[26:29]
	v_mfma_f32_16x16x32_bf16 v[14:17], v[152:155], v[208:211], v[14:17]
	v_mfma_f32_16x16x32_bf16 v[10:13], v[160:163], v[208:211], v[10:13]
	v_mfma_f32_16x16x32_bf16 v[62:65], v[156:159], v[188:191], v[62:65]
	v_mfma_f32_16x16x32_bf16 v[58:61], v[164:167], v[188:191], v[58:61]
	v_mfma_f32_16x16x32_bf16 v[46:49], v[156:159], v[196:199], v[46:49]
	v_mfma_f32_16x16x32_bf16 v[42:45], v[164:167], v[196:199], v[42:45]
	v_mfma_f32_16x16x32_bf16 v[30:33], v[156:159], v[204:207], v[30:33]
	v_mfma_f32_16x16x32_bf16 v[26:29], v[164:167], v[204:207], v[26:29]
	v_mfma_f32_16x16x32_bf16 v[14:17], v[156:159], v[212:215], v[14:17]
	v_mfma_f32_16x16x32_bf16 v[10:13], v[164:167], v[212:215], v[10:13]
	v_mfma_f32_16x16x32_bf16 v[54:57], v[168:171], v[184:187], v[54:57]
	v_mfma_f32_16x16x32_bf16 v[50:53], v[176:179], v[184:187], v[50:53]
	v_mfma_f32_16x16x32_bf16 v[38:41], v[168:171], v[192:195], v[38:41]
	v_mfma_f32_16x16x32_bf16 v[34:37], v[176:179], v[192:195], v[34:37]
	v_mfma_f32_16x16x32_bf16 v[22:25], v[168:171], v[200:203], v[22:25]
	v_mfma_f32_16x16x32_bf16 v[18:21], v[176:179], v[200:203], v[18:21]
	v_mfma_f32_16x16x32_bf16 v[6:9], v[168:171], v[208:211], v[6:9]
	v_mfma_f32_16x16x32_bf16 v[2:5], v[176:179], v[208:211], v[2:5]
	v_mfma_f32_16x16x32_bf16 v[54:57], v[172:175], v[188:191], v[54:57]
	v_mfma_f32_16x16x32_bf16 v[50:53], v[180:183], v[188:191], v[50:53]
	v_mfma_f32_16x16x32_bf16 v[38:41], v[172:175], v[196:199], v[38:41]
	v_mfma_f32_16x16x32_bf16 v[34:37], v[180:183], v[196:199], v[34:37]
	v_mfma_f32_16x16x32_bf16 v[22:25], v[172:175], v[204:207], v[22:25]
	v_mfma_f32_16x16x32_bf16 v[18:21], v[180:183], v[204:207], v[18:21]
	v_mfma_f32_16x16x32_bf16 v[6:9], v[172:175], v[212:215], v[6:9]
	v_mfma_f32_16x16x32_bf16 v[2:5], v[180:183], v[212:215], v[2:5]
	s_barrier
	s_setprio 0
	s_add_i32 s55, 0, 0x18000
	v_add_u32_e32 v151, s55, v147
	s_add_i32 s68, 0, 0x1c000
	ds_read_b128 v[152:155], v151
	ds_read_b128 v[156:159], v151 offset:1024
	ds_read_b128 v[160:163], v151 offset:2048
	ds_read_b128 v[164:167], v151 offset:3072
	v_add_u32_e32 v151, s68, v147
	ds_read_b128 v[168:171], v151
	ds_read_b128 v[172:175], v151 offset:1024
	ds_read_b128 v[176:179], v151 offset:2048
	ds_read_b128 v[180:183], v151 offset:3072
	s_add_u32 s52, s52, 0x80000
	s_addc_u32 s53, s53, 0
	s_mov_b32 m0, s31
	v_lshl_add_u64 v[224:225], s[52:53], 0, v[136:137]
	ds_read_b128 v[184:187], v150 offset:32768
	ds_read_b128 v[188:191], v150 offset:33792
	ds_read_b128 v[192:195], v150 offset:34816
	ds_read_b128 v[196:199], v150 offset:35840
	ds_read_b128 v[200:203], v150 offset:36864
	ds_read_b128 v[204:207], v150 offset:37888
	ds_read_b128 v[208:211], v150 offset:38912
	ds_read_b128 v[212:215], v150 offset:39936
	global_load_lds_dwordx4 v[224:225], off
	v_lshl_add_u64 v[224:225], s[52:53], 0, v[132:133]
	s_mov_b32 m0, s33
	s_nop 0
	global_load_lds_dwordx4 v[224:225], off
	s_waitcnt vmcnt(8)
	s_waitcnt lgkmcnt(0)
	s_setprio 1
	s_barrier
	v_mfma_f32_16x16x32_bf16 v[126:129], v[152:155], v[184:187], v[126:129]
	v_mfma_f32_16x16x32_bf16 v[122:125], v[160:163], v[184:187], v[122:125]
	v_mfma_f32_16x16x32_bf16 v[110:113], v[152:155], v[192:195], v[110:113]
	v_mfma_f32_16x16x32_bf16 v[106:109], v[160:163], v[192:195], v[106:109]
	v_mfma_f32_16x16x32_bf16 v[94:97], v[152:155], v[200:203], v[94:97]
	v_mfma_f32_16x16x32_bf16 v[90:93], v[160:163], v[200:203], v[90:93]
	v_mfma_f32_16x16x32_bf16 v[78:81], v[152:155], v[208:211], v[78:81]
	v_mfma_f32_16x16x32_bf16 v[74:77], v[160:163], v[208:211], v[74:77]
	v_mfma_f32_16x16x32_bf16 v[126:129], v[156:159], v[188:191], v[126:129]
	v_mfma_f32_16x16x32_bf16 v[122:125], v[164:167], v[188:191], v[122:125]
	v_mfma_f32_16x16x32_bf16 v[110:113], v[156:159], v[196:199], v[110:113]
	v_mfma_f32_16x16x32_bf16 v[106:109], v[164:167], v[196:199], v[106:109]
	v_mfma_f32_16x16x32_bf16 v[94:97], v[156:159], v[204:207], v[94:97]
	v_mfma_f32_16x16x32_bf16 v[90:93], v[164:167], v[204:207], v[90:93]
	v_mfma_f32_16x16x32_bf16 v[78:81], v[156:159], v[212:215], v[78:81]
	v_mfma_f32_16x16x32_bf16 v[74:77], v[164:167], v[212:215], v[74:77]
	v_mfma_f32_16x16x32_bf16 v[118:121], v[168:171], v[184:187], v[118:121]
	v_mfma_f32_16x16x32_bf16 v[114:117], v[176:179], v[184:187], v[114:117]
	v_mfma_f32_16x16x32_bf16 v[102:105], v[168:171], v[192:195], v[102:105]
	v_mfma_f32_16x16x32_bf16 v[98:101], v[176:179], v[192:195], v[98:101]
	v_mfma_f32_16x16x32_bf16 v[86:89], v[168:171], v[200:203], v[86:89]
	v_mfma_f32_16x16x32_bf16 v[82:85], v[176:179], v[200:203], v[82:85]
	v_mfma_f32_16x16x32_bf16 v[70:73], v[168:171], v[208:211], v[70:73]
	v_mfma_f32_16x16x32_bf16 v[66:69], v[176:179], v[208:211], v[66:69]
	v_mfma_f32_16x16x32_bf16 v[118:121], v[172:175], v[188:191], v[118:121]
	v_mfma_f32_16x16x32_bf16 v[114:117], v[180:183], v[188:191], v[114:117]
	v_mfma_f32_16x16x32_bf16 v[102:105], v[172:175], v[196:199], v[102:105]
	v_mfma_f32_16x16x32_bf16 v[98:101], v[180:183], v[196:199], v[98:101]
	v_mfma_f32_16x16x32_bf16 v[86:89], v[172:175], v[204:207], v[86:89]
	v_mfma_f32_16x16x32_bf16 v[82:85], v[180:183], v[204:207], v[82:85]
	v_mfma_f32_16x16x32_bf16 v[70:73], v[172:175], v[212:215], v[70:73]
	v_mfma_f32_16x16x32_bf16 v[66:69], v[180:183], v[212:215], v[66:69]
	s_barrier
	s_setprio 0
	s_add_i32 s52, s55, s13
	v_lshl_add_u64 v[216:217], v[216:217], 0, s[16:17]
	s_mov_b32 m0, s52
	ds_read_b128 v[184:187], v150 offset:49152
	ds_read_b128 v[188:191], v150 offset:50176
	ds_read_b128 v[192:195], v150 offset:51200
	ds_read_b128 v[196:199], v150 offset:52224
	ds_read_b128 v[200:203], v150 offset:53248
	ds_read_b128 v[204:207], v150 offset:54272
	ds_read_b128 v[208:211], v150 offset:55296
	ds_read_b128 v[212:215], v150 offset:56320
	global_load_lds_dwordx4 v[216:217], off
	s_add_i32 m0, s52, 0x2000
	s_add_u32 s44, s44, 0x80080
	v_lshl_add_u64 v[216:217], v[218:219], 0, s[16:17]
	s_addc_u32 s45, s45, 0
	s_add_i32 s52, s68, s13
	global_load_lds_dwordx4 v[216:217], off
	v_lshl_add_u64 v[216:217], s[44:45], 0, v[134:135]
	s_mov_b32 m0, s52
	s_nop 0
	global_load_lds_dwordx4 v[216:217], off
	v_lshl_add_u64 v[216:217], s[44:45], 0, v[130:131]
	s_add_i32 m0, s52, 0x2000
	s_nop 0
	global_load_lds_dwordx4 v[216:217], off
	v_lshl_add_u64 v[216:217], v[220:221], 0, s[16:17]
	s_mov_b32 m0, s38
	s_nop 0
	global_load_lds_dwordx4 v[216:217], off
	v_lshl_add_u64 v[216:217], v[222:223], 0, s[16:17]
	s_mov_b32 m0, s39
	s_nop 0
	global_load_lds_dwordx4 v[216:217], off
	s_waitcnt vmcnt(8)
	s_waitcnt lgkmcnt(0)
	s_setprio 1
	s_barrier
	v_mfma_f32_16x16x32_bf16 v[62:65], v[152:155], v[184:187], v[62:65]
	v_mfma_f32_16x16x32_bf16 v[58:61], v[160:163], v[184:187], v[58:61]
	v_mfma_f32_16x16x32_bf16 v[46:49], v[152:155], v[192:195], v[46:49]
	v_mfma_f32_16x16x32_bf16 v[42:45], v[160:163], v[192:195], v[42:45]
	v_mfma_f32_16x16x32_bf16 v[30:33], v[152:155], v[200:203], v[30:33]
	v_mfma_f32_16x16x32_bf16 v[26:29], v[160:163], v[200:203], v[26:29]
	v_mfma_f32_16x16x32_bf16 v[14:17], v[152:155], v[208:211], v[14:17]
	v_mfma_f32_16x16x32_bf16 v[10:13], v[160:163], v[208:211], v[10:13]
	v_mfma_f32_16x16x32_bf16 v[62:65], v[156:159], v[188:191], v[62:65]
	v_mfma_f32_16x16x32_bf16 v[58:61], v[164:167], v[188:191], v[58:61]
	v_mfma_f32_16x16x32_bf16 v[46:49], v[156:159], v[196:199], v[46:49]
	v_mfma_f32_16x16x32_bf16 v[42:45], v[164:167], v[196:199], v[42:45]
	v_mfma_f32_16x16x32_bf16 v[30:33], v[156:159], v[204:207], v[30:33]
	v_mfma_f32_16x16x32_bf16 v[26:29], v[164:167], v[204:207], v[26:29]
	v_mfma_f32_16x16x32_bf16 v[14:17], v[156:159], v[212:215], v[14:17]
	v_mfma_f32_16x16x32_bf16 v[10:13], v[164:167], v[212:215], v[10:13]
	v_mfma_f32_16x16x32_bf16 v[54:57], v[168:171], v[184:187], v[54:57]
	v_mfma_f32_16x16x32_bf16 v[50:53], v[176:179], v[184:187], v[50:53]
	v_mfma_f32_16x16x32_bf16 v[38:41], v[168:171], v[192:195], v[38:41]
	v_mfma_f32_16x16x32_bf16 v[34:37], v[176:179], v[192:195], v[34:37]
	v_mfma_f32_16x16x32_bf16 v[22:25], v[168:171], v[200:203], v[22:25]
	v_mfma_f32_16x16x32_bf16 v[18:21], v[176:179], v[200:203], v[18:21]
	v_mfma_f32_16x16x32_bf16 v[6:9], v[168:171], v[208:211], v[6:9]
	v_mfma_f32_16x16x32_bf16 v[2:5], v[176:179], v[208:211], v[2:5]
	v_mfma_f32_16x16x32_bf16 v[54:57], v[172:175], v[188:191], v[54:57]
	v_mfma_f32_16x16x32_bf16 v[50:53], v[180:183], v[188:191], v[50:53]
	v_mfma_f32_16x16x32_bf16 v[38:41], v[172:175], v[196:199], v[38:41]
	v_mfma_f32_16x16x32_bf16 v[34:37], v[180:183], v[196:199], v[34:37]
	v_mfma_f32_16x16x32_bf16 v[22:25], v[172:175], v[204:207], v[22:25]
	v_mfma_f32_16x16x32_bf16 v[18:21], v[180:183], v[204:207], v[18:21]
	v_mfma_f32_16x16x32_bf16 v[6:9], v[172:175], v[212:215], v[6:9]
	v_mfma_f32_16x16x32_bf16 v[2:5], v[180:183], v[212:215], v[2:5]
	s_barrier
	s_setprio 0
	s_add_i32 s54, s54, 2
	s_add_u32 s50, s50, 0x100
	s_addc_u32 s51, s51, 0
	s_add_u32 s36, s36, 0x100
	s_addc_u32 s37, s37, 0
	s_cmp_gt_u32 s54, 29
	s_cbranch_scc0 .LBB0_122
	s_and_b64 vcc, exec, s[20:21]
	s_cbranch_vccz .LBB0_125
	s_barrier

.LBB0_139:
	ds_read_b128 v[150:153], v146
	ds_read_b128 v[154:157], v146 offset:1024
	ds_read_b128 v[158:161], v146 offset:2048
	ds_read_b128 v[162:165], v146 offset:3072
	ds_read_b128 v[166:169], v147
	ds_read_b128 v[170:173], v147 offset:1024
	ds_read_b128 v[174:177], v147 offset:2048
	ds_read_b128 v[178:181], v147 offset:3072
	s_add_u32 s44, s36, 0xfff80080
	s_addc_u32 s45, s37, -1
	s_cmp_eq_u32 s68, 28
	s_cselect_b32 s53, s23, s45
	s_cselect_b32 s52, s50, s44
	s_cselect_b32 s45, s21, s55
	s_cselect_b32 s44, s51, s54
	v_lshl_add_u64 v[142:143], s[36:37], 0, v[140:141]
	s_add_i32 m0, s34, 0xc000
	ds_read_b128 v[182:185], v148
	ds_read_b128 v[186:189], v148 offset:1024
	ds_read_b128 v[190:193], v148 offset:2048
	ds_read_b128 v[194:197], v148 offset:3072
	ds_read_b128 v[198:201], v148 offset:4096
	ds_read_b128 v[202:205], v148 offset:5120
	ds_read_b128 v[206:209], v148 offset:6144
	ds_read_b128 v[210:213], v148 offset:7168
	global_load_lds_dwordx4 v[142:143], off
	v_lshl_add_u64 v[142:143], s[36:37], 0, v[138:139]
	s_add_i32 m0, s34, 0xe000
	s_nop 0
	global_load_lds_dwordx4 v[142:143], off
	s_waitcnt vmcnt(8)
	s_waitcnt lgkmcnt(0)
	s_setprio 1
	s_barrier
	v_mfma_f32_16x16x32_bf16 v[126:129], v[150:153], v[182:185], v[126:129]
	v_mfma_f32_16x16x32_bf16 v[122:125], v[158:161], v[182:185], v[122:125]
	v_mfma_f32_16x16x32_bf16 v[118:121], v[150:153], v[190:193], v[118:121]
	v_mfma_f32_16x16x32_bf16 v[110:113], v[158:161], v[190:193], v[110:113]
	v_mfma_f32_16x16x32_bf16 v[102:105], v[150:153], v[198:201], v[102:105]
	v_mfma_f32_16x16x32_bf16 v[94:97], v[158:161], v[198:201], v[94:97]
	v_mfma_f32_16x16x32_bf16 v[86:89], v[150:153], v[206:209], v[86:89]
	v_mfma_f32_16x16x32_bf16 v[78:81], v[158:161], v[206:209], v[78:81]
	v_mfma_f32_16x16x32_bf16 v[126:129], v[154:157], v[186:189], v[126:129]
	v_mfma_f32_16x16x32_bf16 v[122:125], v[162:165], v[186:189], v[122:125]
	v_mfma_f32_16x16x32_bf16 v[118:121], v[154:157], v[194:197], v[118:121]
	v_mfma_f32_16x16x32_bf16 v[110:113], v[162:165], v[194:197], v[110:113]
	v_mfma_f32_16x16x32_bf16 v[102:105], v[154:157], v[202:205], v[102:105]
	v_mfma_f32_16x16x32_bf16 v[94:97], v[162:165], v[202:205], v[94:97]
	v_mfma_f32_16x16x32_bf16 v[86:89], v[154:157], v[210:213], v[86:89]
	v_mfma_f32_16x16x32_bf16 v[78:81], v[162:165], v[210:213], v[78:81]
	v_mfma_f32_16x16x32_bf16 v[114:117], v[166:169], v[182:185], v[114:117]
	v_mfma_f32_16x16x32_bf16 v[106:109], v[174:177], v[182:185], v[106:109]
	v_mfma_f32_16x16x32_bf16 v[98:101], v[166:169], v[190:193], v[98:101]
	v_mfma_f32_16x16x32_bf16 v[90:93], v[174:177], v[190:193], v[90:93]
	v_mfma_f32_16x16x32_bf16 v[82:85], v[166:169], v[198:201], v[82:85]
	v_mfma_f32_16x16x32_bf16 v[74:77], v[174:177], v[198:201], v[74:77]
	v_mfma_f32_16x16x32_bf16 v[70:73], v[166:169], v[206:209], v[70:73]
	v_mfma_f32_16x16x32_bf16 v[66:69], v[174:177], v[206:209], v[66:69]
	v_mfma_f32_16x16x32_bf16 v[114:117], v[170:173], v[186:189], v[114:117]
	v_mfma_f32_16x16x32_bf16 v[106:109], v[178:181], v[186:189], v[106:109]
	v_mfma_f32_16x16x32_bf16 v[98:101], v[170:173], v[194:197], v[98:101]
	v_mfma_f32_16x16x32_bf16 v[90:93], v[178:181], v[194:197], v[90:93]
	v_mfma_f32_16x16x32_bf16 v[82:85], v[170:173], v[202:205], v[82:85]
	v_mfma_f32_16x16x32_bf16 v[74:77], v[178:181], v[202:205], v[74:77]
	v_mfma_f32_16x16x32_bf16 v[70:73], v[170:173], v[210:213], v[70:73]
	v_mfma_f32_16x16x32_bf16 v[66:69], v[178:181], v[210:213], v[66:69]
	s_barrier
	s_setprio 0
	s_add_i32 s69, s48, s19
	v_lshl_add_u64 v[142:143], s[44:45], 0, v[134:135]
	s_mov_b32 m0, s69
	ds_read_b128 v[182:185], v148 offset:16384
	ds_read_b128 v[186:189], v148 offset:17408
	ds_read_b128 v[190:193], v148 offset:18432
	ds_read_b128 v[194:197], v148 offset:19456
	ds_read_b128 v[198:201], v148 offset:20480
	ds_read_b128 v[202:205], v148 offset:21504
	ds_read_b128 v[206:209], v148 offset:22528
	ds_read_b128 v[210:213], v148 offset:23552
	global_load_lds_dwordx4 v[142:143], off
	s_add_i32 m0, s69, 0x2000
	s_add_u32 s70, s44, 0x80000
	v_lshl_add_u64 v[214:215], s[44:45], 0, v[130:131]
	s_addc_u32 s71, s45, 0
	s_add_i32 s69, s49, s19
	global_load_lds_dwordx4 v[214:215], off
	v_lshl_add_u64 v[216:217], s[70:71], 0, v[134:135]
	s_mov_b32 m0, s69
	v_lshl_add_u64 v[218:219], s[52:53], 0, v[132:133]
	global_load_lds_dwordx4 v[216:217], off
	v_lshl_add_u64 v[216:217], s[70:71], 0, v[130:131]
	s_add_i32 m0, s69, 0x2000
	s_nop 0
	global_load_lds_dwordx4 v[216:217], off
	v_lshl_add_u64 v[216:217], s[52:53], 0, v[136:137]
	s_mov_b32 m0, s34
	s_nop 0
	global_load_lds_dwordx4 v[216:217], off
	s_mov_b32 m0, s35
	s_nop 0
	global_load_lds_dwordx4 v[218:219], off
	s_waitcnt vmcnt(8)
	s_waitcnt lgkmcnt(0)
	s_setprio 1
	s_barrier
	v_mfma_f32_16x16x32_bf16 v[62:65], v[150:153], v[182:185], v[62:65]
	v_mfma_f32_16x16x32_bf16 v[58:61], v[158:161], v[182:185], v[58:61]
	v_mfma_f32_16x16x32_bf16 v[54:57], v[150:153], v[190:193], v[54:57]
	v_mfma_f32_16x16x32_bf16 v[46:49], v[158:161], v[190:193], v[46:49]
	v_mfma_f32_16x16x32_bf16 v[38:41], v[150:153], v[198:201], v[38:41]
	v_mfma_f32_16x16x32_bf16 v[30:33], v[158:161], v[198:201], v[30:33]
	v_mfma_f32_16x16x32_bf16 v[22:25], v[150:153], v[206:209], v[22:25]
	v_mfma_f32_16x16x32_bf16 v[14:17], v[158:161], v[206:209], v[14:17]
	v_mfma_f32_16x16x32_bf16 v[62:65], v[154:157], v[186:189], v[62:65]
	v_mfma_f32_16x16x32_bf16 v[58:61], v[162:165], v[186:189], v[58:61]
	v_mfma_f32_16x16x32_bf16 v[54:57], v[154:157], v[194:197], v[54:57]
	v_mfma_f32_16x16x32_bf16 v[46:49], v[162:165], v[194:197], v[46:49]
	v_mfma_f32_16x16x32_bf16 v[38:41], v[154:157], v[202:205], v[38:41]
	v_mfma_f32_16x16x32_bf16 v[30:33], v[162:165], v[202:205], v[30:33]
	v_mfma_f32_16x16x32_bf16 v[22:25], v[154:157], v[210:213], v[22:25]
	v_mfma_f32_16x16x32_bf16 v[14:17], v[162:165], v[210:213], v[14:17]
	v_mfma_f32_16x16x32_bf16 v[50:53], v[166:169], v[182:185], v[50:53]
	v_mfma_f32_16x16x32_bf16 v[42:45], v[174:177], v[182:185], v[42:45]
	v_mfma_f32_16x16x32_bf16 v[34:37], v[166:169], v[190:193], v[34:37]
	v_mfma_f32_16x16x32_bf16 v[26:29], v[174:177], v[190:193], v[26:29]
	v_mfma_f32_16x16x32_bf16 v[18:21], v[166:169], v[198:201], v[18:21]
	v_mfma_f32_16x16x32_bf16 v[10:13], v[174:177], v[198:201], v[10:13]
	v_mfma_f32_16x16x32_bf16 v[6:9], v[166:169], v[206:209], v[6:9]
	v_mfma_f32_16x16x32_bf16 v[2:5], v[174:177], v[206:209], v[2:5]
	v_mfma_f32_16x16x32_bf16 v[50:53], v[170:173], v[186:189], v[50:53]
	v_mfma_f32_16x16x32_bf16 v[42:45], v[178:181], v[186:189], v[42:45]
	v_mfma_f32_16x16x32_bf16 v[34:37], v[170:173], v[194:197], v[34:37]
	v_mfma_f32_16x16x32_bf16 v[26:29], v[178:181], v[194:197], v[26:29]
	v_mfma_f32_16x16x32_bf16 v[18:21], v[170:173], v[202:205], v[18:21]
	v_mfma_f32_16x16x32_bf16 v[10:13], v[178:181], v[202:205], v[10:13]
	v_mfma_f32_16x16x32_bf16 v[6:9], v[170:173], v[210:213], v[6:9]
	v_mfma_f32_16x16x32_bf16 v[2:5], v[178:181], v[210:213], v[2:5]
	s_barrier
	s_setprio 0
	s_add_i32 s69, 0, 0x18000
	v_add_u32_e32 v149, s69, v145
	s_add_i32 s70, 0, 0x1c000
	ds_read_b128 v[150:153], v149
	ds_read_b128 v[154:157], v149 offset:1024
	ds_read_b128 v[158:161], v149 offset:2048
	ds_read_b128 v[162:165], v149 offset:3072
	v_add_u32_e32 v149, s70, v145
	ds_read_b128 v[166:169], v149
	ds_read_b128 v[170:173], v149 offset:1024
	ds_read_b128 v[174:177], v149 offset:2048
	ds_read_b128 v[178:181], v149 offset:3072
	s_add_u32 s52, s52, 0x80000
	s_addc_u32 s53, s53, 0
	s_mov_b32 m0, s38
	v_lshl_add_u64 v[220:221], s[52:53], 0, v[136:137]
	ds_read_b128 v[182:185], v148 offset:32768
	ds_read_b128 v[186:189], v148 offset:33792
	ds_read_b128 v[190:193], v148 offset:34816
	ds_read_b128 v[194:197], v148 offset:35840
	ds_read_b128 v[198:201], v148 offset:36864
	ds_read_b128 v[202:205], v148 offset:37888
	ds_read_b128 v[206:209], v148 offset:38912
	ds_read_b128 v[210:213], v148 offset:39936
	global_load_lds_dwordx4 v[220:221], off
	v_lshl_add_u64 v[220:221], s[52:53], 0, v[132:133]
	s_mov_b32 m0, s39
	s_nop 0
	global_load_lds_dwordx4 v[220:221], off
	s_waitcnt vmcnt(8)
	s_waitcnt lgkmcnt(0)
	s_setprio 1
	s_barrier
	v_mfma_f32_16x16x32_bf16 v[126:129], v[150:153], v[182:185], v[126:129]
	v_mfma_f32_16x16x32_bf16 v[122:125], v[158:161], v[182:185], v[122:125]
	v_mfma_f32_16x16x32_bf16 v[118:121], v[150:153], v[190:193], v[118:121]
	v_mfma_f32_16x16x32_bf16 v[110:113], v[158:161], v[190:193], v[110:113]
	v_mfma_f32_16x16x32_bf16 v[102:105], v[150:153], v[198:201], v[102:105]
	v_mfma_f32_16x16x32_bf16 v[94:97], v[158:161], v[198:201], v[94:97]
	v_mfma_f32_16x16x32_bf16 v[86:89], v[150:153], v[206:209], v[86:89]
	v_mfma_f32_16x16x32_bf16 v[78:81], v[158:161], v[206:209], v[78:81]
	v_mfma_f32_16x16x32_bf16 v[126:129], v[154:157], v[186:189], v[126:129]
	v_mfma_f32_16x16x32_bf16 v[122:125], v[162:165], v[186:189], v[122:125]
	v_mfma_f32_16x16x32_bf16 v[118:121], v[154:157], v[194:197], v[118:121]
	v_mfma_f32_16x16x32_bf16 v[110:113], v[162:165], v[194:197], v[110:113]
	v_mfma_f32_16x16x32_bf16 v[102:105], v[154:157], v[202:205], v[102:105]
	v_mfma_f32_16x16x32_bf16 v[94:97], v[162:165], v[202:205], v[94:97]
	v_mfma_f32_16x16x32_bf16 v[86:89], v[154:157], v[210:213], v[86:89]
	v_mfma_f32_16x16x32_bf16 v[78:81], v[162:165], v[210:213], v[78:81]
	v_mfma_f32_16x16x32_bf16 v[114:117], v[166:169], v[182:185], v[114:117]
	v_mfma_f32_16x16x32_bf16 v[106:109], v[174:177], v[182:185], v[106:109]
	v_mfma_f32_16x16x32_bf16 v[98:101], v[166:169], v[190:193], v[98:101]
	v_mfma_f32_16x16x32_bf16 v[90:93], v[174:177], v[190:193], v[90:93]
	v_mfma_f32_16x16x32_bf16 v[82:85], v[166:169], v[198:201], v[82:85]
	v_mfma_f32_16x16x32_bf16 v[74:77], v[174:177], v[198:201], v[74:77]
	v_mfma_f32_16x16x32_bf16 v[70:73], v[166:169], v[206:209], v[70:73]
	v_mfma_f32_16x16x32_bf16 v[66:69], v[174:177], v[206:209], v[66:69]
	v_mfma_f32_16x16x32_bf16 v[114:117], v[170:173], v[186:189], v[114:117]
	v_mfma_f32_16x16x32_bf16 v[106:109], v[178:181], v[186:189], v[106:109]
	v_mfma_f32_16x16x32_bf16 v[98:101], v[170:173], v[194:197], v[98:101]
	v_mfma_f32_16x16x32_bf16 v[90:93], v[178:181], v[194:197], v[90:93]
	v_mfma_f32_16x16x32_bf16 v[82:85], v[170:173], v[202:205], v[82:85]
	v_mfma_f32_16x16x32_bf16 v[74:77], v[178:181], v[202:205], v[74:77]
	v_mfma_f32_16x16x32_bf16 v[70:73], v[170:173], v[210:213], v[70:73]
	v_mfma_f32_16x16x32_bf16 v[66:69], v[178:181], v[210:213], v[66:69]
	s_barrier
	s_setprio 0
	s_add_i32 s52, s69, s19
	v_lshl_add_u64 v[142:143], v[142:143], 0, s[8:9]
	s_mov_b32 m0, s52
	ds_read_b128 v[182:185], v148 offset:49152
	ds_read_b128 v[186:189], v148 offset:50176
	ds_read_b128 v[190:193], v148 offset:51200
	ds_read_b128 v[194:197], v148 offset:52224
	ds_read_b128 v[198:201], v148 offset:53248
	ds_read_b128 v[202:205], v148 offset:54272
	ds_read_b128 v[206:209], v148 offset:55296
	ds_read_b128 v[210:213], v148 offset:56320
	global_load_lds_dwordx4 v[142:143], off
	s_add_i32 m0, s52, 0x2000
	s_add_u32 s44, s44, 0x80080
	v_lshl_add_u64 v[142:143], v[214:215], 0, s[8:9]
	s_addc_u32 s45, s45, 0
	s_add_i32 s52, s70, s19
	global_load_lds_dwordx4 v[142:143], off
	v_lshl_add_u64 v[142:143], s[44:45], 0, v[134:135]
	s_mov_b32 m0, s52
	s_nop 0
	global_load_lds_dwordx4 v[142:143], off
	v_lshl_add_u64 v[142:143], s[44:45], 0, v[130:131]
	s_add_i32 m0, s52, 0x2000
	s_nop 0
	global_load_lds_dwordx4 v[142:143], off
	v_lshl_add_u64 v[142:143], v[216:217], 0, s[8:9]
	s_mov_b32 m0, s42
	s_nop 0
	global_load_lds_dwordx4 v[142:143], off
	v_lshl_add_u64 v[142:143], v[218:219], 0, s[8:9]
	s_mov_b32 m0, s43
	s_nop 0
	global_load_lds_dwordx4 v[142:143], off
	s_waitcnt vmcnt(8)
	s_waitcnt lgkmcnt(0)
	s_setprio 1
	s_barrier
	v_mfma_f32_16x16x32_bf16 v[62:65], v[150:153], v[182:185], v[62:65]
	v_mfma_f32_16x16x32_bf16 v[58:61], v[158:161], v[182:185], v[58:61]
	v_mfma_f32_16x16x32_bf16 v[54:57], v[150:153], v[190:193], v[54:57]
	v_mfma_f32_16x16x32_bf16 v[46:49], v[158:161], v[190:193], v[46:49]
	v_mfma_f32_16x16x32_bf16 v[38:41], v[150:153], v[198:201], v[38:41]
	v_mfma_f32_16x16x32_bf16 v[30:33], v[158:161], v[198:201], v[30:33]
	v_mfma_f32_16x16x32_bf16 v[22:25], v[150:153], v[206:209], v[22:25]
	v_mfma_f32_16x16x32_bf16 v[14:17], v[158:161], v[206:209], v[14:17]
	v_mfma_f32_16x16x32_bf16 v[62:65], v[154:157], v[186:189], v[62:65]
	v_mfma_f32_16x16x32_bf16 v[58:61], v[162:165], v[186:189], v[58:61]
	v_mfma_f32_16x16x32_bf16 v[54:57], v[154:157], v[194:197], v[54:57]
	v_mfma_f32_16x16x32_bf16 v[46:49], v[162:165], v[194:197], v[46:49]
	v_mfma_f32_16x16x32_bf16 v[38:41], v[154:157], v[202:205], v[38:41]
	v_mfma_f32_16x16x32_bf16 v[30:33], v[162:165], v[202:205], v[30:33]
	v_mfma_f32_16x16x32_bf16 v[22:25], v[154:157], v[210:213], v[22:25]
	v_mfma_f32_16x16x32_bf16 v[14:17], v[162:165], v[210:213], v[14:17]
	v_mfma_f32_16x16x32_bf16 v[50:53], v[166:169], v[182:185], v[50:53]
	v_mfma_f32_16x16x32_bf16 v[42:45], v[174:177], v[182:185], v[42:45]
	v_mfma_f32_16x16x32_bf16 v[34:37], v[166:169], v[190:193], v[34:37]
	v_mfma_f32_16x16x32_bf16 v[26:29], v[174:177], v[190:193], v[26:29]
	v_mfma_f32_16x16x32_bf16 v[18:21], v[166:169], v[198:201], v[18:21]
	v_mfma_f32_16x16x32_bf16 v[10:13], v[174:177], v[198:201], v[10:13]
	v_mfma_f32_16x16x32_bf16 v[6:9], v[166:169], v[206:209], v[6:9]
	v_mfma_f32_16x16x32_bf16 v[2:5], v[174:177], v[206:209], v[2:5]
	v_mfma_f32_16x16x32_bf16 v[50:53], v[170:173], v[186:189], v[50:53]
	v_mfma_f32_16x16x32_bf16 v[42:45], v[178:181], v[186:189], v[42:45]
	v_mfma_f32_16x16x32_bf16 v[34:37], v[170:173], v[194:197], v[34:37]
	v_mfma_f32_16x16x32_bf16 v[26:29], v[178:181], v[194:197], v[26:29]
	v_mfma_f32_16x16x32_bf16 v[18:21], v[170:173], v[202:205], v[18:21]
	v_mfma_f32_16x16x32_bf16 v[10:13], v[178:181], v[202:205], v[10:13]
	v_mfma_f32_16x16x32_bf16 v[6:9], v[170:173], v[210:213], v[6:9]
	v_mfma_f32_16x16x32_bf16 v[2:5], v[178:181], v[210:213], v[2:5]
	s_barrier
	s_setprio 0
	s_add_i32 s68, s68, 2
	s_add_u32 s54, s54, 0x100
	s_addc_u32 s55, s55, 0
	s_add_u32 s36, s36, 0x100
	s_addc_u32 s37, s37, 0
	s_cmp_gt_u32 s68, 29
	s_cbranch_scc0 .LBB0_139
	s_and_b64 vcc, exec, s[16:17]
	s_cbranch_vccz .LBB0_142
	s_barrier

.LBB0_266:
	ds_read_b128 v[82:85], v188
	ds_read_b128 v[86:89], v188 offset:1024
	ds_read_b128 v[94:97], v188 offset:2048
	ds_read_b128 v[98:101], v188 offset:3072
	ds_read_b128 v[146:149], v189
	ds_read_b128 v[150:153], v189 offset:1024
	ds_read_b128 v[154:157], v189 offset:2048
	ds_read_b128 v[158:161], v189 offset:3072
	s_add_u32 s6, s44, 0x100
	s_addc_u32 s7, s45, 0
	s_cmpk_eq_i32 s70, 0x54
	s_cselect_b32 s55, s31, s7
	s_cselect_b32 s54, s30, s6
	s_cselect_b32 s53, s37, s69
	s_cselect_b32 s52, s36, s68
	v_lshl_add_u64 v[216:217], s[44:45], 0, v[172:173]
	s_add_i32 m0, s14, 0xc000
	ds_read_b128 v[178:181], v190
	ds_read_b128 v[182:185], v190 offset:1024
	ds_read_b128 v[192:195], v190 offset:2048
	ds_read_b128 v[196:199], v190 offset:3072
	ds_read_b128 v[200:203], v190 offset:4096
	ds_read_b128 v[204:207], v190 offset:5120
	ds_read_b128 v[208:211], v190 offset:6144
	ds_read_b128 v[212:215], v190 offset:7168
	global_load_lds_dwordx4 v[216:217], off
	v_lshl_add_u64 v[216:217], s[44:45], 0, v[170:171]
	s_add_i32 m0, s14, 0xe000
	s_nop 0
	global_load_lds_dwordx4 v[216:217], off
	s_waitcnt vmcnt(8)
	s_waitcnt lgkmcnt(0)
	s_setprio 1
	s_barrier
	v_mfma_f32_16x16x32_bf16 v[142:145], v[82:85], v[178:181], v[142:145]
	v_mfma_f32_16x16x32_bf16 v[138:141], v[94:97], v[178:181], v[138:141]
	v_mfma_f32_16x16x32_bf16 v[126:129], v[82:85], v[192:195], v[126:129]
	v_mfma_f32_16x16x32_bf16 v[122:125], v[94:97], v[192:195], v[122:125]
	v_mfma_f32_16x16x32_bf16 v[110:113], v[82:85], v[200:203], v[110:113]
	v_mfma_f32_16x16x32_bf16 v[106:109], v[94:97], v[200:203], v[106:109]
	v_mfma_f32_16x16x32_bf16 v[78:81], v[82:85], v[208:211], v[78:81]
	v_mfma_f32_16x16x32_bf16 v[74:77], v[94:97], v[208:211], v[74:77]
	v_mfma_f32_16x16x32_bf16 v[142:145], v[86:89], v[182:185], v[142:145]
	v_mfma_f32_16x16x32_bf16 v[138:141], v[98:101], v[182:185], v[138:141]
	v_mfma_f32_16x16x32_bf16 v[126:129], v[86:89], v[196:199], v[126:129]
	v_mfma_f32_16x16x32_bf16 v[122:125], v[98:101], v[196:199], v[122:125]
	v_mfma_f32_16x16x32_bf16 v[110:113], v[86:89], v[204:207], v[110:113]
	v_mfma_f32_16x16x32_bf16 v[106:109], v[98:101], v[204:207], v[106:109]
	v_mfma_f32_16x16x32_bf16 v[78:81], v[86:89], v[212:215], v[78:81]
	v_mfma_f32_16x16x32_bf16 v[74:77], v[98:101], v[212:215], v[74:77]
	v_mfma_f32_16x16x32_bf16 v[134:137], v[146:149], v[178:181], v[134:137]
	v_mfma_f32_16x16x32_bf16 v[130:133], v[154:157], v[178:181], v[130:133]
	v_mfma_f32_16x16x32_bf16 v[118:121], v[146:149], v[192:195], v[118:121]
	v_mfma_f32_16x16x32_bf16 v[114:117], v[154:157], v[192:195], v[114:117]
	v_mfma_f32_16x16x32_bf16 v[102:105], v[146:149], v[200:203], v[102:105]
	v_mfma_f32_16x16x32_bf16 v[90:93], v[154:157], v[200:203], v[90:93]
	v_mfma_f32_16x16x32_bf16 v[70:73], v[146:149], v[208:211], v[70:73]
	v_mfma_f32_16x16x32_bf16 v[66:69], v[154:157], v[208:211], v[66:69]
	v_mfma_f32_16x16x32_bf16 v[134:137], v[150:153], v[182:185], v[134:137]
	v_mfma_f32_16x16x32_bf16 v[130:133], v[158:161], v[182:185], v[130:133]
	v_mfma_f32_16x16x32_bf16 v[118:121], v[150:153], v[196:199], v[118:121]
	v_mfma_f32_16x16x32_bf16 v[114:117], v[158:161], v[196:199], v[114:117]
	v_mfma_f32_16x16x32_bf16 v[102:105], v[150:153], v[204:207], v[102:105]
	v_mfma_f32_16x16x32_bf16 v[90:93], v[158:161], v[204:207], v[90:93]
	v_mfma_f32_16x16x32_bf16 v[70:73], v[150:153], v[212:215], v[70:73]
	v_mfma_f32_16x16x32_bf16 v[66:69], v[158:161], v[212:215], v[66:69]
	s_barrier
	s_setprio 0
	s_add_i32 s44, s46, s13
	v_lshl_add_u64 v[216:217], s[52:53], 0, v[164:165]
	s_mov_b32 m0, s44
	ds_read_b128 v[178:181], v190 offset:16384
	ds_read_b128 v[182:185], v190 offset:17408
	ds_read_b128 v[192:195], v190 offset:18432
	ds_read_b128 v[196:199], v190 offset:19456
	ds_read_b128 v[200:203], v190 offset:20480
	ds_read_b128 v[204:207], v190 offset:21504
	ds_read_b128 v[208:211], v190 offset:22528
	ds_read_b128 v[212:215], v190 offset:23552
	global_load_lds_dwordx4 v[216:217], off
	s_add_i32 m0, s44, 0x2000
	s_add_u32 s44, s52, 0x160000
	v_lshl_add_u64 v[218:219], s[52:53], 0, v[168:169]
	s_addc_u32 s45, s53, 0
	s_add_i32 s71, s47, s13
	global_load_lds_dwordx4 v[218:219], off
	v_lshl_add_u64 v[220:221], s[44:45], 0, v[164:165]
	s_mov_b32 m0, s71
	v_lshl_add_u64 v[222:223], s[54:55], 0, v[166:167]
	global_load_lds_dwordx4 v[220:221], off
	v_lshl_add_u64 v[220:221], s[44:45], 0, v[168:169]
	s_add_i32 m0, s71, 0x2000
	s_nop 0
	global_load_lds_dwordx4 v[220:221], off
	v_lshl_add_u64 v[220:221], s[54:55], 0, v[162:163]
	s_mov_b32 m0, s14
	s_nop 0
	global_load_lds_dwordx4 v[220:221], off
	s_mov_b32 m0, s15
	s_nop 0
	global_load_lds_dwordx4 v[222:223], off
	s_waitcnt vmcnt(8)
	s_waitcnt lgkmcnt(0)
	s_setprio 1
	s_barrier
	v_mfma_f32_16x16x32_bf16 v[62:65], v[82:85], v[178:181], v[62:65]
	v_mfma_f32_16x16x32_bf16 v[58:61], v[94:97], v[178:181], v[58:61]
	v_mfma_f32_16x16x32_bf16 v[46:49], v[82:85], v[192:195], v[46:49]
	v_mfma_f32_16x16x32_bf16 v[42:45], v[94:97], v[192:195], v[42:45]
	v_mfma_f32_16x16x32_bf16 v[30:33], v[82:85], v[200:203], v[30:33]
	v_mfma_f32_16x16x32_bf16 v[26:29], v[94:97], v[200:203], v[26:29]
	v_mfma_f32_16x16x32_bf16 v[14:17], v[82:85], v[208:211], v[14:17]
	v_mfma_f32_16x16x32_bf16 v[10:13], v[94:97], v[208:211], v[10:13]
	v_mfma_f32_16x16x32_bf16 v[62:65], v[86:89], v[182:185], v[62:65]
	v_mfma_f32_16x16x32_bf16 v[58:61], v[98:101], v[182:185], v[58:61]
	v_mfma_f32_16x16x32_bf16 v[46:49], v[86:89], v[196:199], v[46:49]
	v_mfma_f32_16x16x32_bf16 v[42:45], v[98:101], v[196:199], v[42:45]
	v_mfma_f32_16x16x32_bf16 v[30:33], v[86:89], v[204:207], v[30:33]
	v_mfma_f32_16x16x32_bf16 v[26:29], v[98:101], v[204:207], v[26:29]
	v_mfma_f32_16x16x32_bf16 v[14:17], v[86:89], v[212:215], v[14:17]
	v_mfma_f32_16x16x32_bf16 v[10:13], v[98:101], v[212:215], v[10:13]
	v_mfma_f32_16x16x32_bf16 v[54:57], v[146:149], v[178:181], v[54:57]
	v_mfma_f32_16x16x32_bf16 v[50:53], v[154:157], v[178:181], v[50:53]
	v_mfma_f32_16x16x32_bf16 v[38:41], v[146:149], v[192:195], v[38:41]
	v_mfma_f32_16x16x32_bf16 v[34:37], v[154:157], v[192:195], v[34:37]
	v_mfma_f32_16x16x32_bf16 v[22:25], v[146:149], v[200:203], v[22:25]
	v_mfma_f32_16x16x32_bf16 v[18:21], v[154:157], v[200:203], v[18:21]
	v_mfma_f32_16x16x32_bf16 v[6:9], v[146:149], v[208:211], v[6:9]
	v_mfma_f32_16x16x32_bf16 v[2:5], v[154:157], v[208:211], v[2:5]
	v_mfma_f32_16x16x32_bf16 v[54:57], v[150:153], v[182:185], v[54:57]
	v_mfma_f32_16x16x32_bf16 v[50:53], v[158:161], v[182:185], v[50:53]
	v_mfma_f32_16x16x32_bf16 v[38:41], v[150:153], v[196:199], v[38:41]
	v_mfma_f32_16x16x32_bf16 v[34:37], v[158:161], v[196:199], v[34:37]
	v_mfma_f32_16x16x32_bf16 v[22:25], v[150:153], v[204:207], v[22:25]
	v_mfma_f32_16x16x32_bf16 v[18:21], v[158:161], v[204:207], v[18:21]
	v_mfma_f32_16x16x32_bf16 v[6:9], v[150:153], v[212:215], v[6:9]
	v_mfma_f32_16x16x32_bf16 v[2:5], v[158:161], v[212:215], v[2:5]
	s_barrier
	s_setprio 0
	s_add_i32 s71, 0, 0x18000
	s_add_i32 s72, 0, 0x1c000
	v_add_u32_e32 v98, s71, v187
	v_add_u32_e32 v158, s72, v187
	ds_read_b128 v[82:85], v98
	ds_read_b128 v[86:89], v98 offset:1024
	ds_read_b128 v[94:97], v98 offset:2048
	ds_read_b128 v[98:101], v98 offset:3072
	ds_read_b128 v[146:149], v158
	ds_read_b128 v[150:153], v158 offset:1024
	ds_read_b128 v[154:157], v158 offset:2048
	ds_read_b128 v[158:161], v158 offset:3072
	s_add_u32 s44, s54, 0x160000
	s_addc_u32 s45, s55, 0
	s_mov_b32 m0, s18
	v_lshl_add_u64 v[224:225], s[44:45], 0, v[162:163]
	ds_read_b128 v[178:181], v190 offset:32768
	ds_read_b128 v[182:185], v190 offset:33792
	ds_read_b128 v[192:195], v190 offset:34816
	ds_read_b128 v[196:199], v190 offset:35840
	ds_read_b128 v[200:203], v190 offset:36864
	ds_read_b128 v[204:207], v190 offset:37888
	ds_read_b128 v[208:211], v190 offset:38912
	ds_read_b128 v[212:215], v190 offset:39936
	global_load_lds_dwordx4 v[224:225], off
	v_lshl_add_u64 v[224:225], s[44:45], 0, v[166:167]
	s_mov_b32 m0, s19
	s_nop 0
	global_load_lds_dwordx4 v[224:225], off
	s_waitcnt vmcnt(8)
	s_waitcnt lgkmcnt(0)
	s_setprio 1
	s_barrier
	v_mfma_f32_16x16x32_bf16 v[142:145], v[82:85], v[178:181], v[142:145]
	v_mfma_f32_16x16x32_bf16 v[138:141], v[94:97], v[178:181], v[138:141]
	v_mfma_f32_16x16x32_bf16 v[126:129], v[82:85], v[192:195], v[126:129]
	v_mfma_f32_16x16x32_bf16 v[122:125], v[94:97], v[192:195], v[122:125]
	v_mfma_f32_16x16x32_bf16 v[110:113], v[82:85], v[200:203], v[110:113]
	v_mfma_f32_16x16x32_bf16 v[106:109], v[94:97], v[200:203], v[106:109]
	v_mfma_f32_16x16x32_bf16 v[78:81], v[82:85], v[208:211], v[78:81]
	v_mfma_f32_16x16x32_bf16 v[74:77], v[94:97], v[208:211], v[74:77]
	v_mfma_f32_16x16x32_bf16 v[142:145], v[86:89], v[182:185], v[142:145]
	v_mfma_f32_16x16x32_bf16 v[138:141], v[98:101], v[182:185], v[138:141]
	v_mfma_f32_16x16x32_bf16 v[126:129], v[86:89], v[196:199], v[126:129]
	v_mfma_f32_16x16x32_bf16 v[122:125], v[98:101], v[196:199], v[122:125]
	v_mfma_f32_16x16x32_bf16 v[110:113], v[86:89], v[204:207], v[110:113]
	v_mfma_f32_16x16x32_bf16 v[106:109], v[98:101], v[204:207], v[106:109]
	v_mfma_f32_16x16x32_bf16 v[78:81], v[86:89], v[212:215], v[78:81]
	v_mfma_f32_16x16x32_bf16 v[74:77], v[98:101], v[212:215], v[74:77]
	v_mfma_f32_16x16x32_bf16 v[134:137], v[146:149], v[178:181], v[134:137]
	v_mfma_f32_16x16x32_bf16 v[130:133], v[154:157], v[178:181], v[130:133]
	v_mfma_f32_16x16x32_bf16 v[118:121], v[146:149], v[192:195], v[118:121]
	v_mfma_f32_16x16x32_bf16 v[114:117], v[154:157], v[192:195], v[114:117]
	v_mfma_f32_16x16x32_bf16 v[102:105], v[146:149], v[200:203], v[102:105]
	v_mfma_f32_16x16x32_bf16 v[90:93], v[154:157], v[200:203], v[90:93]
	v_mfma_f32_16x16x32_bf16 v[70:73], v[146:149], v[208:211], v[70:73]
	v_mfma_f32_16x16x32_bf16 v[66:69], v[154:157], v[208:211], v[66:69]
	v_mfma_f32_16x16x32_bf16 v[134:137], v[150:153], v[182:185], v[134:137]
	v_mfma_f32_16x16x32_bf16 v[130:133], v[158:161], v[182:185], v[130:133]
	v_mfma_f32_16x16x32_bf16 v[118:121], v[150:153], v[196:199], v[118:121]
	v_mfma_f32_16x16x32_bf16 v[114:117], v[158:161], v[196:199], v[114:117]
	v_mfma_f32_16x16x32_bf16 v[102:105], v[150:153], v[204:207], v[102:105]
	v_mfma_f32_16x16x32_bf16 v[90:93], v[158:161], v[204:207], v[90:93]
	v_mfma_f32_16x16x32_bf16 v[70:73], v[150:153], v[212:215], v[70:73]
	v_mfma_f32_16x16x32_bf16 v[66:69], v[158:161], v[212:215], v[66:69]
	s_barrier
	s_setprio 0
	s_add_i32 s44, s71, s13
	v_lshl_add_u64 v[216:217], v[216:217], 0, s[26:27]
	s_mov_b32 m0, s44
	ds_read_b128 v[178:181], v190 offset:49152
	ds_read_b128 v[182:185], v190 offset:50176
	ds_read_b128 v[192:195], v190 offset:51200
	ds_read_b128 v[196:199], v190 offset:52224
	ds_read_b128 v[200:203], v190 offset:53248
	ds_read_b128 v[204:207], v190 offset:54272
	ds_read_b128 v[208:211], v190 offset:55296
	ds_read_b128 v[212:215], v190 offset:56320
	global_load_lds_dwordx4 v[216:217], off
	s_add_i32 m0, s44, 0x2000
	s_add_u32 s44, s52, 0x160080
	v_lshl_add_u64 v[216:217], v[218:219], 0, s[26:27]
	s_addc_u32 s45, s53, 0
	s_add_i32 s52, s72, s13
	global_load_lds_dwordx4 v[216:217], off
	v_lshl_add_u64 v[216:217], s[44:45], 0, v[164:165]
	s_mov_b32 m0, s52
	s_nop 0
	global_load_lds_dwordx4 v[216:217], off
	v_lshl_add_u64 v[216:217], s[44:45], 0, v[168:169]
	s_add_i32 m0, s52, 0x2000
	s_nop 0
	global_load_lds_dwordx4 v[216:217], off
	v_lshl_add_u64 v[216:217], v[220:221], 0, s[26:27]
	s_mov_b32 m0, s40
	s_nop 0
	global_load_lds_dwordx4 v[216:217], off
	v_lshl_add_u64 v[216:217], v[222:223], 0, s[26:27]
	s_mov_b32 m0, s41
	s_nop 0
	global_load_lds_dwordx4 v[216:217], off
	s_waitcnt vmcnt(8)
	s_waitcnt lgkmcnt(0)
	s_setprio 1
	s_barrier
	v_mfma_f32_16x16x32_bf16 v[62:65], v[82:85], v[178:181], v[62:65]
	v_mfma_f32_16x16x32_bf16 v[58:61], v[94:97], v[178:181], v[58:61]
	v_mfma_f32_16x16x32_bf16 v[46:49], v[82:85], v[192:195], v[46:49]
	v_mfma_f32_16x16x32_bf16 v[42:45], v[94:97], v[192:195], v[42:45]
	v_mfma_f32_16x16x32_bf16 v[30:33], v[82:85], v[200:203], v[30:33]
	v_mfma_f32_16x16x32_bf16 v[26:29], v[94:97], v[200:203], v[26:29]
	v_mfma_f32_16x16x32_bf16 v[14:17], v[82:85], v[208:211], v[14:17]
	v_mfma_f32_16x16x32_bf16 v[10:13], v[94:97], v[208:211], v[10:13]
	v_mfma_f32_16x16x32_bf16 v[62:65], v[86:89], v[182:185], v[62:65]
	v_mfma_f32_16x16x32_bf16 v[58:61], v[98:101], v[182:185], v[58:61]
	v_mfma_f32_16x16x32_bf16 v[46:49], v[86:89], v[196:199], v[46:49]
	v_mfma_f32_16x16x32_bf16 v[42:45], v[98:101], v[196:199], v[42:45]
	v_mfma_f32_16x16x32_bf16 v[30:33], v[86:89], v[204:207], v[30:33]
	v_mfma_f32_16x16x32_bf16 v[26:29], v[98:101], v[204:207], v[26:29]
	v_mfma_f32_16x16x32_bf16 v[14:17], v[86:89], v[212:215], v[14:17]
	v_mfma_f32_16x16x32_bf16 v[10:13], v[98:101], v[212:215], v[10:13]
	v_mfma_f32_16x16x32_bf16 v[54:57], v[146:149], v[178:181], v[54:57]
	v_mfma_f32_16x16x32_bf16 v[50:53], v[154:157], v[178:181], v[50:53]
	v_mfma_f32_16x16x32_bf16 v[38:41], v[146:149], v[192:195], v[38:41]
	v_mfma_f32_16x16x32_bf16 v[34:37], v[154:157], v[192:195], v[34:37]
	v_mfma_f32_16x16x32_bf16 v[22:25], v[146:149], v[200:203], v[22:25]
	v_mfma_f32_16x16x32_bf16 v[18:21], v[154:157], v[200:203], v[18:21]
	v_mfma_f32_16x16x32_bf16 v[6:9], v[146:149], v[208:211], v[6:9]
	v_mfma_f32_16x16x32_bf16 v[2:5], v[154:157], v[208:211], v[2:5]
	v_mfma_f32_16x16x32_bf16 v[54:57], v[150:153], v[182:185], v[54:57]
	v_mfma_f32_16x16x32_bf16 v[50:53], v[158:161], v[182:185], v[50:53]
	v_mfma_f32_16x16x32_bf16 v[38:41], v[150:153], v[196:199], v[38:41]
	v_mfma_f32_16x16x32_bf16 v[34:37], v[158:161], v[196:199], v[34:37]
	v_mfma_f32_16x16x32_bf16 v[22:25], v[150:153], v[204:207], v[22:25]
	v_mfma_f32_16x16x32_bf16 v[18:21], v[158:161], v[204:207], v[18:21]
	v_mfma_f32_16x16x32_bf16 v[6:9], v[150:153], v[212:215], v[6:9]
	v_mfma_f32_16x16x32_bf16 v[2:5], v[158:161], v[212:215], v[2:5]
	s_barrier
	s_setprio 0
	s_add_i32 s70, s70, 2
	s_add_u32 s68, s68, 0x100
	s_addc_u32 s69, s69, 0
	s_cmpk_gt_u32 s70, 0x55
	s_mov_b64 s[44:45], s[6:7]
	s_cbranch_scc0 .LBB0_266
	s_and_b64 vcc, exec, s[28:29]
	s_cbranch_vccz .LBB0_269
	s_barrier

.LBB0_632:
	ds_read_b128 v[146:149], v162
	ds_read_b128 v[150:153], v162 offset:1024
	ds_read_b128 v[154:157], v162 offset:2048
	ds_read_b128 v[168:171], v162 offset:3072
	ds_read_b128 v[172:175], v163
	ds_read_b128 v[176:179], v163 offset:1024
	ds_read_b128 v[180:183], v163 offset:2048
	ds_read_b128 v[184:187], v163 offset:3072
	s_add_u32 s15, s52, 0xfff80080
	s_addc_u32 s16, s53, -1
	s_cmp_eq_u32 s14, 28
	s_cselect_b32 s57, s7, s16
	s_cselect_b32 s56, s9, s15
	s_cselect_b32 s55, s10, s13
	s_cselect_b32 s54, s11, s12
	v_lshl_add_u64 v[158:159], s[52:53], 0, v[140:141]
	s_add_i32 m0, s39, 0xc000
	ds_read_b128 v[188:191], v164
	ds_read_b128 v[192:195], v164 offset:1024
	ds_read_b128 v[196:199], v164 offset:2048
	ds_read_b128 v[200:203], v164 offset:3072
	ds_read_b128 v[204:207], v164 offset:4096
	ds_read_b128 v[208:211], v164 offset:5120
	ds_read_b128 v[212:215], v164 offset:6144
	ds_read_b128 v[216:219], v164 offset:7168
	global_load_lds_dwordx4 v[158:159], off
	v_lshl_add_u64 v[158:159], s[52:53], 0, v[138:139]
	s_add_i32 m0, s39, 0xe000
	s_nop 0
	global_load_lds_dwordx4 v[158:159], off
	s_waitcnt vmcnt(8)
	s_waitcnt lgkmcnt(0)
	s_setprio 1
	s_barrier
	v_mfma_f32_16x16x32_bf16 v[126:129], v[146:149], v[188:191], v[126:129]
	v_mfma_f32_16x16x32_bf16 v[122:125], v[154:157], v[188:191], v[122:125]
	v_mfma_f32_16x16x32_bf16 v[110:113], v[146:149], v[196:199], v[110:113]
	v_mfma_f32_16x16x32_bf16 v[106:109], v[154:157], v[196:199], v[106:109]
	v_mfma_f32_16x16x32_bf16 v[94:97], v[146:149], v[204:207], v[94:97]
	v_mfma_f32_16x16x32_bf16 v[90:93], v[154:157], v[204:207], v[90:93]
	v_mfma_f32_16x16x32_bf16 v[78:81], v[146:149], v[212:215], v[78:81]
	v_mfma_f32_16x16x32_bf16 v[74:77], v[154:157], v[212:215], v[74:77]
	v_mfma_f32_16x16x32_bf16 v[126:129], v[150:153], v[192:195], v[126:129]
	v_mfma_f32_16x16x32_bf16 v[122:125], v[168:171], v[192:195], v[122:125]
	v_mfma_f32_16x16x32_bf16 v[110:113], v[150:153], v[200:203], v[110:113]
	v_mfma_f32_16x16x32_bf16 v[106:109], v[168:171], v[200:203], v[106:109]
	v_mfma_f32_16x16x32_bf16 v[94:97], v[150:153], v[208:211], v[94:97]
	v_mfma_f32_16x16x32_bf16 v[90:93], v[168:171], v[208:211], v[90:93]
	v_mfma_f32_16x16x32_bf16 v[78:81], v[150:153], v[216:219], v[78:81]
	v_mfma_f32_16x16x32_bf16 v[74:77], v[168:171], v[216:219], v[74:77]
	v_mfma_f32_16x16x32_bf16 v[118:121], v[172:175], v[188:191], v[118:121]
	v_mfma_f32_16x16x32_bf16 v[114:117], v[180:183], v[188:191], v[114:117]
	v_mfma_f32_16x16x32_bf16 v[102:105], v[172:175], v[196:199], v[102:105]
	v_mfma_f32_16x16x32_bf16 v[98:101], v[180:183], v[196:199], v[98:101]
	v_mfma_f32_16x16x32_bf16 v[86:89], v[172:175], v[204:207], v[86:89]
	v_mfma_f32_16x16x32_bf16 v[82:85], v[180:183], v[204:207], v[82:85]
	v_mfma_f32_16x16x32_bf16 v[70:73], v[172:175], v[212:215], v[70:73]
	v_mfma_f32_16x16x32_bf16 v[66:69], v[180:183], v[212:215], v[66:69]
	v_mfma_f32_16x16x32_bf16 v[118:121], v[176:179], v[192:195], v[118:121]
	v_mfma_f32_16x16x32_bf16 v[114:117], v[184:187], v[192:195], v[114:117]
	v_mfma_f32_16x16x32_bf16 v[102:105], v[176:179], v[200:203], v[102:105]
	v_mfma_f32_16x16x32_bf16 v[98:101], v[184:187], v[200:203], v[98:101]
	v_mfma_f32_16x16x32_bf16 v[86:89], v[176:179], v[208:211], v[86:89]
	v_mfma_f32_16x16x32_bf16 v[82:85], v[184:187], v[208:211], v[82:85]
	v_mfma_f32_16x16x32_bf16 v[70:73], v[176:179], v[216:219], v[70:73]
	v_mfma_f32_16x16x32_bf16 v[66:69], v[184:187], v[216:219], v[66:69]
	s_barrier
	s_setprio 0
	s_add_i32 s15, s75, s38
	v_lshl_add_u64 v[158:159], s[54:55], 0, v[132:133]
	s_mov_b32 m0, s15
	ds_read_b128 v[188:191], v164 offset:16384
	ds_read_b128 v[192:195], v164 offset:17408
	ds_read_b128 v[196:199], v164 offset:18432
	ds_read_b128 v[200:203], v164 offset:19456
	ds_read_b128 v[204:207], v164 offset:20480
	ds_read_b128 v[208:211], v164 offset:21504
	ds_read_b128 v[212:215], v164 offset:22528
	ds_read_b128 v[216:219], v164 offset:23552
	global_load_lds_dwordx4 v[158:159], off
	s_add_i32 m0, s15, 0x2000
	s_add_u32 s58, s54, 0x80000
	v_lshl_add_u64 v[220:221], s[54:55], 0, v[136:137]
	s_addc_u32 s59, s55, 0
	s_add_i32 s15, s76, s38
	global_load_lds_dwordx4 v[220:221], off
	v_lshl_add_u64 v[222:223], s[58:59], 0, v[132:133]
	s_mov_b32 m0, s15
	v_lshl_add_u64 v[224:225], s[56:57], 0, v[134:135]
	global_load_lds_dwordx4 v[222:223], off
	v_lshl_add_u64 v[222:223], s[58:59], 0, v[136:137]
	s_add_i32 m0, s15, 0x2000
	s_nop 0
	global_load_lds_dwordx4 v[222:223], off
	v_lshl_add_u64 v[222:223], s[56:57], 0, v[130:131]
	s_mov_b32 m0, s39
	s_nop 0
	global_load_lds_dwordx4 v[222:223], off
	s_mov_b32 m0, s46
	s_nop 0
	global_load_lds_dwordx4 v[224:225], off
	s_waitcnt vmcnt(8)
	s_waitcnt lgkmcnt(0)
	s_setprio 1
	s_barrier
	v_mfma_f32_16x16x32_bf16 v[62:65], v[146:149], v[188:191], v[62:65]
	v_mfma_f32_16x16x32_bf16 v[58:61], v[154:157], v[188:191], v[58:61]
	v_mfma_f32_16x16x32_bf16 v[46:49], v[146:149], v[196:199], v[46:49]
	v_mfma_f32_16x16x32_bf16 v[42:45], v[154:157], v[196:199], v[42:45]
	v_mfma_f32_16x16x32_bf16 v[30:33], v[146:149], v[204:207], v[30:33]
	v_mfma_f32_16x16x32_bf16 v[26:29], v[154:157], v[204:207], v[26:29]
	v_mfma_f32_16x16x32_bf16 v[14:17], v[146:149], v[212:215], v[14:17]
	v_mfma_f32_16x16x32_bf16 v[10:13], v[154:157], v[212:215], v[10:13]
	v_mfma_f32_16x16x32_bf16 v[62:65], v[150:153], v[192:195], v[62:65]
	v_mfma_f32_16x16x32_bf16 v[58:61], v[168:171], v[192:195], v[58:61]
	v_mfma_f32_16x16x32_bf16 v[46:49], v[150:153], v[200:203], v[46:49]
	v_mfma_f32_16x16x32_bf16 v[42:45], v[168:171], v[200:203], v[42:45]
	v_mfma_f32_16x16x32_bf16 v[30:33], v[150:153], v[208:211], v[30:33]
	v_mfma_f32_16x16x32_bf16 v[26:29], v[168:171], v[208:211], v[26:29]
	v_mfma_f32_16x16x32_bf16 v[14:17], v[150:153], v[216:219], v[14:17]
	v_mfma_f32_16x16x32_bf16 v[10:13], v[168:171], v[216:219], v[10:13]
	v_mfma_f32_16x16x32_bf16 v[54:57], v[172:175], v[188:191], v[54:57]
	v_mfma_f32_16x16x32_bf16 v[50:53], v[180:183], v[188:191], v[50:53]
	v_mfma_f32_16x16x32_bf16 v[38:41], v[172:175], v[196:199], v[38:41]
	v_mfma_f32_16x16x32_bf16 v[34:37], v[180:183], v[196:199], v[34:37]
	v_mfma_f32_16x16x32_bf16 v[22:25], v[172:175], v[204:207], v[22:25]
	v_mfma_f32_16x16x32_bf16 v[18:21], v[180:183], v[204:207], v[18:21]
	v_mfma_f32_16x16x32_bf16 v[6:9], v[172:175], v[212:215], v[6:9]
	v_mfma_f32_16x16x32_bf16 v[2:5], v[180:183], v[212:215], v[2:5]
	v_mfma_f32_16x16x32_bf16 v[54:57], v[176:179], v[192:195], v[54:57]
	v_mfma_f32_16x16x32_bf16 v[50:53], v[184:187], v[192:195], v[50:53]
	v_mfma_f32_16x16x32_bf16 v[38:41], v[176:179], v[200:203], v[38:41]
	v_mfma_f32_16x16x32_bf16 v[34:37], v[184:187], v[200:203], v[34:37]
	v_mfma_f32_16x16x32_bf16 v[22:25], v[176:179], v[208:211], v[22:25]
	v_mfma_f32_16x16x32_bf16 v[18:21], v[184:187], v[208:211], v[18:21]
	v_mfma_f32_16x16x32_bf16 v[6:9], v[176:179], v[216:219], v[6:9]
	v_mfma_f32_16x16x32_bf16 v[2:5], v[184:187], v[216:219], v[2:5]
	s_barrier
	s_setprio 0
	s_add_i32 s15, 0, 0x18000
	v_add_u32_e32 v167, s15, v161
	s_add_i32 s16, 0, 0x1c000
	ds_read_b128 v[146:149], v167
	ds_read_b128 v[150:153], v167 offset:1024
	ds_read_b128 v[154:157], v167 offset:2048
	ds_read_b128 v[168:171], v167 offset:3072
	v_add_u32_e32 v167, s16, v161
	ds_read_b128 v[172:175], v167
	ds_read_b128 v[176:179], v167 offset:1024
	ds_read_b128 v[180:183], v167 offset:2048
	ds_read_b128 v[184:187], v167 offset:3072
	s_add_u32 s56, s56, 0x80000
	s_addc_u32 s57, s57, 0
	s_mov_b32 m0, s47
	v_lshl_add_u64 v[226:227], s[56:57], 0, v[130:131]
	ds_read_b128 v[188:191], v164 offset:32768
	ds_read_b128 v[192:195], v164 offset:33792
	ds_read_b128 v[196:199], v164 offset:34816
	ds_read_b128 v[200:203], v164 offset:35840
	ds_read_b128 v[204:207], v164 offset:36864
	ds_read_b128 v[208:211], v164 offset:37888
	ds_read_b128 v[212:215], v164 offset:38912
	ds_read_b128 v[216:219], v164 offset:39936
	global_load_lds_dwordx4 v[226:227], off
	v_lshl_add_u64 v[226:227], s[56:57], 0, v[134:135]
	s_mov_b32 m0, s48
	s_nop 0
	global_load_lds_dwordx4 v[226:227], off
	s_waitcnt vmcnt(8)
	s_waitcnt lgkmcnt(0)
	s_setprio 1
	s_barrier
	v_mfma_f32_16x16x32_bf16 v[126:129], v[146:149], v[188:191], v[126:129]
	v_mfma_f32_16x16x32_bf16 v[122:125], v[154:157], v[188:191], v[122:125]
	v_mfma_f32_16x16x32_bf16 v[110:113], v[146:149], v[196:199], v[110:113]
	v_mfma_f32_16x16x32_bf16 v[106:109], v[154:157], v[196:199], v[106:109]
	v_mfma_f32_16x16x32_bf16 v[94:97], v[146:149], v[204:207], v[94:97]
	v_mfma_f32_16x16x32_bf16 v[90:93], v[154:157], v[204:207], v[90:93]
	v_mfma_f32_16x16x32_bf16 v[78:81], v[146:149], v[212:215], v[78:81]
	v_mfma_f32_16x16x32_bf16 v[74:77], v[154:157], v[212:215], v[74:77]
	v_mfma_f32_16x16x32_bf16 v[126:129], v[150:153], v[192:195], v[126:129]
	v_mfma_f32_16x16x32_bf16 v[122:125], v[168:171], v[192:195], v[122:125]
	v_mfma_f32_16x16x32_bf16 v[110:113], v[150:153], v[200:203], v[110:113]
	v_mfma_f32_16x16x32_bf16 v[106:109], v[168:171], v[200:203], v[106:109]
	v_mfma_f32_16x16x32_bf16 v[94:97], v[150:153], v[208:211], v[94:97]
	v_mfma_f32_16x16x32_bf16 v[90:93], v[168:171], v[208:211], v[90:93]
	v_mfma_f32_16x16x32_bf16 v[78:81], v[150:153], v[216:219], v[78:81]
	v_mfma_f32_16x16x32_bf16 v[74:77], v[168:171], v[216:219], v[74:77]
	v_mfma_f32_16x16x32_bf16 v[118:121], v[172:175], v[188:191], v[118:121]
	v_mfma_f32_16x16x32_bf16 v[114:117], v[180:183], v[188:191], v[114:117]
	v_mfma_f32_16x16x32_bf16 v[102:105], v[172:175], v[196:199], v[102:105]
	v_mfma_f32_16x16x32_bf16 v[98:101], v[180:183], v[196:199], v[98:101]
	v_mfma_f32_16x16x32_bf16 v[86:89], v[172:175], v[204:207], v[86:89]
	v_mfma_f32_16x16x32_bf16 v[82:85], v[180:183], v[204:207], v[82:85]
	v_mfma_f32_16x16x32_bf16 v[70:73], v[172:175], v[212:215], v[70:73]
	v_mfma_f32_16x16x32_bf16 v[66:69], v[180:183], v[212:215], v[66:69]
	v_mfma_f32_16x16x32_bf16 v[118:121], v[176:179], v[192:195], v[118:121]
	v_mfma_f32_16x16x32_bf16 v[114:117], v[184:187], v[192:195], v[114:117]
	v_mfma_f32_16x16x32_bf16 v[102:105], v[176:179], v[200:203], v[102:105]
	v_mfma_f32_16x16x32_bf16 v[98:101], v[184:187], v[200:203], v[98:101]
	v_mfma_f32_16x16x32_bf16 v[86:89], v[176:179], v[208:211], v[86:89]
	v_mfma_f32_16x16x32_bf16 v[82:85], v[184:187], v[208:211], v[82:85]
	v_mfma_f32_16x16x32_bf16 v[70:73], v[176:179], v[216:219], v[70:73]
	v_mfma_f32_16x16x32_bf16 v[66:69], v[184:187], v[216:219], v[66:69]
	s_barrier
	s_setprio 0
	s_add_i32 s15, s15, s38
	v_lshl_add_u64 v[158:159], v[158:159], 0, s[24:25]
	s_mov_b32 m0, s15
	ds_read_b128 v[188:191], v164 offset:49152
	ds_read_b128 v[192:195], v164 offset:50176
	ds_read_b128 v[196:199], v164 offset:51200
	ds_read_b128 v[200:203], v164 offset:52224
	ds_read_b128 v[204:207], v164 offset:53248
	ds_read_b128 v[208:211], v164 offset:54272
	ds_read_b128 v[212:215], v164 offset:55296
	ds_read_b128 v[216:219], v164 offset:56320
	global_load_lds_dwordx4 v[158:159], off
	s_add_i32 m0, s15, 0x2000
	s_add_u32 s54, s54, 0x80080
	v_lshl_add_u64 v[158:159], v[220:221], 0, s[24:25]
	s_addc_u32 s55, s55, 0
	s_add_i32 s15, s16, s38
	global_load_lds_dwordx4 v[158:159], off
	v_lshl_add_u64 v[158:159], s[54:55], 0, v[132:133]
	s_mov_b32 m0, s15
	s_nop 0
	global_load_lds_dwordx4 v[158:159], off
	v_lshl_add_u64 v[158:159], s[54:55], 0, v[136:137]
	s_add_i32 m0, s15, 0x2000
	s_nop 0
	global_load_lds_dwordx4 v[158:159], off
	v_lshl_add_u64 v[158:159], v[222:223], 0, s[24:25]
	s_mov_b32 m0, s71
	s_nop 0
	global_load_lds_dwordx4 v[158:159], off
	v_lshl_add_u64 v[158:159], v[224:225], 0, s[24:25]
	s_mov_b32 m0, s72
	s_nop 0
	global_load_lds_dwordx4 v[158:159], off
	s_waitcnt vmcnt(8)
	s_waitcnt lgkmcnt(0)
	s_setprio 1
	s_barrier
	v_mfma_f32_16x16x32_bf16 v[62:65], v[146:149], v[188:191], v[62:65]
	v_mfma_f32_16x16x32_bf16 v[58:61], v[154:157], v[188:191], v[58:61]
	v_mfma_f32_16x16x32_bf16 v[46:49], v[146:149], v[196:199], v[46:49]
	v_mfma_f32_16x16x32_bf16 v[42:45], v[154:157], v[196:199], v[42:45]
	v_mfma_f32_16x16x32_bf16 v[30:33], v[146:149], v[204:207], v[30:33]
	v_mfma_f32_16x16x32_bf16 v[26:29], v[154:157], v[204:207], v[26:29]
	v_mfma_f32_16x16x32_bf16 v[14:17], v[146:149], v[212:215], v[14:17]
	v_mfma_f32_16x16x32_bf16 v[10:13], v[154:157], v[212:215], v[10:13]
	v_mfma_f32_16x16x32_bf16 v[62:65], v[150:153], v[192:195], v[62:65]
	v_mfma_f32_16x16x32_bf16 v[58:61], v[168:171], v[192:195], v[58:61]
	v_mfma_f32_16x16x32_bf16 v[46:49], v[150:153], v[200:203], v[46:49]
	v_mfma_f32_16x16x32_bf16 v[42:45], v[168:171], v[200:203], v[42:45]
	v_mfma_f32_16x16x32_bf16 v[30:33], v[150:153], v[208:211], v[30:33]
	v_mfma_f32_16x16x32_bf16 v[26:29], v[168:171], v[208:211], v[26:29]
	v_mfma_f32_16x16x32_bf16 v[14:17], v[150:153], v[216:219], v[14:17]
	v_mfma_f32_16x16x32_bf16 v[10:13], v[168:171], v[216:219], v[10:13]
	v_mfma_f32_16x16x32_bf16 v[54:57], v[172:175], v[188:191], v[54:57]
	v_mfma_f32_16x16x32_bf16 v[50:53], v[180:183], v[188:191], v[50:53]
	v_mfma_f32_16x16x32_bf16 v[38:41], v[172:175], v[196:199], v[38:41]
	v_mfma_f32_16x16x32_bf16 v[34:37], v[180:183], v[196:199], v[34:37]
	v_mfma_f32_16x16x32_bf16 v[22:25], v[172:175], v[204:207], v[22:25]
	v_mfma_f32_16x16x32_bf16 v[18:21], v[180:183], v[204:207], v[18:21]
	v_mfma_f32_16x16x32_bf16 v[6:9], v[172:175], v[212:215], v[6:9]
	v_mfma_f32_16x16x32_bf16 v[2:5], v[180:183], v[212:215], v[2:5]
	v_mfma_f32_16x16x32_bf16 v[54:57], v[176:179], v[192:195], v[54:57]
	v_mfma_f32_16x16x32_bf16 v[50:53], v[184:187], v[192:195], v[50:53]
	v_mfma_f32_16x16x32_bf16 v[38:41], v[176:179], v[200:203], v[38:41]
	v_mfma_f32_16x16x32_bf16 v[34:37], v[184:187], v[200:203], v[34:37]
	v_mfma_f32_16x16x32_bf16 v[22:25], v[176:179], v[208:211], v[22:25]
	v_mfma_f32_16x16x32_bf16 v[18:21], v[184:187], v[208:211], v[18:21]
	v_mfma_f32_16x16x32_bf16 v[6:9], v[176:179], v[216:219], v[6:9]
	v_mfma_f32_16x16x32_bf16 v[2:5], v[184:187], v[216:219], v[2:5]
	s_barrier
	s_setprio 0
	s_add_i32 s14, s14, 2
	s_add_u32 s12, s12, 0x100
	s_addc_u32 s13, s13, 0
	s_add_u32 s52, s52, 0x100
	s_addc_u32 s53, s53, 0
	s_cmp_gt_u32 s14, 29
	s_cbranch_scc0 .LBB0_632
	s_and_b64 vcc, exec, s[26:27]
	s_cbranch_vccz .LBB0_635
	s_barrier

.LBB0_1130:
	ds_read_b128 v[86:89], v166
	ds_read_b128 v[90:93], v166 offset:1024
	ds_read_b128 v[98:101], v166 offset:2048
	ds_read_b128 v[106:109], v166 offset:3072
	ds_read_b128 v[170:173], v167
	ds_read_b128 v[174:177], v167 offset:1024
	ds_read_b128 v[178:181], v167 offset:2048
	ds_read_b128 v[182:185], v167 offset:3072
	s_add_u32 s62, s60, 0xfff80080
	s_addc_u32 s63, s61, -1
	s_cmp_eq_u32 s70, 28
	s_cselect_b32 s65, s53, s63
	s_cselect_b32 s64, s66, s62
	s_cselect_b32 s63, s45, s69
	s_cselect_b32 s62, s67, s68
	v_lshl_add_u64 v[162:163], s[60:61], 0, v[156:157]
	s_add_i32 m0, s14, 0xc000
	ds_read_b128 v[186:189], v168
	ds_read_b128 v[190:193], v168 offset:1024
	ds_read_b128 v[194:197], v168 offset:2048
	ds_read_b128 v[198:201], v168 offset:3072
	ds_read_b128 v[202:205], v168 offset:4096
	ds_read_b128 v[206:209], v168 offset:5120
	ds_read_b128 v[210:213], v168 offset:6144
	ds_read_b128 v[214:217], v168 offset:7168
	global_load_lds_dwordx4 v[162:163], off
	v_lshl_add_u64 v[162:163], s[60:61], 0, v[154:155]
	s_add_i32 m0, s14, 0xe000
	s_nop 0
	global_load_lds_dwordx4 v[162:163], off
	s_waitcnt vmcnt(8)
	s_waitcnt lgkmcnt(0)
	s_setprio 1
	s_barrier
	v_mfma_f32_16x16x32_bf16 v[142:145], v[86:89], v[186:189], v[142:145]
	v_mfma_f32_16x16x32_bf16 v[134:137], v[98:101], v[186:189], v[134:137]
	v_mfma_f32_16x16x32_bf16 v[126:129], v[86:89], v[194:197], v[126:129]
	v_mfma_f32_16x16x32_bf16 v[118:121], v[98:101], v[194:197], v[118:121]
	v_mfma_f32_16x16x32_bf16 v[110:113], v[86:89], v[202:205], v[110:113]
	v_mfma_f32_16x16x32_bf16 v[94:97], v[98:101], v[202:205], v[94:97]
	v_mfma_f32_16x16x32_bf16 v[78:81], v[86:89], v[210:213], v[78:81]
	v_mfma_f32_16x16x32_bf16 v[70:73], v[98:101], v[210:213], v[70:73]
	v_mfma_f32_16x16x32_bf16 v[142:145], v[90:93], v[190:193], v[142:145]
	v_mfma_f32_16x16x32_bf16 v[134:137], v[106:109], v[190:193], v[134:137]
	v_mfma_f32_16x16x32_bf16 v[126:129], v[90:93], v[198:201], v[126:129]
	v_mfma_f32_16x16x32_bf16 v[118:121], v[106:109], v[198:201], v[118:121]
	v_mfma_f32_16x16x32_bf16 v[110:113], v[90:93], v[206:209], v[110:113]
	v_mfma_f32_16x16x32_bf16 v[94:97], v[106:109], v[206:209], v[94:97]
	v_mfma_f32_16x16x32_bf16 v[78:81], v[90:93], v[214:217], v[78:81]
	v_mfma_f32_16x16x32_bf16 v[70:73], v[106:109], v[214:217], v[70:73]
	v_mfma_f32_16x16x32_bf16 v[138:141], v[170:173], v[186:189], v[138:141]
	v_mfma_f32_16x16x32_bf16 v[130:133], v[178:181], v[186:189], v[130:133]
	v_mfma_f32_16x16x32_bf16 v[122:125], v[170:173], v[194:197], v[122:125]
	v_mfma_f32_16x16x32_bf16 v[114:117], v[178:181], v[194:197], v[114:117]
	v_mfma_f32_16x16x32_bf16 v[102:105], v[170:173], v[202:205], v[102:105]
	v_mfma_f32_16x16x32_bf16 v[82:85], v[178:181], v[202:205], v[82:85]
	v_mfma_f32_16x16x32_bf16 v[74:77], v[170:173], v[210:213], v[74:77]
	v_mfma_f32_16x16x32_bf16 v[66:69], v[178:181], v[210:213], v[66:69]
	v_mfma_f32_16x16x32_bf16 v[138:141], v[174:177], v[190:193], v[138:141]
	v_mfma_f32_16x16x32_bf16 v[130:133], v[182:185], v[190:193], v[130:133]
	v_mfma_f32_16x16x32_bf16 v[122:125], v[174:177], v[198:201], v[122:125]
	v_mfma_f32_16x16x32_bf16 v[114:117], v[182:185], v[198:201], v[114:117]
	v_mfma_f32_16x16x32_bf16 v[102:105], v[174:177], v[206:209], v[102:105]
	v_mfma_f32_16x16x32_bf16 v[82:85], v[182:185], v[206:209], v[82:85]
	v_mfma_f32_16x16x32_bf16 v[74:77], v[174:177], v[214:217], v[74:77]
	v_mfma_f32_16x16x32_bf16 v[66:69], v[182:185], v[214:217], v[66:69]
	s_barrier
	s_setprio 0
	s_add_i32 s71, s49, s11
	v_lshl_add_u64 v[162:163], s[62:63], 0, v[150:151]
	s_mov_b32 m0, s71
	ds_read_b128 v[186:189], v168 offset:16384
	ds_read_b128 v[190:193], v168 offset:17408
	ds_read_b128 v[194:197], v168 offset:18432
	ds_read_b128 v[198:201], v168 offset:19456
	ds_read_b128 v[202:205], v168 offset:20480
	ds_read_b128 v[206:209], v168 offset:21504
	ds_read_b128 v[210:213], v168 offset:22528
	ds_read_b128 v[214:217], v168 offset:23552
	global_load_lds_dwordx4 v[162:163], off
	s_add_i32 m0, s71, 0x2000
	s_add_u32 s72, s62, 0x80000
	v_lshl_add_u64 v[218:219], s[62:63], 0, v[146:147]
	s_addc_u32 s73, s63, 0
	s_add_i32 s71, s50, s11
	global_load_lds_dwordx4 v[218:219], off
	v_lshl_add_u64 v[220:221], s[72:73], 0, v[150:151]
	s_mov_b32 m0, s71
	v_lshl_add_u64 v[222:223], s[64:65], 0, v[148:149]
	global_load_lds_dwordx4 v[220:221], off
	v_lshl_add_u64 v[220:221], s[72:73], 0, v[146:147]
	s_add_i32 m0, s71, 0x2000
	s_nop 0
	global_load_lds_dwordx4 v[220:221], off
	v_lshl_add_u64 v[220:221], s[64:65], 0, v[152:153]
	s_mov_b32 m0, s14
	s_nop 0
	global_load_lds_dwordx4 v[220:221], off
	s_mov_b32 m0, s15
	s_nop 0
	global_load_lds_dwordx4 v[222:223], off
	s_waitcnt vmcnt(8)
	s_waitcnt lgkmcnt(0)
	s_setprio 1
	s_barrier
	v_mfma_f32_16x16x32_bf16 v[62:65], v[86:89], v[186:189], v[62:65]
	v_mfma_f32_16x16x32_bf16 v[54:57], v[98:101], v[186:189], v[54:57]
	v_mfma_f32_16x16x32_bf16 v[46:49], v[86:89], v[194:197], v[46:49]
	v_mfma_f32_16x16x32_bf16 v[38:41], v[98:101], v[194:197], v[38:41]
	v_mfma_f32_16x16x32_bf16 v[30:33], v[86:89], v[202:205], v[30:33]
	v_mfma_f32_16x16x32_bf16 v[22:25], v[98:101], v[202:205], v[22:25]
	v_mfma_f32_16x16x32_bf16 v[14:17], v[86:89], v[210:213], v[14:17]
	v_mfma_f32_16x16x32_bf16 v[6:9], v[98:101], v[210:213], v[6:9]
	v_mfma_f32_16x16x32_bf16 v[62:65], v[90:93], v[190:193], v[62:65]
	v_mfma_f32_16x16x32_bf16 v[54:57], v[106:109], v[190:193], v[54:57]
	v_mfma_f32_16x16x32_bf16 v[46:49], v[90:93], v[198:201], v[46:49]
	v_mfma_f32_16x16x32_bf16 v[38:41], v[106:109], v[198:201], v[38:41]
	v_mfma_f32_16x16x32_bf16 v[30:33], v[90:93], v[206:209], v[30:33]
	v_mfma_f32_16x16x32_bf16 v[22:25], v[106:109], v[206:209], v[22:25]
	v_mfma_f32_16x16x32_bf16 v[14:17], v[90:93], v[214:217], v[14:17]
	v_mfma_f32_16x16x32_bf16 v[6:9], v[106:109], v[214:217], v[6:9]
	v_mfma_f32_16x16x32_bf16 v[58:61], v[170:173], v[186:189], v[58:61]
	v_mfma_f32_16x16x32_bf16 v[50:53], v[178:181], v[186:189], v[50:53]
	v_mfma_f32_16x16x32_bf16 v[42:45], v[170:173], v[194:197], v[42:45]
	v_mfma_f32_16x16x32_bf16 v[34:37], v[178:181], v[194:197], v[34:37]
	v_mfma_f32_16x16x32_bf16 v[26:29], v[170:173], v[202:205], v[26:29]
	v_mfma_f32_16x16x32_bf16 v[18:21], v[178:181], v[202:205], v[18:21]
	v_mfma_f32_16x16x32_bf16 v[10:13], v[170:173], v[210:213], v[10:13]
	v_mfma_f32_16x16x32_bf16 v[2:5], v[178:181], v[210:213], v[2:5]
	v_mfma_f32_16x16x32_bf16 v[58:61], v[174:177], v[190:193], v[58:61]
	v_mfma_f32_16x16x32_bf16 v[50:53], v[182:185], v[190:193], v[50:53]
	v_mfma_f32_16x16x32_bf16 v[42:45], v[174:177], v[198:201], v[42:45]
	v_mfma_f32_16x16x32_bf16 v[34:37], v[182:185], v[198:201], v[34:37]
	v_mfma_f32_16x16x32_bf16 v[26:29], v[174:177], v[206:209], v[26:29]
	v_mfma_f32_16x16x32_bf16 v[18:21], v[182:185], v[206:209], v[18:21]
	v_mfma_f32_16x16x32_bf16 v[10:13], v[174:177], v[214:217], v[10:13]
	v_mfma_f32_16x16x32_bf16 v[2:5], v[182:185], v[214:217], v[2:5]
	s_barrier
	s_setprio 0
	s_add_i32 s71, 0, 0x18000
	s_add_i32 s72, 0, 0x1c000
	v_add_u32_e32 v106, s71, v165
	v_add_u32_e32 v182, s72, v165
	ds_read_b128 v[86:89], v106
	ds_read_b128 v[90:93], v106 offset:1024
	ds_read_b128 v[98:101], v106 offset:2048
	ds_read_b128 v[106:109], v106 offset:3072
	ds_read_b128 v[170:173], v182
	ds_read_b128 v[174:177], v182 offset:1024
	ds_read_b128 v[178:181], v182 offset:2048
	ds_read_b128 v[182:185], v182 offset:3072
	s_add_u32 s64, s64, 0x80000
	s_addc_u32 s65, s65, 0
	s_mov_b32 m0, s33
	v_lshl_add_u64 v[224:225], s[64:65], 0, v[152:153]
	ds_read_b128 v[186:189], v168 offset:32768
	ds_read_b128 v[190:193], v168 offset:33792
	ds_read_b128 v[194:197], v168 offset:34816
	ds_read_b128 v[198:201], v168 offset:35840
	ds_read_b128 v[202:205], v168 offset:36864
	ds_read_b128 v[206:209], v168 offset:37888
	ds_read_b128 v[210:213], v168 offset:38912
	ds_read_b128 v[214:217], v168 offset:39936
	global_load_lds_dwordx4 v[224:225], off
	v_lshl_add_u64 v[224:225], s[64:65], 0, v[148:149]
	s_mov_b32 m0, s34
	s_nop 0
	global_load_lds_dwordx4 v[224:225], off
	s_waitcnt vmcnt(8)
	s_waitcnt lgkmcnt(0)
	s_setprio 1
	s_barrier
	v_mfma_f32_16x16x32_bf16 v[142:145], v[86:89], v[186:189], v[142:145]
	v_mfma_f32_16x16x32_bf16 v[134:137], v[98:101], v[186:189], v[134:137]
	v_mfma_f32_16x16x32_bf16 v[126:129], v[86:89], v[194:197], v[126:129]
	v_mfma_f32_16x16x32_bf16 v[118:121], v[98:101], v[194:197], v[118:121]
	v_mfma_f32_16x16x32_bf16 v[110:113], v[86:89], v[202:205], v[110:113]
	v_mfma_f32_16x16x32_bf16 v[94:97], v[98:101], v[202:205], v[94:97]
	v_mfma_f32_16x16x32_bf16 v[78:81], v[86:89], v[210:213], v[78:81]
	v_mfma_f32_16x16x32_bf16 v[70:73], v[98:101], v[210:213], v[70:73]
	v_mfma_f32_16x16x32_bf16 v[142:145], v[90:93], v[190:193], v[142:145]
	v_mfma_f32_16x16x32_bf16 v[134:137], v[106:109], v[190:193], v[134:137]
	v_mfma_f32_16x16x32_bf16 v[126:129], v[90:93], v[198:201], v[126:129]
	v_mfma_f32_16x16x32_bf16 v[118:121], v[106:109], v[198:201], v[118:121]
	v_mfma_f32_16x16x32_bf16 v[110:113], v[90:93], v[206:209], v[110:113]
	v_mfma_f32_16x16x32_bf16 v[94:97], v[106:109], v[206:209], v[94:97]
	v_mfma_f32_16x16x32_bf16 v[78:81], v[90:93], v[214:217], v[78:81]
	v_mfma_f32_16x16x32_bf16 v[70:73], v[106:109], v[214:217], v[70:73]
	v_mfma_f32_16x16x32_bf16 v[138:141], v[170:173], v[186:189], v[138:141]
	v_mfma_f32_16x16x32_bf16 v[130:133], v[178:181], v[186:189], v[130:133]
	v_mfma_f32_16x16x32_bf16 v[122:125], v[170:173], v[194:197], v[122:125]
	v_mfma_f32_16x16x32_bf16 v[114:117], v[178:181], v[194:197], v[114:117]
	v_mfma_f32_16x16x32_bf16 v[102:105], v[170:173], v[202:205], v[102:105]
	v_mfma_f32_16x16x32_bf16 v[82:85], v[178:181], v[202:205], v[82:85]
	v_mfma_f32_16x16x32_bf16 v[74:77], v[170:173], v[210:213], v[74:77]
	v_mfma_f32_16x16x32_bf16 v[66:69], v[178:181], v[210:213], v[66:69]
	v_mfma_f32_16x16x32_bf16 v[138:141], v[174:177], v[190:193], v[138:141]
	v_mfma_f32_16x16x32_bf16 v[130:133], v[182:185], v[190:193], v[130:133]
	v_mfma_f32_16x16x32_bf16 v[122:125], v[174:177], v[198:201], v[122:125]
	v_mfma_f32_16x16x32_bf16 v[114:117], v[182:185], v[198:201], v[114:117]
	v_mfma_f32_16x16x32_bf16 v[102:105], v[174:177], v[206:209], v[102:105]
	v_mfma_f32_16x16x32_bf16 v[82:85], v[182:185], v[206:209], v[82:85]
	v_mfma_f32_16x16x32_bf16 v[74:77], v[174:177], v[214:217], v[74:77]
	v_mfma_f32_16x16x32_bf16 v[66:69], v[182:185], v[214:217], v[66:69]
	s_barrier
	s_setprio 0
	s_add_i32 s64, s71, s11
	v_lshl_add_u64 v[162:163], v[162:163], 0, s[22:23]
	s_mov_b32 m0, s64
	ds_read_b128 v[186:189], v168 offset:49152
	ds_read_b128 v[190:193], v168 offset:50176
	ds_read_b128 v[194:197], v168 offset:51200
	ds_read_b128 v[198:201], v168 offset:52224
	ds_read_b128 v[202:205], v168 offset:53248
	ds_read_b128 v[206:209], v168 offset:54272
	ds_read_b128 v[210:213], v168 offset:55296
	ds_read_b128 v[214:217], v168 offset:56320
	global_load_lds_dwordx4 v[162:163], off
	s_add_i32 m0, s64, 0x2000
	s_add_u32 s62, s62, 0x80080
	v_lshl_add_u64 v[162:163], v[218:219], 0, s[22:23]
	s_addc_u32 s63, s63, 0
	s_add_i32 s64, s72, s11
	global_load_lds_dwordx4 v[162:163], off
	v_lshl_add_u64 v[162:163], s[62:63], 0, v[150:151]
	s_mov_b32 m0, s64
	s_nop 0
	global_load_lds_dwordx4 v[162:163], off
	v_lshl_add_u64 v[162:163], s[62:63], 0, v[146:147]
	s_add_i32 m0, s64, 0x2000
	s_nop 0
	global_load_lds_dwordx4 v[162:163], off
	v_lshl_add_u64 v[162:163], v[220:221], 0, s[22:23]
	s_mov_b32 m0, s39
	s_nop 0
	global_load_lds_dwordx4 v[162:163], off
	v_lshl_add_u64 v[162:163], v[222:223], 0, s[22:23]
	s_mov_b32 m0, s46
	s_nop 0
	global_load_lds_dwordx4 v[162:163], off
	s_waitcnt vmcnt(8)
	s_waitcnt lgkmcnt(0)
	s_setprio 1
	s_barrier
	v_mfma_f32_16x16x32_bf16 v[62:65], v[86:89], v[186:189], v[62:65]
	v_mfma_f32_16x16x32_bf16 v[54:57], v[98:101], v[186:189], v[54:57]
	v_mfma_f32_16x16x32_bf16 v[46:49], v[86:89], v[194:197], v[46:49]
	v_mfma_f32_16x16x32_bf16 v[38:41], v[98:101], v[194:197], v[38:41]
	v_mfma_f32_16x16x32_bf16 v[30:33], v[86:89], v[202:205], v[30:33]
	v_mfma_f32_16x16x32_bf16 v[22:25], v[98:101], v[202:205], v[22:25]
	v_mfma_f32_16x16x32_bf16 v[14:17], v[86:89], v[210:213], v[14:17]
	v_mfma_f32_16x16x32_bf16 v[6:9], v[98:101], v[210:213], v[6:9]
	v_mfma_f32_16x16x32_bf16 v[62:65], v[90:93], v[190:193], v[62:65]
	v_mfma_f32_16x16x32_bf16 v[54:57], v[106:109], v[190:193], v[54:57]
	v_mfma_f32_16x16x32_bf16 v[46:49], v[90:93], v[198:201], v[46:49]
	v_mfma_f32_16x16x32_bf16 v[38:41], v[106:109], v[198:201], v[38:41]
	v_mfma_f32_16x16x32_bf16 v[30:33], v[90:93], v[206:209], v[30:33]
	v_mfma_f32_16x16x32_bf16 v[22:25], v[106:109], v[206:209], v[22:25]
	v_mfma_f32_16x16x32_bf16 v[14:17], v[90:93], v[214:217], v[14:17]
	v_mfma_f32_16x16x32_bf16 v[6:9], v[106:109], v[214:217], v[6:9]
	v_mfma_f32_16x16x32_bf16 v[58:61], v[170:173], v[186:189], v[58:61]
	v_mfma_f32_16x16x32_bf16 v[50:53], v[178:181], v[186:189], v[50:53]
	v_mfma_f32_16x16x32_bf16 v[42:45], v[170:173], v[194:197], v[42:45]
	v_mfma_f32_16x16x32_bf16 v[34:37], v[178:181], v[194:197], v[34:37]
	v_mfma_f32_16x16x32_bf16 v[26:29], v[170:173], v[202:205], v[26:29]
	v_mfma_f32_16x16x32_bf16 v[18:21], v[178:181], v[202:205], v[18:21]
	v_mfma_f32_16x16x32_bf16 v[10:13], v[170:173], v[210:213], v[10:13]
	v_mfma_f32_16x16x32_bf16 v[2:5], v[178:181], v[210:213], v[2:5]
	v_mfma_f32_16x16x32_bf16 v[58:61], v[174:177], v[190:193], v[58:61]
	v_mfma_f32_16x16x32_bf16 v[50:53], v[182:185], v[190:193], v[50:53]
	v_mfma_f32_16x16x32_bf16 v[42:45], v[174:177], v[198:201], v[42:45]
	v_mfma_f32_16x16x32_bf16 v[34:37], v[182:185], v[198:201], v[34:37]
	v_mfma_f32_16x16x32_bf16 v[26:29], v[174:177], v[206:209], v[26:29]
	v_mfma_f32_16x16x32_bf16 v[18:21], v[182:185], v[206:209], v[18:21]
	v_mfma_f32_16x16x32_bf16 v[10:13], v[174:177], v[214:217], v[10:13]
	v_mfma_f32_16x16x32_bf16 v[2:5], v[182:185], v[214:217], v[2:5]
	s_barrier
	s_setprio 0
	s_add_i32 s70, s70, 2
	s_add_u32 s68, s68, 0x100
	s_addc_u32 s69, s69, 0
	s_add_u32 s60, s60, 0x100
	s_addc_u32 s61, s61, 0
	s_cmp_gt_u32 s70, 29
	s_cbranch_scc0 .LBB0_1130
	s_and_b64 vcc, exec, s[24:25]
	s_cbranch_vccz .LBB0_1133
	s_barrier

.LBB0_1201:
	s_add_u32 s62, s58, s60
	s_addc_u32 s63, s59, s61
	s_add_u32 s62, s62, 0x100
	s_addc_u32 s63, s63, 0
	s_add_u32 s71, s68, s60
	s_addc_u32 s72, s69, s61
	s_cmpk_eq_i32 s60, 0xf00
	s_cselect_b32 s65, s50, s63
	s_cselect_b32 s64, s51, s62
	s_cselect_b32 s63, s66, s72
	s_cselect_b32 s62, s67, s71
	s_add_i32 s71, 0, 0x10000
	v_add_u32_e32 v3, s71, v171
	ds_read_b128 v[134:137], v3
	ds_read_b128 v[138:141], v3 offset:1024
	ds_read_b128 v[142:145], v3 offset:2048
	ds_read_b128 v[146:149], v3 offset:3072
	v_add_u32_e32 v3, s49, v171
	ds_read_b128 v[174:177], v3
	ds_read_b128 v[178:181], v3 offset:1024
	ds_read_b128 v[182:185], v3 offset:2048
	ds_read_b128 v[186:189], v3 offset:3072
	v_lshl_add_u64 v[4:5], v[168:169], 0, s[60:61]
	s_add_i32 m0, s14, 0xc000
	ds_read_b128 v[190:193], v172
	ds_read_b128 v[194:197], v172 offset:1024
	ds_read_b128 v[198:201], v172 offset:2048
	ds_read_b128 v[202:205], v172 offset:3072
	ds_read_b128 v[206:209], v172 offset:4096
	ds_read_b128 v[210:213], v172 offset:5120
	ds_read_b128 v[214:217], v172 offset:6144
	ds_read_b128 v[218:221], v172 offset:7168
	global_load_lds_dwordx4 v[4:5], off
	v_lshl_add_u64 v[4:5], v[166:167], 0, s[60:61]
	s_add_i32 m0, s14, 0xe000
	s_nop 0
	global_load_lds_dwordx4 v[4:5], off
	s_waitcnt vmcnt(8)
	s_waitcnt lgkmcnt(0)
	s_setprio 1
	s_barrier
	v_mfma_f32_16x16x32_bf16 v[130:133], v[134:137], v[190:193], v[130:133]
	v_mfma_f32_16x16x32_bf16 v[126:129], v[142:145], v[190:193], v[126:129]
	v_mfma_f32_16x16x32_bf16 v[122:125], v[134:137], v[198:201], v[122:125]
	v_mfma_f32_16x16x32_bf16 v[114:117], v[142:145], v[198:201], v[114:117]
	v_mfma_f32_16x16x32_bf16 v[98:101], v[134:137], v[206:209], v[98:101]
	v_mfma_f32_16x16x32_bf16 v[94:97], v[142:145], v[206:209], v[94:97]
	v_mfma_f32_16x16x32_bf16 v[82:85], v[134:137], v[214:217], v[82:85]
	v_mfma_f32_16x16x32_bf16 v[78:81], v[142:145], v[214:217], v[78:81]
	v_mfma_f32_16x16x32_bf16 v[130:133], v[138:141], v[194:197], v[130:133]
	v_mfma_f32_16x16x32_bf16 v[126:129], v[146:149], v[194:197], v[126:129]
	v_mfma_f32_16x16x32_bf16 v[122:125], v[138:141], v[202:205], v[122:125]
	v_mfma_f32_16x16x32_bf16 v[114:117], v[146:149], v[202:205], v[114:117]
	v_mfma_f32_16x16x32_bf16 v[98:101], v[138:141], v[210:213], v[98:101]
	v_mfma_f32_16x16x32_bf16 v[94:97], v[146:149], v[210:213], v[94:97]
	v_mfma_f32_16x16x32_bf16 v[82:85], v[138:141], v[218:221], v[82:85]
	v_mfma_f32_16x16x32_bf16 v[78:81], v[146:149], v[218:221], v[78:81]
	v_mfma_f32_16x16x32_bf16 v[118:121], v[174:177], v[190:193], v[118:121]
	v_mfma_f32_16x16x32_bf16 v[110:113], v[182:185], v[190:193], v[110:113]
	v_mfma_f32_16x16x32_bf16 v[106:109], v[174:177], v[198:201], v[106:109]
	v_mfma_f32_16x16x32_bf16 v[102:105], v[182:185], v[198:201], v[102:105]
	v_mfma_f32_16x16x32_bf16 v[90:93], v[174:177], v[206:209], v[90:93]
	v_mfma_f32_16x16x32_bf16 v[86:89], v[182:185], v[206:209], v[86:89]
	v_mfma_f32_16x16x32_bf16 v[74:77], v[174:177], v[214:217], v[74:77]
	v_mfma_f32_16x16x32_bf16 v[70:73], v[182:185], v[214:217], v[70:73]
	v_mfma_f32_16x16x32_bf16 v[118:121], v[178:181], v[194:197], v[118:121]
	v_mfma_f32_16x16x32_bf16 v[110:113], v[186:189], v[194:197], v[110:113]
	v_mfma_f32_16x16x32_bf16 v[106:109], v[178:181], v[202:205], v[106:109]
	v_mfma_f32_16x16x32_bf16 v[102:105], v[186:189], v[202:205], v[102:105]
	v_mfma_f32_16x16x32_bf16 v[90:93], v[178:181], v[210:213], v[90:93]
	v_mfma_f32_16x16x32_bf16 v[86:89], v[186:189], v[210:213], v[86:89]
	v_mfma_f32_16x16x32_bf16 v[74:77], v[178:181], v[218:221], v[74:77]
	v_mfma_f32_16x16x32_bf16 v[70:73], v[186:189], v[218:221], v[70:73]
	s_barrier
	s_setprio 0
	s_add_i32 s71, s71, s11
	v_lshl_add_u64 v[222:223], s[62:63], 0, v[154:155]
	s_mov_b32 m0, s71
	ds_read_b128 v[190:193], v172 offset:16384
	ds_read_b128 v[194:197], v172 offset:17408
	ds_read_b128 v[198:201], v172 offset:18432
	ds_read_b128 v[202:205], v172 offset:19456
	ds_read_b128 v[206:209], v172 offset:20480
	ds_read_b128 v[210:213], v172 offset:21504
	ds_read_b128 v[214:217], v172 offset:22528
	ds_read_b128 v[218:221], v172 offset:23552
	global_load_lds_dwordx4 v[222:223], off
	s_add_i32 m0, s71, 0x2000
	s_add_u32 s72, s62, 0x80000
	v_lshl_add_u64 v[224:225], s[62:63], 0, v[150:151]
	s_addc_u32 s73, s63, 0
	s_add_i32 s71, s49, s11
	global_load_lds_dwordx4 v[224:225], off
	v_lshl_add_u64 v[4:5], s[72:73], 0, v[154:155]
	s_mov_b32 m0, s71
	v_lshl_add_u64 v[226:227], s[64:65], 0, v[156:157]
	global_load_lds_dwordx4 v[4:5], off
	v_lshl_add_u64 v[4:5], s[72:73], 0, v[150:151]
	s_add_i32 m0, s71, 0x2000
	v_lshl_add_u64 v[228:229], s[64:65], 0, v[152:153]
	global_load_lds_dwordx4 v[4:5], off
	s_mov_b32 m0, s14
	s_nop 0
	global_load_lds_dwordx4 v[226:227], off
	s_mov_b32 m0, s15
	s_nop 0
	global_load_lds_dwordx4 v[228:229], off
	s_waitcnt vmcnt(8)
	s_waitcnt lgkmcnt(0)
	s_setprio 1
	s_barrier
	v_mfma_f32_16x16x32_bf16 v[66:69], v[134:137], v[190:193], v[66:69]
	v_mfma_f32_16x16x32_bf16 v[62:65], v[142:145], v[190:193], v[62:65]
	v_mfma_f32_16x16x32_bf16 v[50:53], v[134:137], v[198:201], v[50:53]
	v_mfma_f32_16x16x32_bf16 v[46:49], v[142:145], v[198:201], v[46:49]
	v_mfma_f32_16x16x32_bf16 v[34:37], v[134:137], v[206:209], v[34:37]
	v_mfma_f32_16x16x32_bf16 v[30:33], v[142:145], v[206:209], v[30:33]
	v_mfma_f32_16x16x32_bf16 v[18:21], v[134:137], v[214:217], v[18:21]
	v_mfma_f32_16x16x32_bf16 v[14:17], v[142:145], v[214:217], v[14:17]
	v_mfma_f32_16x16x32_bf16 v[66:69], v[138:141], v[194:197], v[66:69]
	v_mfma_f32_16x16x32_bf16 v[62:65], v[146:149], v[194:197], v[62:65]
	v_mfma_f32_16x16x32_bf16 v[50:53], v[138:141], v[202:205], v[50:53]
	v_mfma_f32_16x16x32_bf16 v[46:49], v[146:149], v[202:205], v[46:49]
	v_mfma_f32_16x16x32_bf16 v[34:37], v[138:141], v[210:213], v[34:37]
	v_mfma_f32_16x16x32_bf16 v[30:33], v[146:149], v[210:213], v[30:33]
	v_mfma_f32_16x16x32_bf16 v[18:21], v[138:141], v[218:221], v[18:21]
	v_mfma_f32_16x16x32_bf16 v[14:17], v[146:149], v[218:221], v[14:17]
	v_mfma_f32_16x16x32_bf16 v[58:61], v[174:177], v[190:193], v[58:61]
	v_mfma_f32_16x16x32_bf16 v[54:57], v[182:185], v[190:193], v[54:57]
	v_mfma_f32_16x16x32_bf16 v[42:45], v[174:177], v[198:201], v[42:45]
	v_mfma_f32_16x16x32_bf16 v[38:41], v[182:185], v[198:201], v[38:41]
	v_mfma_f32_16x16x32_bf16 v[26:29], v[174:177], v[206:209], v[26:29]
	v_mfma_f32_16x16x32_bf16 v[22:25], v[182:185], v[206:209], v[22:25]
	v_mfma_f32_16x16x32_bf16 v[10:13], v[174:177], v[214:217], v[10:13]
	v_mfma_f32_16x16x32_bf16 v[4:7], v[182:185], v[214:217], v[6:9]
	v_mfma_f32_16x16x32_bf16 v[58:61], v[178:181], v[194:197], v[58:61]
	v_mfma_f32_16x16x32_bf16 v[54:57], v[186:189], v[194:197], v[54:57]
	v_mfma_f32_16x16x32_bf16 v[42:45], v[178:181], v[202:205], v[42:45]
	v_mfma_f32_16x16x32_bf16 v[38:41], v[186:189], v[202:205], v[38:41]
	v_mfma_f32_16x16x32_bf16 v[26:29], v[178:181], v[210:213], v[26:29]
	v_mfma_f32_16x16x32_bf16 v[22:25], v[186:189], v[210:213], v[22:25]
	v_mfma_f32_16x16x32_bf16 v[10:13], v[178:181], v[218:221], v[10:13]
	v_mfma_f32_16x16x32_bf16 v[4:7], v[186:189], v[218:221], v[4:7]
	s_barrier
	s_setprio 0
	s_add_i32 s71, 0, 0x18000
	v_add_u32_e32 v3, s71, v171
	s_add_i32 s72, 0, 0x1c000
	ds_read_b128 v[134:137], v3
	ds_read_b128 v[138:141], v3 offset:1024
	ds_read_b128 v[142:145], v3 offset:2048
	ds_read_b128 v[146:149], v3 offset:3072
	v_add_u32_e32 v3, s72, v171
	ds_read_b128 v[174:177], v3
	ds_read_b128 v[178:181], v3 offset:1024
	ds_read_b128 v[182:185], v3 offset:2048
	ds_read_b128 v[186:189], v3 offset:3072
	s_add_u32 s64, s64, 0x80000
	s_addc_u32 s65, s65, 0
	s_mov_b32 m0, s33
	v_lshl_add_u64 v[8:9], s[64:65], 0, v[156:157]
	ds_read_b128 v[190:193], v172 offset:32768
	ds_read_b128 v[194:197], v172 offset:33792
	ds_read_b128 v[198:201], v172 offset:34816
	ds_read_b128 v[202:205], v172 offset:35840
	ds_read_b128 v[206:209], v172 offset:36864
	ds_read_b128 v[210:213], v172 offset:37888
	ds_read_b128 v[214:217], v172 offset:38912
	ds_read_b128 v[218:221], v172 offset:39936
	global_load_lds_dwordx4 v[8:9], off
	v_lshl_add_u64 v[8:9], s[64:65], 0, v[152:153]
	s_mov_b32 m0, s34
	s_nop 0
	global_load_lds_dwordx4 v[8:9], off
	s_waitcnt vmcnt(8)
	s_waitcnt lgkmcnt(0)
	s_setprio 1
	s_barrier
	v_mfma_f32_16x16x32_bf16 v[130:133], v[134:137], v[190:193], v[130:133]
	v_mfma_f32_16x16x32_bf16 v[126:129], v[142:145], v[190:193], v[126:129]
	v_mfma_f32_16x16x32_bf16 v[122:125], v[134:137], v[198:201], v[122:125]
	v_mfma_f32_16x16x32_bf16 v[114:117], v[142:145], v[198:201], v[114:117]
	v_mfma_f32_16x16x32_bf16 v[98:101], v[134:137], v[206:209], v[98:101]
	v_mfma_f32_16x16x32_bf16 v[94:97], v[142:145], v[206:209], v[94:97]
	v_mfma_f32_16x16x32_bf16 v[82:85], v[134:137], v[214:217], v[82:85]
	v_mfma_f32_16x16x32_bf16 v[78:81], v[142:145], v[214:217], v[78:81]
	v_mfma_f32_16x16x32_bf16 v[130:133], v[138:141], v[194:197], v[130:133]
	v_mfma_f32_16x16x32_bf16 v[126:129], v[146:149], v[194:197], v[126:129]
	v_mfma_f32_16x16x32_bf16 v[122:125], v[138:141], v[202:205], v[122:125]
	v_mfma_f32_16x16x32_bf16 v[114:117], v[146:149], v[202:205], v[114:117]
	v_mfma_f32_16x16x32_bf16 v[98:101], v[138:141], v[210:213], v[98:101]
	v_mfma_f32_16x16x32_bf16 v[94:97], v[146:149], v[210:213], v[94:97]
	v_mfma_f32_16x16x32_bf16 v[82:85], v[138:141], v[218:221], v[82:85]
	v_mfma_f32_16x16x32_bf16 v[78:81], v[146:149], v[218:221], v[78:81]
	v_mfma_f32_16x16x32_bf16 v[118:121], v[174:177], v[190:193], v[118:121]
	v_mfma_f32_16x16x32_bf16 v[110:113], v[182:185], v[190:193], v[110:113]
	v_mfma_f32_16x16x32_bf16 v[106:109], v[174:177], v[198:201], v[106:109]
	v_mfma_f32_16x16x32_bf16 v[102:105], v[182:185], v[198:201], v[102:105]
	v_mfma_f32_16x16x32_bf16 v[90:93], v[174:177], v[206:209], v[90:93]
	v_mfma_f32_16x16x32_bf16 v[86:89], v[182:185], v[206:209], v[86:89]
	v_mfma_f32_16x16x32_bf16 v[74:77], v[174:177], v[214:217], v[74:77]
	v_mfma_f32_16x16x32_bf16 v[70:73], v[182:185], v[214:217], v[70:73]
	v_mfma_f32_16x16x32_bf16 v[118:121], v[178:181], v[194:197], v[118:121]
	v_mfma_f32_16x16x32_bf16 v[110:113], v[186:189], v[194:197], v[110:113]
	v_mfma_f32_16x16x32_bf16 v[106:109], v[178:181], v[202:205], v[106:109]
	v_mfma_f32_16x16x32_bf16 v[102:105], v[186:189], v[202:205], v[102:105]
	v_mfma_f32_16x16x32_bf16 v[90:93], v[178:181], v[210:213], v[90:93]
	v_mfma_f32_16x16x32_bf16 v[86:89], v[186:189], v[210:213], v[86:89]
	v_mfma_f32_16x16x32_bf16 v[74:77], v[178:181], v[218:221], v[74:77]
	v_mfma_f32_16x16x32_bf16 v[70:73], v[186:189], v[218:221], v[70:73]
	s_barrier
	s_setprio 0
	s_add_i32 s64, s71, s11
	v_lshl_add_u64 v[8:9], v[222:223], 0, s[22:23]
	s_mov_b32 m0, s64
	ds_read_b128 v[190:193], v172 offset:49152
	ds_read_b128 v[194:197], v172 offset:50176
	ds_read_b128 v[198:201], v172 offset:51200
	ds_read_b128 v[202:205], v172 offset:52224
	ds_read_b128 v[206:209], v172 offset:53248
	ds_read_b128 v[210:213], v172 offset:54272
	ds_read_b128 v[214:217], v172 offset:55296
	ds_read_b128 v[218:221], v172 offset:56320
	global_load_lds_dwordx4 v[8:9], off
	s_add_i32 m0, s64, 0x2000
	s_add_u32 s62, s62, 0x80080
	v_lshl_add_u64 v[8:9], v[224:225], 0, s[22:23]
	s_addc_u32 s63, s63, 0
	s_add_i32 s64, s72, s11
	global_load_lds_dwordx4 v[8:9], off
	v_lshl_add_u64 v[8:9], s[62:63], 0, v[154:155]
	s_mov_b32 m0, s64
	s_nop 0
	global_load_lds_dwordx4 v[8:9], off
	v_lshl_add_u64 v[8:9], s[62:63], 0, v[150:151]
	s_add_i32 m0, s64, 0x2000
	s_nop 0
	global_load_lds_dwordx4 v[8:9], off
	v_lshl_add_u64 v[8:9], v[226:227], 0, s[22:23]
	s_mov_b32 m0, s39
	s_nop 0
	global_load_lds_dwordx4 v[8:9], off
	v_lshl_add_u64 v[8:9], v[228:229], 0, s[22:23]
	s_mov_b32 m0, s46
	s_nop 0
	global_load_lds_dwordx4 v[8:9], off
	s_waitcnt vmcnt(8)
	s_waitcnt lgkmcnt(0)
	s_setprio 1
	s_barrier
	v_mfma_f32_16x16x32_bf16 v[66:69], v[134:137], v[190:193], v[66:69]
	v_mfma_f32_16x16x32_bf16 v[62:65], v[142:145], v[190:193], v[62:65]
	v_mfma_f32_16x16x32_bf16 v[50:53], v[134:137], v[198:201], v[50:53]
	v_mfma_f32_16x16x32_bf16 v[46:49], v[142:145], v[198:201], v[46:49]
	v_mfma_f32_16x16x32_bf16 v[34:37], v[134:137], v[206:209], v[34:37]
	v_mfma_f32_16x16x32_bf16 v[30:33], v[142:145], v[206:209], v[30:33]
	v_mfma_f32_16x16x32_bf16 v[18:21], v[134:137], v[214:217], v[18:21]
	v_mfma_f32_16x16x32_bf16 v[14:17], v[142:145], v[214:217], v[14:17]
	v_mfma_f32_16x16x32_bf16 v[66:69], v[138:141], v[194:197], v[66:69]
	v_mfma_f32_16x16x32_bf16 v[62:65], v[146:149], v[194:197], v[62:65]
	v_mfma_f32_16x16x32_bf16 v[50:53], v[138:141], v[202:205], v[50:53]
	v_mfma_f32_16x16x32_bf16 v[46:49], v[146:149], v[202:205], v[46:49]
	v_mfma_f32_16x16x32_bf16 v[34:37], v[138:141], v[210:213], v[34:37]
	v_mfma_f32_16x16x32_bf16 v[30:33], v[146:149], v[210:213], v[30:33]
	v_mfma_f32_16x16x32_bf16 v[18:21], v[138:141], v[218:221], v[18:21]
	v_mfma_f32_16x16x32_bf16 v[14:17], v[146:149], v[218:221], v[14:17]
	v_mfma_f32_16x16x32_bf16 v[58:61], v[174:177], v[190:193], v[58:61]
	v_mfma_f32_16x16x32_bf16 v[54:57], v[182:185], v[190:193], v[54:57]
	v_mfma_f32_16x16x32_bf16 v[42:45], v[174:177], v[198:201], v[42:45]
	v_mfma_f32_16x16x32_bf16 v[38:41], v[182:185], v[198:201], v[38:41]
	v_mfma_f32_16x16x32_bf16 v[26:29], v[174:177], v[206:209], v[26:29]
	v_mfma_f32_16x16x32_bf16 v[22:25], v[182:185], v[206:209], v[22:25]
	v_mfma_f32_16x16x32_bf16 v[8:11], v[174:177], v[214:217], v[10:13]
	v_mfma_f32_16x16x32_bf16 v[4:7], v[182:185], v[214:217], v[4:7]
	v_mfma_f32_16x16x32_bf16 v[58:61], v[178:181], v[194:197], v[58:61]
	v_mfma_f32_16x16x32_bf16 v[54:57], v[186:189], v[194:197], v[54:57]
	v_mfma_f32_16x16x32_bf16 v[42:45], v[178:181], v[202:205], v[42:45]
	v_mfma_f32_16x16x32_bf16 v[38:41], v[186:189], v[202:205], v[38:41]
	v_mfma_f32_16x16x32_bf16 v[26:29], v[178:181], v[210:213], v[26:29]
	v_mfma_f32_16x16x32_bf16 v[22:25], v[186:189], v[210:213], v[22:25]
	v_mfma_f32_16x16x32_bf16 v[10:13], v[178:181], v[218:221], v[8:11]
	v_mfma_f32_16x16x32_bf16 v[6:9], v[186:189], v[218:221], v[4:7]
	s_barrier
	s_setprio 0
	s_add_i32 s70, s70, 2
	s_add_u32 s60, s60, 0x100
	s_addc_u32 s61, s61, 0
	s_cmp_gt_u32 s70, 29
	s_cbranch_scc1 .LBB0_1204

.LBB0_1364:
	ds_read_b128 v[86:89], v220
	ds_read_b128 v[90:93], v220 offset:1024
	ds_read_b128 v[114:117], v220 offset:2048
	ds_read_b128 v[118:121], v220 offset:3072
	ds_read_b128 v[146:149], v221
	ds_read_b128 v[150:153], v221 offset:1024
	ds_read_b128 v[154:157], v221 offset:2048
	ds_read_b128 v[158:161], v221 offset:3072
	s_add_u32 s10, s8, 0xfff80080
	s_addc_u32 s11, s9, -1
	s_cmp_eq_u32 s63, 28
	s_cselect_b32 s13, s7, s11
	s_cselect_b32 s12, s14, s10
	s_cselect_b32 s11, s15, s41
	s_cselect_b32 s10, s18, s39
	v_lshl_add_u64 v[208:209], s[8:9], 0, v[180:181]
	s_add_i32 m0, s47, 0xc000
	ds_read_b128 v[162:165], v222
	ds_read_b128 v[166:169], v222 offset:1024
	ds_read_b128 v[184:187], v222 offset:2048
	ds_read_b128 v[188:191], v222 offset:3072
	ds_read_b128 v[192:195], v222 offset:4096
	ds_read_b128 v[196:199], v222 offset:5120
	ds_read_b128 v[200:203], v222 offset:6144
	ds_read_b128 v[204:207], v222 offset:7168
	global_load_lds_dwordx4 v[208:209], off
	v_lshl_add_u64 v[208:209], s[8:9], 0, v[178:179]
	s_add_i32 m0, s47, 0xe000
	s_nop 0
	global_load_lds_dwordx4 v[208:209], off
	s_waitcnt vmcnt(8)
	s_waitcnt lgkmcnt(0)
	s_setprio 1
	s_barrier
	v_mfma_f32_16x16x32_bf16 v[142:145], v[86:89], v[162:165], v[142:145]
	v_mfma_f32_16x16x32_bf16 v[138:141], v[114:117], v[162:165], v[138:141]
	v_mfma_f32_16x16x32_bf16 v[126:129], v[86:89], v[184:187], v[126:129]
	v_mfma_f32_16x16x32_bf16 v[122:125], v[114:117], v[184:187], v[122:125]
	v_mfma_f32_16x16x32_bf16 v[102:105], v[86:89], v[192:195], v[102:105]
	v_mfma_f32_16x16x32_bf16 v[98:101], v[114:117], v[192:195], v[98:101]
	v_mfma_f32_16x16x32_bf16 v[78:81], v[86:89], v[200:203], v[78:81]
	v_mfma_f32_16x16x32_bf16 v[74:77], v[114:117], v[200:203], v[74:77]
	v_mfma_f32_16x16x32_bf16 v[142:145], v[90:93], v[166:169], v[142:145]
	v_mfma_f32_16x16x32_bf16 v[138:141], v[118:121], v[166:169], v[138:141]
	v_mfma_f32_16x16x32_bf16 v[126:129], v[90:93], v[188:191], v[126:129]
	v_mfma_f32_16x16x32_bf16 v[122:125], v[118:121], v[188:191], v[122:125]
	v_mfma_f32_16x16x32_bf16 v[102:105], v[90:93], v[196:199], v[102:105]
	v_mfma_f32_16x16x32_bf16 v[98:101], v[118:121], v[196:199], v[98:101]
	v_mfma_f32_16x16x32_bf16 v[78:81], v[90:93], v[204:207], v[78:81]
	v_mfma_f32_16x16x32_bf16 v[74:77], v[118:121], v[204:207], v[74:77]
	v_mfma_f32_16x16x32_bf16 v[134:137], v[146:149], v[162:165], v[134:137]
	v_mfma_f32_16x16x32_bf16 v[130:133], v[154:157], v[162:165], v[130:133]
	v_mfma_f32_16x16x32_bf16 v[110:113], v[146:149], v[184:187], v[110:113]
	v_mfma_f32_16x16x32_bf16 v[106:109], v[154:157], v[184:187], v[106:109]
	v_mfma_f32_16x16x32_bf16 v[94:97], v[146:149], v[192:195], v[94:97]
	v_mfma_f32_16x16x32_bf16 v[82:85], v[154:157], v[192:195], v[82:85]
	v_mfma_f32_16x16x32_bf16 v[70:73], v[146:149], v[200:203], v[70:73]
	v_mfma_f32_16x16x32_bf16 v[66:69], v[154:157], v[200:203], v[66:69]
	v_mfma_f32_16x16x32_bf16 v[134:137], v[150:153], v[166:169], v[134:137]
	v_mfma_f32_16x16x32_bf16 v[130:133], v[158:161], v[166:169], v[130:133]
	v_mfma_f32_16x16x32_bf16 v[110:113], v[150:153], v[188:191], v[110:113]
	v_mfma_f32_16x16x32_bf16 v[106:109], v[158:161], v[188:191], v[106:109]
	v_mfma_f32_16x16x32_bf16 v[94:97], v[150:153], v[196:199], v[94:97]
	v_mfma_f32_16x16x32_bf16 v[82:85], v[158:161], v[196:199], v[82:85]
	v_mfma_f32_16x16x32_bf16 v[70:73], v[150:153], v[204:207], v[70:73]
	v_mfma_f32_16x16x32_bf16 v[66:69], v[158:161], v[204:207], v[66:69]
	s_barrier
	s_setprio 0
	s_add_i32 s64, s60, s49
	v_lshl_add_u64 v[208:209], s[10:11], 0, v[172:173]
	s_mov_b32 m0, s64
	ds_read_b128 v[162:165], v222 offset:16384
	ds_read_b128 v[166:169], v222 offset:17408
	ds_read_b128 v[184:187], v222 offset:18432
	ds_read_b128 v[188:191], v222 offset:19456
	ds_read_b128 v[192:195], v222 offset:20480
	ds_read_b128 v[196:199], v222 offset:21504
	ds_read_b128 v[200:203], v222 offset:22528
	ds_read_b128 v[204:207], v222 offset:23552
	global_load_lds_dwordx4 v[208:209], off
	s_add_i32 m0, s64, 0x2000
	s_add_u32 s64, s10, 0x80000
	v_lshl_add_u64 v[210:211], s[10:11], 0, v[176:177]
	s_addc_u32 s65, s11, 0
	s_add_i32 s66, s61, s49
	global_load_lds_dwordx4 v[210:211], off
	v_lshl_add_u64 v[212:213], s[64:65], 0, v[172:173]
	s_mov_b32 m0, s66
	v_lshl_add_u64 v[214:215], s[12:13], 0, v[174:175]
	global_load_lds_dwordx4 v[212:213], off
	v_lshl_add_u64 v[212:213], s[64:65], 0, v[176:177]
	s_add_i32 m0, s66, 0x2000
	s_nop 0
	global_load_lds_dwordx4 v[212:213], off
	v_lshl_add_u64 v[212:213], s[12:13], 0, v[170:171]
	s_mov_b32 m0, s47
	s_nop 0
	global_load_lds_dwordx4 v[212:213], off
	s_mov_b32 m0, s50
	s_nop 0
	global_load_lds_dwordx4 v[214:215], off
	s_waitcnt vmcnt(8)
	s_waitcnt lgkmcnt(0)
	s_setprio 1
	s_barrier
	v_mfma_f32_16x16x32_bf16 v[62:65], v[86:89], v[162:165], v[62:65]
	v_mfma_f32_16x16x32_bf16 v[58:61], v[114:117], v[162:165], v[58:61]
	v_mfma_f32_16x16x32_bf16 v[46:49], v[86:89], v[184:187], v[46:49]
	v_mfma_f32_16x16x32_bf16 v[42:45], v[114:117], v[184:187], v[42:45]
	v_mfma_f32_16x16x32_bf16 v[30:33], v[86:89], v[192:195], v[30:33]
	v_mfma_f32_16x16x32_bf16 v[26:29], v[114:117], v[192:195], v[26:29]
	v_mfma_f32_16x16x32_bf16 v[14:17], v[86:89], v[200:203], v[14:17]
	v_mfma_f32_16x16x32_bf16 v[10:13], v[114:117], v[200:203], v[10:13]
	v_mfma_f32_16x16x32_bf16 v[62:65], v[90:93], v[166:169], v[62:65]
	v_mfma_f32_16x16x32_bf16 v[58:61], v[118:121], v[166:169], v[58:61]
	v_mfma_f32_16x16x32_bf16 v[46:49], v[90:93], v[188:191], v[46:49]
	v_mfma_f32_16x16x32_bf16 v[42:45], v[118:121], v[188:191], v[42:45]
	v_mfma_f32_16x16x32_bf16 v[30:33], v[90:93], v[196:199], v[30:33]
	v_mfma_f32_16x16x32_bf16 v[26:29], v[118:121], v[196:199], v[26:29]
	v_mfma_f32_16x16x32_bf16 v[14:17], v[90:93], v[204:207], v[14:17]
	v_mfma_f32_16x16x32_bf16 v[10:13], v[118:121], v[204:207], v[10:13]
	v_mfma_f32_16x16x32_bf16 v[54:57], v[146:149], v[162:165], v[54:57]
	v_mfma_f32_16x16x32_bf16 v[50:53], v[154:157], v[162:165], v[50:53]
	v_mfma_f32_16x16x32_bf16 v[38:41], v[146:149], v[184:187], v[38:41]
	v_mfma_f32_16x16x32_bf16 v[34:37], v[154:157], v[184:187], v[34:37]
	v_mfma_f32_16x16x32_bf16 v[22:25], v[146:149], v[192:195], v[22:25]
	v_mfma_f32_16x16x32_bf16 v[18:21], v[154:157], v[192:195], v[18:21]
	v_mfma_f32_16x16x32_bf16 v[6:9], v[146:149], v[200:203], v[6:9]
	v_mfma_f32_16x16x32_bf16 v[2:5], v[154:157], v[200:203], v[2:5]
	v_mfma_f32_16x16x32_bf16 v[54:57], v[150:153], v[166:169], v[54:57]
	v_mfma_f32_16x16x32_bf16 v[50:53], v[158:161], v[166:169], v[50:53]
	v_mfma_f32_16x16x32_bf16 v[38:41], v[150:153], v[188:191], v[38:41]
	v_mfma_f32_16x16x32_bf16 v[34:37], v[158:161], v[188:191], v[34:37]
	v_mfma_f32_16x16x32_bf16 v[22:25], v[150:153], v[196:199], v[22:25]
	v_mfma_f32_16x16x32_bf16 v[18:21], v[158:161], v[196:199], v[18:21]
	v_mfma_f32_16x16x32_bf16 v[6:9], v[150:153], v[204:207], v[6:9]
	v_mfma_f32_16x16x32_bf16 v[2:5], v[158:161], v[204:207], v[2:5]
	s_barrier
	s_setprio 0
	s_add_i32 s64, 0, 0x18000
	s_add_i32 s65, 0, 0x1c000
	v_add_u32_e32 v118, s64, v219
	v_add_u32_e32 v158, s65, v219
	ds_read_b128 v[86:89], v118
	ds_read_b128 v[90:93], v118 offset:1024
	ds_read_b128 v[114:117], v118 offset:2048
	ds_read_b128 v[118:121], v118 offset:3072
	ds_read_b128 v[146:149], v158
	ds_read_b128 v[150:153], v158 offset:1024
	ds_read_b128 v[154:157], v158 offset:2048
	ds_read_b128 v[158:161], v158 offset:3072
	s_add_u32 s12, s12, 0x80000
	s_addc_u32 s13, s13, 0
	s_mov_b32 m0, s51
	v_lshl_add_u64 v[216:217], s[12:13], 0, v[170:171]
	ds_read_b128 v[162:165], v222 offset:32768
	ds_read_b128 v[166:169], v222 offset:33792
	ds_read_b128 v[184:187], v222 offset:34816
	ds_read_b128 v[188:191], v222 offset:35840
	ds_read_b128 v[192:195], v222 offset:36864
	ds_read_b128 v[196:199], v222 offset:37888
	ds_read_b128 v[200:203], v222 offset:38912
	ds_read_b128 v[204:207], v222 offset:39936
	global_load_lds_dwordx4 v[216:217], off
	v_lshl_add_u64 v[216:217], s[12:13], 0, v[174:175]
	s_mov_b32 m0, s52
	s_nop 0
	global_load_lds_dwordx4 v[216:217], off
	s_waitcnt vmcnt(8)
	s_waitcnt lgkmcnt(0)
	s_setprio 1
	s_barrier
	v_mfma_f32_16x16x32_bf16 v[142:145], v[86:89], v[162:165], v[142:145]
	v_mfma_f32_16x16x32_bf16 v[138:141], v[114:117], v[162:165], v[138:141]
	v_mfma_f32_16x16x32_bf16 v[126:129], v[86:89], v[184:187], v[126:129]
	v_mfma_f32_16x16x32_bf16 v[122:125], v[114:117], v[184:187], v[122:125]
	v_mfma_f32_16x16x32_bf16 v[102:105], v[86:89], v[192:195], v[102:105]
	v_mfma_f32_16x16x32_bf16 v[98:101], v[114:117], v[192:195], v[98:101]
	v_mfma_f32_16x16x32_bf16 v[78:81], v[86:89], v[200:203], v[78:81]
	v_mfma_f32_16x16x32_bf16 v[74:77], v[114:117], v[200:203], v[74:77]
	v_mfma_f32_16x16x32_bf16 v[142:145], v[90:93], v[166:169], v[142:145]
	v_mfma_f32_16x16x32_bf16 v[138:141], v[118:121], v[166:169], v[138:141]
	v_mfma_f32_16x16x32_bf16 v[126:129], v[90:93], v[188:191], v[126:129]
	v_mfma_f32_16x16x32_bf16 v[122:125], v[118:121], v[188:191], v[122:125]
	v_mfma_f32_16x16x32_bf16 v[102:105], v[90:93], v[196:199], v[102:105]
	v_mfma_f32_16x16x32_bf16 v[98:101], v[118:121], v[196:199], v[98:101]
	v_mfma_f32_16x16x32_bf16 v[78:81], v[90:93], v[204:207], v[78:81]
	v_mfma_f32_16x16x32_bf16 v[74:77], v[118:121], v[204:207], v[74:77]
	v_mfma_f32_16x16x32_bf16 v[134:137], v[146:149], v[162:165], v[134:137]
	v_mfma_f32_16x16x32_bf16 v[130:133], v[154:157], v[162:165], v[130:133]
	v_mfma_f32_16x16x32_bf16 v[110:113], v[146:149], v[184:187], v[110:113]
	v_mfma_f32_16x16x32_bf16 v[106:109], v[154:157], v[184:187], v[106:109]
	v_mfma_f32_16x16x32_bf16 v[94:97], v[146:149], v[192:195], v[94:97]
	v_mfma_f32_16x16x32_bf16 v[82:85], v[154:157], v[192:195], v[82:85]
	v_mfma_f32_16x16x32_bf16 v[70:73], v[146:149], v[200:203], v[70:73]
	v_mfma_f32_16x16x32_bf16 v[66:69], v[154:157], v[200:203], v[66:69]
	v_mfma_f32_16x16x32_bf16 v[134:137], v[150:153], v[166:169], v[134:137]
	v_mfma_f32_16x16x32_bf16 v[130:133], v[158:161], v[166:169], v[130:133]
	v_mfma_f32_16x16x32_bf16 v[110:113], v[150:153], v[188:191], v[110:113]
	v_mfma_f32_16x16x32_bf16 v[106:109], v[158:161], v[188:191], v[106:109]
	v_mfma_f32_16x16x32_bf16 v[94:97], v[150:153], v[196:199], v[94:97]
	v_mfma_f32_16x16x32_bf16 v[82:85], v[158:161], v[196:199], v[82:85]
	v_mfma_f32_16x16x32_bf16 v[70:73], v[150:153], v[204:207], v[70:73]
	v_mfma_f32_16x16x32_bf16 v[66:69], v[158:161], v[204:207], v[66:69]
	s_barrier
	s_setprio 0
	s_add_i32 s12, s64, s49
	v_lshl_add_u64 v[208:209], v[208:209], 0, s[30:31]
	s_mov_b32 m0, s12
	ds_read_b128 v[162:165], v222 offset:49152
	ds_read_b128 v[166:169], v222 offset:50176
	ds_read_b128 v[184:187], v222 offset:51200
	ds_read_b128 v[188:191], v222 offset:52224
	ds_read_b128 v[192:195], v222 offset:53248
	ds_read_b128 v[196:199], v222 offset:54272
	ds_read_b128 v[200:203], v222 offset:55296
	ds_read_b128 v[204:207], v222 offset:56320
	global_load_lds_dwordx4 v[208:209], off
	s_add_i32 m0, s12, 0x2000
	s_add_u32 s10, s10, 0x80080
	v_lshl_add_u64 v[208:209], v[210:211], 0, s[30:31]
	s_addc_u32 s11, s11, 0
	s_add_i32 s12, s65, s49
	global_load_lds_dwordx4 v[208:209], off
	v_lshl_add_u64 v[208:209], s[10:11], 0, v[172:173]
	s_mov_b32 m0, s12
	s_nop 0
	global_load_lds_dwordx4 v[208:209], off
	v_lshl_add_u64 v[208:209], s[10:11], 0, v[176:177]
	s_add_i32 m0, s12, 0x2000
	s_nop 0
	global_load_lds_dwordx4 v[208:209], off
	v_lshl_add_u64 v[208:209], v[212:213], 0, s[30:31]
	s_mov_b32 m0, s56
	s_nop 0
	global_load_lds_dwordx4 v[208:209], off
	v_lshl_add_u64 v[208:209], v[214:215], 0, s[30:31]
	s_mov_b32 m0, s57
	s_nop 0
	global_load_lds_dwordx4 v[208:209], off
	s_waitcnt vmcnt(8)
	s_waitcnt lgkmcnt(0)
	s_setprio 1
	s_barrier
	v_mfma_f32_16x16x32_bf16 v[62:65], v[86:89], v[162:165], v[62:65]
	v_mfma_f32_16x16x32_bf16 v[58:61], v[114:117], v[162:165], v[58:61]
	v_mfma_f32_16x16x32_bf16 v[46:49], v[86:89], v[184:187], v[46:49]
	v_mfma_f32_16x16x32_bf16 v[42:45], v[114:117], v[184:187], v[42:45]
	v_mfma_f32_16x16x32_bf16 v[30:33], v[86:89], v[192:195], v[30:33]
	v_mfma_f32_16x16x32_bf16 v[26:29], v[114:117], v[192:195], v[26:29]
	v_mfma_f32_16x16x32_bf16 v[14:17], v[86:89], v[200:203], v[14:17]
	v_mfma_f32_16x16x32_bf16 v[10:13], v[114:117], v[200:203], v[10:13]
	v_mfma_f32_16x16x32_bf16 v[62:65], v[90:93], v[166:169], v[62:65]
	v_mfma_f32_16x16x32_bf16 v[58:61], v[118:121], v[166:169], v[58:61]
	v_mfma_f32_16x16x32_bf16 v[46:49], v[90:93], v[188:191], v[46:49]
	v_mfma_f32_16x16x32_bf16 v[42:45], v[118:121], v[188:191], v[42:45]
	v_mfma_f32_16x16x32_bf16 v[30:33], v[90:93], v[196:199], v[30:33]
	v_mfma_f32_16x16x32_bf16 v[26:29], v[118:121], v[196:199], v[26:29]
	v_mfma_f32_16x16x32_bf16 v[14:17], v[90:93], v[204:207], v[14:17]
	v_mfma_f32_16x16x32_bf16 v[10:13], v[118:121], v[204:207], v[10:13]
	v_mfma_f32_16x16x32_bf16 v[54:57], v[146:149], v[162:165], v[54:57]
	v_mfma_f32_16x16x32_bf16 v[50:53], v[154:157], v[162:165], v[50:53]
	v_mfma_f32_16x16x32_bf16 v[38:41], v[146:149], v[184:187], v[38:41]
	v_mfma_f32_16x16x32_bf16 v[34:37], v[154:157], v[184:187], v[34:37]
	v_mfma_f32_16x16x32_bf16 v[22:25], v[146:149], v[192:195], v[22:25]
	v_mfma_f32_16x16x32_bf16 v[18:21], v[154:157], v[192:195], v[18:21]
	v_mfma_f32_16x16x32_bf16 v[6:9], v[146:149], v[200:203], v[6:9]
	v_mfma_f32_16x16x32_bf16 v[2:5], v[154:157], v[200:203], v[2:5]
	v_mfma_f32_16x16x32_bf16 v[54:57], v[150:153], v[166:169], v[54:57]
	v_mfma_f32_16x16x32_bf16 v[50:53], v[158:161], v[166:169], v[50:53]
	v_mfma_f32_16x16x32_bf16 v[38:41], v[150:153], v[188:191], v[38:41]
	v_mfma_f32_16x16x32_bf16 v[34:37], v[158:161], v[188:191], v[34:37]
	v_mfma_f32_16x16x32_bf16 v[22:25], v[150:153], v[196:199], v[22:25]
	v_mfma_f32_16x16x32_bf16 v[18:21], v[158:161], v[196:199], v[18:21]
	v_mfma_f32_16x16x32_bf16 v[6:9], v[150:153], v[204:207], v[6:9]
	v_mfma_f32_16x16x32_bf16 v[2:5], v[158:161], v[204:207], v[2:5]
	s_barrier
	s_setprio 0
	s_add_i32 s63, s63, 2
	s_add_u32 s39, s39, 0x100
	s_addc_u32 s41, s41, 0
	s_add_u32 s8, s8, 0x100
	s_addc_u32 s9, s9, 0
	s_cmp_gt_u32 s63, 29
	s_cbranch_scc0 .LBB0_1364
	s_and_b64 vcc, exec, s[36:37]
	s_cbranch_vccz .LBB0_1367
	s_barrier

.LBB0_1390:
	ds_read_b128 v[148:151], v143
	ds_read_b128 v[152:155], v143 offset:1024
	ds_read_b128 v[156:159], v143 offset:2048
	ds_read_b128 v[160:163], v143 offset:3072
	ds_read_b128 v[164:167], v144
	ds_read_b128 v[168:171], v144 offset:1024
	ds_read_b128 v[172:175], v144 offset:2048
	ds_read_b128 v[176:179], v144 offset:3072
	s_add_u32 s12, s10, 0x100
	s_addc_u32 s13, s11, 0
	s_cmp_lg_u32 s0, 4
	s_cselect_b32 s14, s12, 0
	s_cselect_b32 s15, s13, 0
	s_add_u32 s16, s6, s14
	s_addc_u32 s17, s7, s15
	s_add_u32 s14, s4, s14
	s_addc_u32 s15, s5, s15
	s_mov_b32 m0, s1
	v_lshl_add_u64 v[212:213], v[140:141], 0, s[10:11]
	ds_read_b128 v[180:183], v145
	ds_read_b128 v[184:187], v145 offset:1024
	ds_read_b128 v[188:191], v145 offset:2048
	ds_read_b128 v[192:195], v145 offset:3072
	ds_read_b128 v[196:199], v145 offset:4096
	ds_read_b128 v[200:203], v145 offset:5120
	ds_read_b128 v[204:207], v145 offset:6144
	ds_read_b128 v[208:211], v145 offset:7168
	global_load_lds_dwordx4 v[212:213], off
	v_lshl_add_u64 v[212:213], v[138:139], 0, s[10:11]
	s_mov_b32 m0, s30
	s_nop 0
	global_load_lds_dwordx4 v[212:213], off
	s_waitcnt vmcnt(8)
	s_waitcnt lgkmcnt(0)
	s_setprio 1
	s_barrier
	v_mfma_f32_16x16x32_bf16 v[126:129], v[148:151], v[180:183], v[126:129]
	v_mfma_f32_16x16x32_bf16 v[122:125], v[156:159], v[180:183], v[122:125]
	v_mfma_f32_16x16x32_bf16 v[118:121], v[148:151], v[188:191], v[118:121]
	v_mfma_f32_16x16x32_bf16 v[114:117], v[156:159], v[188:191], v[114:117]
	v_mfma_f32_16x16x32_bf16 v[106:109], v[148:151], v[196:199], v[106:109]
	v_mfma_f32_16x16x32_bf16 v[98:101], v[156:159], v[196:199], v[98:101]
	v_mfma_f32_16x16x32_bf16 v[90:93], v[148:151], v[204:207], v[90:93]
	v_mfma_f32_16x16x32_bf16 v[82:85], v[156:159], v[204:207], v[82:85]
	v_mfma_f32_16x16x32_bf16 v[126:129], v[152:155], v[184:187], v[126:129]
	v_mfma_f32_16x16x32_bf16 v[122:125], v[160:163], v[184:187], v[122:125]
	v_mfma_f32_16x16x32_bf16 v[118:121], v[152:155], v[192:195], v[118:121]
	v_mfma_f32_16x16x32_bf16 v[114:117], v[160:163], v[192:195], v[114:117]
	v_mfma_f32_16x16x32_bf16 v[106:109], v[152:155], v[200:203], v[106:109]
	v_mfma_f32_16x16x32_bf16 v[98:101], v[160:163], v[200:203], v[98:101]
	v_mfma_f32_16x16x32_bf16 v[90:93], v[152:155], v[208:211], v[90:93]
	v_mfma_f32_16x16x32_bf16 v[82:85], v[160:163], v[208:211], v[82:85]
	v_mfma_f32_16x16x32_bf16 v[110:113], v[164:167], v[180:183], v[110:113]
	v_mfma_f32_16x16x32_bf16 v[102:105], v[172:175], v[180:183], v[102:105]
	v_mfma_f32_16x16x32_bf16 v[94:97], v[164:167], v[188:191], v[94:97]
	v_mfma_f32_16x16x32_bf16 v[86:89], v[172:175], v[188:191], v[86:89]
	v_mfma_f32_16x16x32_bf16 v[78:81], v[164:167], v[196:199], v[78:81]
	v_mfma_f32_16x16x32_bf16 v[74:77], v[172:175], v[196:199], v[74:77]
	v_mfma_f32_16x16x32_bf16 v[70:73], v[164:167], v[204:207], v[70:73]
	v_mfma_f32_16x16x32_bf16 v[66:69], v[172:175], v[204:207], v[66:69]
	v_mfma_f32_16x16x32_bf16 v[110:113], v[168:171], v[184:187], v[110:113]
	v_mfma_f32_16x16x32_bf16 v[102:105], v[176:179], v[184:187], v[102:105]
	v_mfma_f32_16x16x32_bf16 v[94:97], v[168:171], v[192:195], v[94:97]
	v_mfma_f32_16x16x32_bf16 v[86:89], v[176:179], v[192:195], v[86:89]
	v_mfma_f32_16x16x32_bf16 v[78:81], v[168:171], v[200:203], v[78:81]
	v_mfma_f32_16x16x32_bf16 v[74:77], v[176:179], v[200:203], v[74:77]
	v_mfma_f32_16x16x32_bf16 v[70:73], v[168:171], v[208:211], v[70:73]
	v_mfma_f32_16x16x32_bf16 v[66:69], v[176:179], v[208:211], v[66:69]
	s_barrier
	s_setprio 0
	s_mov_b32 m0, s31
	v_lshl_add_u64 v[212:213], s[14:15], 0, v[132:133]
	s_add_u32 s10, s14, 0x80000
	ds_read_b128 v[180:183], v145 offset:16384
	ds_read_b128 v[184:187], v145 offset:17408
	ds_read_b128 v[188:191], v145 offset:18432
	ds_read_b128 v[192:195], v145 offset:19456
	ds_read_b128 v[196:199], v145 offset:20480
	ds_read_b128 v[200:203], v145 offset:21504
	ds_read_b128 v[204:207], v145 offset:22528
	ds_read_b128 v[208:211], v145 offset:23552
	global_load_lds_dwordx4 v[212:213], off
	v_lshl_add_u64 v[214:215], s[14:15], 0, v[136:137]
	s_mov_b32 m0, s33
	s_addc_u32 s11, s15, 0
	global_load_lds_dwordx4 v[214:215], off
	v_lshl_add_u64 v[216:217], s[10:11], 0, v[132:133]
	s_mov_b32 m0, s34
	v_lshl_add_u64 v[218:219], s[16:17], 0, v[134:135]
	global_load_lds_dwordx4 v[216:217], off
	v_lshl_add_u64 v[216:217], s[10:11], 0, v[136:137]
	s_mov_b32 m0, s35
	s_nop 0
	global_load_lds_dwordx4 v[216:217], off
	v_lshl_add_u64 v[216:217], s[16:17], 0, v[130:131]
	s_mov_b32 m0, s20
	s_nop 0
	global_load_lds_dwordx4 v[216:217], off
	s_mov_b32 m0, s23
	s_nop 0
	global_load_lds_dwordx4 v[218:219], off
	s_waitcnt vmcnt(8)
	s_waitcnt lgkmcnt(0)
	s_setprio 1
	s_barrier
	v_mfma_f32_16x16x32_bf16 v[62:65], v[148:151], v[180:183], v[62:65]
	v_mfma_f32_16x16x32_bf16 v[58:61], v[156:159], v[180:183], v[58:61]
	v_mfma_f32_16x16x32_bf16 v[54:57], v[148:151], v[188:191], v[54:57]
	v_mfma_f32_16x16x32_bf16 v[50:53], v[156:159], v[188:191], v[50:53]
	v_mfma_f32_16x16x32_bf16 v[42:45], v[148:151], v[196:199], v[42:45]
	v_mfma_f32_16x16x32_bf16 v[34:37], v[156:159], v[196:199], v[34:37]
	v_mfma_f32_16x16x32_bf16 v[26:29], v[148:151], v[204:207], v[26:29]
	v_mfma_f32_16x16x32_bf16 v[18:21], v[156:159], v[204:207], v[18:21]
	v_mfma_f32_16x16x32_bf16 v[62:65], v[152:155], v[184:187], v[62:65]
	v_mfma_f32_16x16x32_bf16 v[58:61], v[160:163], v[184:187], v[58:61]
	v_mfma_f32_16x16x32_bf16 v[54:57], v[152:155], v[192:195], v[54:57]
	v_mfma_f32_16x16x32_bf16 v[50:53], v[160:163], v[192:195], v[50:53]
	v_mfma_f32_16x16x32_bf16 v[42:45], v[152:155], v[200:203], v[42:45]
	v_mfma_f32_16x16x32_bf16 v[34:37], v[160:163], v[200:203], v[34:37]
	v_mfma_f32_16x16x32_bf16 v[26:29], v[152:155], v[208:211], v[26:29]
	v_mfma_f32_16x16x32_bf16 v[18:21], v[160:163], v[208:211], v[18:21]
	v_mfma_f32_16x16x32_bf16 v[46:49], v[164:167], v[180:183], v[46:49]
	v_mfma_f32_16x16x32_bf16 v[38:41], v[172:175], v[180:183], v[38:41]
	v_mfma_f32_16x16x32_bf16 v[30:33], v[164:167], v[188:191], v[30:33]
	v_mfma_f32_16x16x32_bf16 v[22:25], v[172:175], v[188:191], v[22:25]
	v_mfma_f32_16x16x32_bf16 v[14:17], v[164:167], v[196:199], v[14:17]
	v_mfma_f32_16x16x32_bf16 v[10:13], v[172:175], v[196:199], v[10:13]
	v_mfma_f32_16x16x32_bf16 v[6:9], v[164:167], v[204:207], v[6:9]
	v_mfma_f32_16x16x32_bf16 v[2:5], v[172:175], v[204:207], v[2:5]
	v_mfma_f32_16x16x32_bf16 v[46:49], v[168:171], v[184:187], v[46:49]
	v_mfma_f32_16x16x32_bf16 v[38:41], v[176:179], v[184:187], v[38:41]
	v_mfma_f32_16x16x32_bf16 v[30:33], v[168:171], v[192:195], v[30:33]
	v_mfma_f32_16x16x32_bf16 v[22:25], v[176:179], v[192:195], v[22:25]
	v_mfma_f32_16x16x32_bf16 v[14:17], v[168:171], v[200:203], v[14:17]
	v_mfma_f32_16x16x32_bf16 v[10:13], v[176:179], v[200:203], v[10:13]
	v_mfma_f32_16x16x32_bf16 v[6:9], v[168:171], v[208:211], v[6:9]
	v_mfma_f32_16x16x32_bf16 v[2:5], v[176:179], v[208:211], v[2:5]
	s_barrier
	s_setprio 0
	ds_read_b128 v[148:151], v146
	ds_read_b128 v[152:155], v146 offset:1024
	ds_read_b128 v[156:159], v146 offset:2048
	ds_read_b128 v[160:163], v146 offset:3072
	ds_read_b128 v[164:167], v147
	ds_read_b128 v[168:171], v147 offset:1024
	ds_read_b128 v[172:175], v147 offset:2048
	ds_read_b128 v[176:179], v147 offset:3072
	s_add_u32 s10, s16, 0x80000
	s_addc_u32 s11, s17, 0
	s_mov_b32 m0, s24
	v_lshl_add_u64 v[220:221], s[10:11], 0, v[130:131]
	ds_read_b128 v[180:183], v145 offset:32768
	ds_read_b128 v[184:187], v145 offset:33792
	ds_read_b128 v[188:191], v145 offset:34816
	ds_read_b128 v[192:195], v145 offset:35840
	ds_read_b128 v[196:199], v145 offset:36864
	ds_read_b128 v[200:203], v145 offset:37888
	ds_read_b128 v[204:207], v145 offset:38912
	ds_read_b128 v[208:211], v145 offset:39936
	global_load_lds_dwordx4 v[220:221], off
	v_lshl_add_u64 v[220:221], s[10:11], 0, v[134:135]
	s_mov_b32 m0, s26
	s_nop 0
	global_load_lds_dwordx4 v[220:221], off
	s_waitcnt vmcnt(8)
	s_waitcnt lgkmcnt(0)
	s_setprio 1
	s_barrier
	v_mfma_f32_16x16x32_bf16 v[126:129], v[148:151], v[180:183], v[126:129]
	v_mfma_f32_16x16x32_bf16 v[122:125], v[156:159], v[180:183], v[122:125]
	v_mfma_f32_16x16x32_bf16 v[118:121], v[148:151], v[188:191], v[118:121]
	v_mfma_f32_16x16x32_bf16 v[114:117], v[156:159], v[188:191], v[114:117]
	v_mfma_f32_16x16x32_bf16 v[106:109], v[148:151], v[196:199], v[106:109]
	v_mfma_f32_16x16x32_bf16 v[98:101], v[156:159], v[196:199], v[98:101]
	v_mfma_f32_16x16x32_bf16 v[90:93], v[148:151], v[204:207], v[90:93]
	v_mfma_f32_16x16x32_bf16 v[82:85], v[156:159], v[204:207], v[82:85]
	v_mfma_f32_16x16x32_bf16 v[126:129], v[152:155], v[184:187], v[126:129]
	v_mfma_f32_16x16x32_bf16 v[122:125], v[160:163], v[184:187], v[122:125]
	v_mfma_f32_16x16x32_bf16 v[118:121], v[152:155], v[192:195], v[118:121]
	v_mfma_f32_16x16x32_bf16 v[114:117], v[160:163], v[192:195], v[114:117]
	v_mfma_f32_16x16x32_bf16 v[106:109], v[152:155], v[200:203], v[106:109]
	v_mfma_f32_16x16x32_bf16 v[98:101], v[160:163], v[200:203], v[98:101]
	v_mfma_f32_16x16x32_bf16 v[90:93], v[152:155], v[208:211], v[90:93]
	v_mfma_f32_16x16x32_bf16 v[82:85], v[160:163], v[208:211], v[82:85]
	v_mfma_f32_16x16x32_bf16 v[110:113], v[164:167], v[180:183], v[110:113]
	v_mfma_f32_16x16x32_bf16 v[102:105], v[172:175], v[180:183], v[102:105]
	v_mfma_f32_16x16x32_bf16 v[94:97], v[164:167], v[188:191], v[94:97]
	v_mfma_f32_16x16x32_bf16 v[86:89], v[172:175], v[188:191], v[86:89]
	v_mfma_f32_16x16x32_bf16 v[78:81], v[164:167], v[196:199], v[78:81]
	v_mfma_f32_16x16x32_bf16 v[74:77], v[172:175], v[196:199], v[74:77]
	v_mfma_f32_16x16x32_bf16 v[70:73], v[164:167], v[204:207], v[70:73]
	v_mfma_f32_16x16x32_bf16 v[66:69], v[172:175], v[204:207], v[66:69]
	v_mfma_f32_16x16x32_bf16 v[110:113], v[168:171], v[184:187], v[110:113]
	v_mfma_f32_16x16x32_bf16 v[102:105], v[176:179], v[184:187], v[102:105]
	v_mfma_f32_16x16x32_bf16 v[94:97], v[168:171], v[192:195], v[94:97]
	v_mfma_f32_16x16x32_bf16 v[86:89], v[176:179], v[192:195], v[86:89]
	v_mfma_f32_16x16x32_bf16 v[78:81], v[168:171], v[200:203], v[78:81]
	v_mfma_f32_16x16x32_bf16 v[74:77], v[176:179], v[200:203], v[74:77]
	v_mfma_f32_16x16x32_bf16 v[70:73], v[168:171], v[208:211], v[70:73]
	v_mfma_f32_16x16x32_bf16 v[66:69], v[176:179], v[208:211], v[66:69]
	s_barrier
	s_setprio 0
	s_mov_b32 m0, s36
	v_lshl_add_u64 v[212:213], v[212:213], 0, s[8:9]
	s_add_u32 s10, s14, 0x80080
	ds_read_b128 v[180:183], v145 offset:49152
	ds_read_b128 v[184:187], v145 offset:50176
	ds_read_b128 v[188:191], v145 offset:51200
	ds_read_b128 v[192:195], v145 offset:52224
	ds_read_b128 v[196:199], v145 offset:53248
	ds_read_b128 v[200:203], v145 offset:54272
	ds_read_b128 v[204:207], v145 offset:55296
	ds_read_b128 v[208:211], v145 offset:56320
	global_load_lds_dwordx4 v[212:213], off
	v_lshl_add_u64 v[212:213], v[214:215], 0, s[8:9]
	s_mov_b32 m0, s37
	s_addc_u32 s11, s15, 0
	global_load_lds_dwordx4 v[212:213], off
	v_lshl_add_u64 v[212:213], s[10:11], 0, v[132:133]
	s_mov_b32 m0, s38
	s_nop 0
	global_load_lds_dwordx4 v[212:213], off
	v_lshl_add_u64 v[212:213], s[10:11], 0, v[136:137]
	s_mov_b32 m0, s39
	s_nop 0
	global_load_lds_dwordx4 v[212:213], off
	v_lshl_add_u64 v[212:213], v[216:217], 0, s[8:9]
	s_mov_b32 m0, s28
	s_nop 0
	global_load_lds_dwordx4 v[212:213], off
	v_lshl_add_u64 v[212:213], v[218:219], 0, s[8:9]
	s_mov_b32 m0, s29
	s_nop 0
	global_load_lds_dwordx4 v[212:213], off
	s_waitcnt vmcnt(8)
	s_waitcnt lgkmcnt(0)
	s_setprio 1
	s_barrier
	v_mfma_f32_16x16x32_bf16 v[62:65], v[148:151], v[180:183], v[62:65]
	v_mfma_f32_16x16x32_bf16 v[58:61], v[156:159], v[180:183], v[58:61]
	v_mfma_f32_16x16x32_bf16 v[54:57], v[148:151], v[188:191], v[54:57]
	v_mfma_f32_16x16x32_bf16 v[50:53], v[156:159], v[188:191], v[50:53]
	v_mfma_f32_16x16x32_bf16 v[42:45], v[148:151], v[196:199], v[42:45]
	v_mfma_f32_16x16x32_bf16 v[34:37], v[156:159], v[196:199], v[34:37]
	v_mfma_f32_16x16x32_bf16 v[26:29], v[148:151], v[204:207], v[26:29]
	v_mfma_f32_16x16x32_bf16 v[18:21], v[156:159], v[204:207], v[18:21]
	v_mfma_f32_16x16x32_bf16 v[62:65], v[152:155], v[184:187], v[62:65]
	v_mfma_f32_16x16x32_bf16 v[58:61], v[160:163], v[184:187], v[58:61]
	v_mfma_f32_16x16x32_bf16 v[54:57], v[152:155], v[192:195], v[54:57]
	v_mfma_f32_16x16x32_bf16 v[50:53], v[160:163], v[192:195], v[50:53]
	v_mfma_f32_16x16x32_bf16 v[42:45], v[152:155], v[200:203], v[42:45]
	v_mfma_f32_16x16x32_bf16 v[34:37], v[160:163], v[200:203], v[34:37]
	v_mfma_f32_16x16x32_bf16 v[26:29], v[152:155], v[208:211], v[26:29]
	v_mfma_f32_16x16x32_bf16 v[18:21], v[160:163], v[208:211], v[18:21]
	v_mfma_f32_16x16x32_bf16 v[46:49], v[164:167], v[180:183], v[46:49]
	v_mfma_f32_16x16x32_bf16 v[38:41], v[172:175], v[180:183], v[38:41]
	v_mfma_f32_16x16x32_bf16 v[30:33], v[164:167], v[188:191], v[30:33]
	v_mfma_f32_16x16x32_bf16 v[22:25], v[172:175], v[188:191], v[22:25]
	v_mfma_f32_16x16x32_bf16 v[14:17], v[164:167], v[196:199], v[14:17]
	v_mfma_f32_16x16x32_bf16 v[10:13], v[172:175], v[196:199], v[10:13]
	v_mfma_f32_16x16x32_bf16 v[6:9], v[164:167], v[204:207], v[6:9]
	v_mfma_f32_16x16x32_bf16 v[2:5], v[172:175], v[204:207], v[2:5]
	v_mfma_f32_16x16x32_bf16 v[46:49], v[168:171], v[184:187], v[46:49]
	v_mfma_f32_16x16x32_bf16 v[38:41], v[176:179], v[184:187], v[38:41]
	v_mfma_f32_16x16x32_bf16 v[30:33], v[168:171], v[192:195], v[30:33]
	v_mfma_f32_16x16x32_bf16 v[22:25], v[176:179], v[192:195], v[22:25]
	v_mfma_f32_16x16x32_bf16 v[14:17], v[168:171], v[200:203], v[14:17]
	v_mfma_f32_16x16x32_bf16 v[10:13], v[176:179], v[200:203], v[10:13]
	v_mfma_f32_16x16x32_bf16 v[6:9], v[168:171], v[208:211], v[6:9]
	v_mfma_f32_16x16x32_bf16 v[2:5], v[176:179], v[208:211], v[2:5]
	s_barrier
	s_setprio 0
	s_add_i32 s0, s0, 2
	s_cmp_gt_u32 s0, 5
	s_mov_b64 s[10:11], s[12:13]
	s_cbranch_scc0 .LBB0_1390
	s_cmpk_lt_u32 s19, 0x100
	s_cbranch_scc0 .LBB0_1393
	s_barrier

.LBB0_1525:
	ds_read_b128 v[146:149], v152
	ds_read_b128 v[156:159], v152 offset:1024
	ds_read_b128 v[160:163], v152 offset:2048
	ds_read_b128 v[164:167], v152 offset:3072
	ds_read_b128 v[168:171], v153
	ds_read_b128 v[172:175], v153 offset:1024
	ds_read_b128 v[176:179], v153 offset:2048
	ds_read_b128 v[180:183], v153 offset:3072
	s_add_u32 s46, s44, 0xfff80080
	s_addc_u32 s47, s45, -1
	s_cmp_eq_u32 s73, 28
	s_cselect_b32 s49, s37, s47
	s_cselect_b32 s48, s69, s46
	s_cselect_b32 s47, s31, s72
	s_cselect_b32 s46, s70, s71
	v_lshl_add_u64 v[216:217], s[44:45], 0, v[140:141]
	s_add_i32 m0, s43, 0xc000
	ds_read_b128 v[184:187], v154
	ds_read_b128 v[188:191], v154 offset:1024
	ds_read_b128 v[192:195], v154 offset:2048
	ds_read_b128 v[196:199], v154 offset:3072
	ds_read_b128 v[200:203], v154 offset:4096
	ds_read_b128 v[204:207], v154 offset:5120
	ds_read_b128 v[208:211], v154 offset:6144
	ds_read_b128 v[212:215], v154 offset:7168
	global_load_lds_dwordx4 v[216:217], off
	v_lshl_add_u64 v[216:217], s[44:45], 0, v[138:139]
	s_add_i32 m0, s43, 0xe000
	s_nop 0
	global_load_lds_dwordx4 v[216:217], off
	s_waitcnt vmcnt(8)
	s_waitcnt lgkmcnt(0)
	s_setprio 1
	s_barrier
	v_mfma_f32_16x16x32_bf16 v[126:129], v[146:149], v[184:187], v[126:129]
	v_mfma_f32_16x16x32_bf16 v[122:125], v[160:163], v[184:187], v[122:125]
	v_mfma_f32_16x16x32_bf16 v[110:113], v[146:149], v[192:195], v[110:113]
	v_mfma_f32_16x16x32_bf16 v[106:109], v[160:163], v[192:195], v[106:109]
	v_mfma_f32_16x16x32_bf16 v[94:97], v[146:149], v[200:203], v[94:97]
	v_mfma_f32_16x16x32_bf16 v[90:93], v[160:163], v[200:203], v[90:93]
	v_mfma_f32_16x16x32_bf16 v[78:81], v[146:149], v[208:211], v[78:81]
	v_mfma_f32_16x16x32_bf16 v[74:77], v[160:163], v[208:211], v[74:77]
	v_mfma_f32_16x16x32_bf16 v[126:129], v[156:159], v[188:191], v[126:129]
	v_mfma_f32_16x16x32_bf16 v[122:125], v[164:167], v[188:191], v[122:125]
	v_mfma_f32_16x16x32_bf16 v[110:113], v[156:159], v[196:199], v[110:113]
	v_mfma_f32_16x16x32_bf16 v[106:109], v[164:167], v[196:199], v[106:109]
	v_mfma_f32_16x16x32_bf16 v[94:97], v[156:159], v[204:207], v[94:97]
	v_mfma_f32_16x16x32_bf16 v[90:93], v[164:167], v[204:207], v[90:93]
	v_mfma_f32_16x16x32_bf16 v[78:81], v[156:159], v[212:215], v[78:81]
	v_mfma_f32_16x16x32_bf16 v[74:77], v[164:167], v[212:215], v[74:77]
	v_mfma_f32_16x16x32_bf16 v[118:121], v[168:171], v[184:187], v[118:121]
	v_mfma_f32_16x16x32_bf16 v[114:117], v[176:179], v[184:187], v[114:117]
	v_mfma_f32_16x16x32_bf16 v[102:105], v[168:171], v[192:195], v[102:105]
	v_mfma_f32_16x16x32_bf16 v[98:101], v[176:179], v[192:195], v[98:101]
	v_mfma_f32_16x16x32_bf16 v[86:89], v[168:171], v[200:203], v[86:89]
	v_mfma_f32_16x16x32_bf16 v[82:85], v[176:179], v[200:203], v[82:85]
	v_mfma_f32_16x16x32_bf16 v[70:73], v[168:171], v[208:211], v[70:73]
	v_mfma_f32_16x16x32_bf16 v[66:69], v[176:179], v[208:211], v[66:69]
	v_mfma_f32_16x16x32_bf16 v[118:121], v[172:175], v[188:191], v[118:121]
	v_mfma_f32_16x16x32_bf16 v[114:117], v[180:183], v[188:191], v[114:117]
	v_mfma_f32_16x16x32_bf16 v[102:105], v[172:175], v[196:199], v[102:105]
	v_mfma_f32_16x16x32_bf16 v[98:101], v[180:183], v[196:199], v[98:101]
	v_mfma_f32_16x16x32_bf16 v[86:89], v[172:175], v[204:207], v[86:89]
	v_mfma_f32_16x16x32_bf16 v[82:85], v[180:183], v[204:207], v[82:85]
	v_mfma_f32_16x16x32_bf16 v[70:73], v[172:175], v[212:215], v[70:73]
	v_mfma_f32_16x16x32_bf16 v[66:69], v[180:183], v[212:215], v[66:69]
	s_barrier
	s_setprio 0
	s_add_i32 s74, s61, s34
	v_lshl_add_u64 v[216:217], s[46:47], 0, v[134:135]
	s_mov_b32 m0, s74
	ds_read_b128 v[184:187], v154 offset:16384
	ds_read_b128 v[188:191], v154 offset:17408
	ds_read_b128 v[192:195], v154 offset:18432
	ds_read_b128 v[196:199], v154 offset:19456
	ds_read_b128 v[200:203], v154 offset:20480
	ds_read_b128 v[204:207], v154 offset:21504
	ds_read_b128 v[208:211], v154 offset:22528
	ds_read_b128 v[212:215], v154 offset:23552
	global_load_lds_dwordx4 v[216:217], off
	s_add_i32 m0, s74, 0x2000
	s_add_u32 s74, s46, 0x80000
	v_lshl_add_u64 v[218:219], s[46:47], 0, v[130:131]
	s_addc_u32 s75, s47, 0
	s_add_i32 s76, s62, s34
	global_load_lds_dwordx4 v[218:219], off
	v_lshl_add_u64 v[220:221], s[74:75], 0, v[134:135]
	s_mov_b32 m0, s76
	v_lshl_add_u64 v[222:223], s[48:49], 0, v[132:133]
	global_load_lds_dwordx4 v[220:221], off
	v_lshl_add_u64 v[220:221], s[74:75], 0, v[130:131]
	s_add_i32 m0, s76, 0x2000
	s_nop 0
	global_load_lds_dwordx4 v[220:221], off
	v_lshl_add_u64 v[220:221], s[48:49], 0, v[136:137]
	s_mov_b32 m0, s43
	s_nop 0
	global_load_lds_dwordx4 v[220:221], off
	s_mov_b32 m0, s50
	s_nop 0
	global_load_lds_dwordx4 v[222:223], off
	s_waitcnt vmcnt(8)
	s_waitcnt lgkmcnt(0)
	s_setprio 1
	s_barrier
	v_mfma_f32_16x16x32_bf16 v[62:65], v[146:149], v[184:187], v[62:65]
	v_mfma_f32_16x16x32_bf16 v[58:61], v[160:163], v[184:187], v[58:61]
	v_mfma_f32_16x16x32_bf16 v[46:49], v[146:149], v[192:195], v[46:49]
	v_mfma_f32_16x16x32_bf16 v[42:45], v[160:163], v[192:195], v[42:45]
	v_mfma_f32_16x16x32_bf16 v[30:33], v[146:149], v[200:203], v[30:33]
	v_mfma_f32_16x16x32_bf16 v[26:29], v[160:163], v[200:203], v[26:29]
	v_mfma_f32_16x16x32_bf16 v[14:17], v[146:149], v[208:211], v[14:17]
	v_mfma_f32_16x16x32_bf16 v[10:13], v[160:163], v[208:211], v[10:13]
	v_mfma_f32_16x16x32_bf16 v[62:65], v[156:159], v[188:191], v[62:65]
	v_mfma_f32_16x16x32_bf16 v[58:61], v[164:167], v[188:191], v[58:61]
	v_mfma_f32_16x16x32_bf16 v[46:49], v[156:159], v[196:199], v[46:49]
	v_mfma_f32_16x16x32_bf16 v[42:45], v[164:167], v[196:199], v[42:45]
	v_mfma_f32_16x16x32_bf16 v[30:33], v[156:159], v[204:207], v[30:33]
	v_mfma_f32_16x16x32_bf16 v[26:29], v[164:167], v[204:207], v[26:29]
	v_mfma_f32_16x16x32_bf16 v[14:17], v[156:159], v[212:215], v[14:17]
	v_mfma_f32_16x16x32_bf16 v[10:13], v[164:167], v[212:215], v[10:13]
	v_mfma_f32_16x16x32_bf16 v[54:57], v[168:171], v[184:187], v[54:57]
	v_mfma_f32_16x16x32_bf16 v[50:53], v[176:179], v[184:187], v[50:53]
	v_mfma_f32_16x16x32_bf16 v[38:41], v[168:171], v[192:195], v[38:41]
	v_mfma_f32_16x16x32_bf16 v[34:37], v[176:179], v[192:195], v[34:37]
	v_mfma_f32_16x16x32_bf16 v[22:25], v[168:171], v[200:203], v[22:25]
	v_mfma_f32_16x16x32_bf16 v[18:21], v[176:179], v[200:203], v[18:21]
	v_mfma_f32_16x16x32_bf16 v[6:9], v[168:171], v[208:211], v[6:9]
	v_mfma_f32_16x16x32_bf16 v[2:5], v[176:179], v[208:211], v[2:5]
	v_mfma_f32_16x16x32_bf16 v[54:57], v[172:175], v[188:191], v[54:57]
	v_mfma_f32_16x16x32_bf16 v[50:53], v[180:183], v[188:191], v[50:53]
	v_mfma_f32_16x16x32_bf16 v[38:41], v[172:175], v[196:199], v[38:41]
	v_mfma_f32_16x16x32_bf16 v[34:37], v[180:183], v[196:199], v[34:37]
	v_mfma_f32_16x16x32_bf16 v[22:25], v[172:175], v[204:207], v[22:25]
	v_mfma_f32_16x16x32_bf16 v[18:21], v[180:183], v[204:207], v[18:21]
	v_mfma_f32_16x16x32_bf16 v[6:9], v[172:175], v[212:215], v[6:9]
	v_mfma_f32_16x16x32_bf16 v[2:5], v[180:183], v[212:215], v[2:5]
	s_barrier
	s_setprio 0
	s_add_i32 s74, 0, 0x18000
	v_add_u32_e32 v155, s74, v151
	s_add_i32 s75, 0, 0x1c000
	ds_read_b128 v[146:149], v155
	ds_read_b128 v[156:159], v155 offset:1024
	ds_read_b128 v[160:163], v155 offset:2048
	ds_read_b128 v[164:167], v155 offset:3072
	v_add_u32_e32 v155, s75, v151
	ds_read_b128 v[168:171], v155
	ds_read_b128 v[172:175], v155 offset:1024
	ds_read_b128 v[176:179], v155 offset:2048
	ds_read_b128 v[180:183], v155 offset:3072
	s_add_u32 s48, s48, 0x80000
	s_addc_u32 s49, s49, 0
	s_mov_b32 m0, s51
	v_lshl_add_u64 v[224:225], s[48:49], 0, v[136:137]
	ds_read_b128 v[184:187], v154 offset:32768
	ds_read_b128 v[188:191], v154 offset:33792
	ds_read_b128 v[192:195], v154 offset:34816
	ds_read_b128 v[196:199], v154 offset:35840
	ds_read_b128 v[200:203], v154 offset:36864
	ds_read_b128 v[204:207], v154 offset:37888
	ds_read_b128 v[208:211], v154 offset:38912
	ds_read_b128 v[212:215], v154 offset:39936
	global_load_lds_dwordx4 v[224:225], off
	v_lshl_add_u64 v[224:225], s[48:49], 0, v[132:133]
	s_mov_b32 m0, s52
	s_nop 0
	global_load_lds_dwordx4 v[224:225], off
	s_waitcnt vmcnt(8)
	s_waitcnt lgkmcnt(0)
	s_setprio 1
	s_barrier
	v_mfma_f32_16x16x32_bf16 v[126:129], v[146:149], v[184:187], v[126:129]
	v_mfma_f32_16x16x32_bf16 v[122:125], v[160:163], v[184:187], v[122:125]
	v_mfma_f32_16x16x32_bf16 v[110:113], v[146:149], v[192:195], v[110:113]
	v_mfma_f32_16x16x32_bf16 v[106:109], v[160:163], v[192:195], v[106:109]
	v_mfma_f32_16x16x32_bf16 v[94:97], v[146:149], v[200:203], v[94:97]
	v_mfma_f32_16x16x32_bf16 v[90:93], v[160:163], v[200:203], v[90:93]
	v_mfma_f32_16x16x32_bf16 v[78:81], v[146:149], v[208:211], v[78:81]
	v_mfma_f32_16x16x32_bf16 v[74:77], v[160:163], v[208:211], v[74:77]
	v_mfma_f32_16x16x32_bf16 v[126:129], v[156:159], v[188:191], v[126:129]
	v_mfma_f32_16x16x32_bf16 v[122:125], v[164:167], v[188:191], v[122:125]
	v_mfma_f32_16x16x32_bf16 v[110:113], v[156:159], v[196:199], v[110:113]
	v_mfma_f32_16x16x32_bf16 v[106:109], v[164:167], v[196:199], v[106:109]
	v_mfma_f32_16x16x32_bf16 v[94:97], v[156:159], v[204:207], v[94:97]
	v_mfma_f32_16x16x32_bf16 v[90:93], v[164:167], v[204:207], v[90:93]
	v_mfma_f32_16x16x32_bf16 v[78:81], v[156:159], v[212:215], v[78:81]
	v_mfma_f32_16x16x32_bf16 v[74:77], v[164:167], v[212:215], v[74:77]
	v_mfma_f32_16x16x32_bf16 v[118:121], v[168:171], v[184:187], v[118:121]
	v_mfma_f32_16x16x32_bf16 v[114:117], v[176:179], v[184:187], v[114:117]
	v_mfma_f32_16x16x32_bf16 v[102:105], v[168:171], v[192:195], v[102:105]
	v_mfma_f32_16x16x32_bf16 v[98:101], v[176:179], v[192:195], v[98:101]
	v_mfma_f32_16x16x32_bf16 v[86:89], v[168:171], v[200:203], v[86:89]
	v_mfma_f32_16x16x32_bf16 v[82:85], v[176:179], v[200:203], v[82:85]
	v_mfma_f32_16x16x32_bf16 v[70:73], v[168:171], v[208:211], v[70:73]
	v_mfma_f32_16x16x32_bf16 v[66:69], v[176:179], v[208:211], v[66:69]
	v_mfma_f32_16x16x32_bf16 v[118:121], v[172:175], v[188:191], v[118:121]
	v_mfma_f32_16x16x32_bf16 v[114:117], v[180:183], v[188:191], v[114:117]
	v_mfma_f32_16x16x32_bf16 v[102:105], v[172:175], v[196:199], v[102:105]
	v_mfma_f32_16x16x32_bf16 v[98:101], v[180:183], v[196:199], v[98:101]
	v_mfma_f32_16x16x32_bf16 v[86:89], v[172:175], v[204:207], v[86:89]
	v_mfma_f32_16x16x32_bf16 v[82:85], v[180:183], v[204:207], v[82:85]
	v_mfma_f32_16x16x32_bf16 v[70:73], v[172:175], v[212:215], v[70:73]
	v_mfma_f32_16x16x32_bf16 v[66:69], v[180:183], v[212:215], v[66:69]
	s_barrier
	s_setprio 0
	s_add_i32 s48, s74, s34
	v_lshl_add_u64 v[216:217], v[216:217], 0, s[12:13]
	s_mov_b32 m0, s48
	ds_read_b128 v[184:187], v154 offset:49152
	ds_read_b128 v[188:191], v154 offset:50176
	ds_read_b128 v[192:195], v154 offset:51200
	ds_read_b128 v[196:199], v154 offset:52224
	ds_read_b128 v[200:203], v154 offset:53248
	ds_read_b128 v[204:207], v154 offset:54272
	ds_read_b128 v[208:211], v154 offset:55296
	ds_read_b128 v[212:215], v154 offset:56320
	global_load_lds_dwordx4 v[216:217], off
	s_add_i32 m0, s48, 0x2000
	s_add_u32 s46, s46, 0x80080
	v_lshl_add_u64 v[216:217], v[218:219], 0, s[12:13]
	s_addc_u32 s47, s47, 0
	s_add_i32 s48, s75, s34
	global_load_lds_dwordx4 v[216:217], off
	v_lshl_add_u64 v[216:217], s[46:47], 0, v[134:135]
	s_mov_b32 m0, s48
	s_nop 0
	global_load_lds_dwordx4 v[216:217], off
	v_lshl_add_u64 v[216:217], s[46:47], 0, v[130:131]
	s_add_i32 m0, s48, 0x2000
	s_nop 0
	global_load_lds_dwordx4 v[216:217], off
	v_lshl_add_u64 v[216:217], v[220:221], 0, s[12:13]
	s_mov_b32 m0, s56
	s_nop 0
	global_load_lds_dwordx4 v[216:217], off
	v_lshl_add_u64 v[216:217], v[222:223], 0, s[12:13]
	s_mov_b32 m0, s57
	s_nop 0
	global_load_lds_dwordx4 v[216:217], off
	s_waitcnt vmcnt(8)
	s_waitcnt lgkmcnt(0)
	s_setprio 1
	s_barrier
	v_mfma_f32_16x16x32_bf16 v[62:65], v[146:149], v[184:187], v[62:65]
	v_mfma_f32_16x16x32_bf16 v[58:61], v[160:163], v[184:187], v[58:61]
	v_mfma_f32_16x16x32_bf16 v[46:49], v[146:149], v[192:195], v[46:49]
	v_mfma_f32_16x16x32_bf16 v[42:45], v[160:163], v[192:195], v[42:45]
	v_mfma_f32_16x16x32_bf16 v[30:33], v[146:149], v[200:203], v[30:33]
	v_mfma_f32_16x16x32_bf16 v[26:29], v[160:163], v[200:203], v[26:29]
	v_mfma_f32_16x16x32_bf16 v[14:17], v[146:149], v[208:211], v[14:17]
	v_mfma_f32_16x16x32_bf16 v[10:13], v[160:163], v[208:211], v[10:13]
	v_mfma_f32_16x16x32_bf16 v[62:65], v[156:159], v[188:191], v[62:65]
	v_mfma_f32_16x16x32_bf16 v[58:61], v[164:167], v[188:191], v[58:61]
	v_mfma_f32_16x16x32_bf16 v[46:49], v[156:159], v[196:199], v[46:49]
	v_mfma_f32_16x16x32_bf16 v[42:45], v[164:167], v[196:199], v[42:45]
	v_mfma_f32_16x16x32_bf16 v[30:33], v[156:159], v[204:207], v[30:33]
	v_mfma_f32_16x16x32_bf16 v[26:29], v[164:167], v[204:207], v[26:29]
	v_mfma_f32_16x16x32_bf16 v[14:17], v[156:159], v[212:215], v[14:17]
	v_mfma_f32_16x16x32_bf16 v[10:13], v[164:167], v[212:215], v[10:13]
	v_mfma_f32_16x16x32_bf16 v[54:57], v[168:171], v[184:187], v[54:57]
	v_mfma_f32_16x16x32_bf16 v[50:53], v[176:179], v[184:187], v[50:53]
	v_mfma_f32_16x16x32_bf16 v[38:41], v[168:171], v[192:195], v[38:41]
	v_mfma_f32_16x16x32_bf16 v[34:37], v[176:179], v[192:195], v[34:37]
	v_mfma_f32_16x16x32_bf16 v[22:25], v[168:171], v[200:203], v[22:25]
	v_mfma_f32_16x16x32_bf16 v[18:21], v[176:179], v[200:203], v[18:21]
	v_mfma_f32_16x16x32_bf16 v[6:9], v[168:171], v[208:211], v[6:9]
	v_mfma_f32_16x16x32_bf16 v[2:5], v[176:179], v[208:211], v[2:5]
	v_mfma_f32_16x16x32_bf16 v[54:57], v[172:175], v[188:191], v[54:57]
	v_mfma_f32_16x16x32_bf16 v[50:53], v[180:183], v[188:191], v[50:53]
	v_mfma_f32_16x16x32_bf16 v[38:41], v[172:175], v[196:199], v[38:41]
	v_mfma_f32_16x16x32_bf16 v[34:37], v[180:183], v[196:199], v[34:37]
	v_mfma_f32_16x16x32_bf16 v[22:25], v[172:175], v[204:207], v[22:25]
	v_mfma_f32_16x16x32_bf16 v[18:21], v[180:183], v[204:207], v[18:21]
	v_mfma_f32_16x16x32_bf16 v[6:9], v[172:175], v[212:215], v[6:9]
	v_mfma_f32_16x16x32_bf16 v[2:5], v[180:183], v[212:215], v[2:5]
	s_barrier
	s_setprio 0
	s_add_i32 s73, s73, 2
	s_add_u32 s71, s71, 0x100
	s_addc_u32 s72, s72, 0
	s_add_u32 s44, s44, 0x100
	s_addc_u32 s45, s45, 0
	s_cmp_gt_u32 s73, 29
	s_cbranch_scc0 .LBB0_1525
	s_and_b64 vcc, exec, s[14:15]
	s_cbranch_vccz .LBB0_1528
	s_barrier

.LBB0_1681:
	ds_read_b128 v[86:89], v220
	ds_read_b128 v[90:93], v220 offset:1024
	ds_read_b128 v[114:117], v220 offset:2048
	ds_read_b128 v[118:121], v220 offset:3072
	ds_read_b128 v[146:149], v221
	ds_read_b128 v[150:153], v221 offset:1024
	ds_read_b128 v[154:157], v221 offset:2048
	ds_read_b128 v[158:161], v221 offset:3072
	s_add_u32 s10, s8, 0xfffe0080
	s_addc_u32 s11, s9, -1
	s_cmp_eq_u32 s63, 4
	s_cselect_b32 s13, s7, s11
	s_cselect_b32 s12, s14, s10
	s_cselect_b32 s11, s15, s41
	s_cselect_b32 s10, s18, s39
	v_lshl_add_u64 v[208:209], s[8:9], 0, v[180:181]
	s_add_i32 m0, s47, 0xc000
	ds_read_b128 v[162:165], v222
	ds_read_b128 v[166:169], v222 offset:1024
	ds_read_b128 v[184:187], v222 offset:2048
	ds_read_b128 v[188:191], v222 offset:3072
	ds_read_b128 v[192:195], v222 offset:4096
	ds_read_b128 v[196:199], v222 offset:5120
	ds_read_b128 v[200:203], v222 offset:6144
	ds_read_b128 v[204:207], v222 offset:7168
	global_load_lds_dwordx4 v[208:209], off
	v_lshl_add_u64 v[208:209], s[8:9], 0, v[178:179]
	s_add_i32 m0, s47, 0xe000
	s_nop 0
	global_load_lds_dwordx4 v[208:209], off
	s_waitcnt vmcnt(8)
	s_waitcnt lgkmcnt(0)
	s_setprio 1
	s_barrier
	v_mfma_f32_16x16x32_bf16 v[142:145], v[86:89], v[162:165], v[142:145]
	v_mfma_f32_16x16x32_bf16 v[138:141], v[114:117], v[162:165], v[138:141]
	v_mfma_f32_16x16x32_bf16 v[126:129], v[86:89], v[184:187], v[126:129]
	v_mfma_f32_16x16x32_bf16 v[122:125], v[114:117], v[184:187], v[122:125]
	v_mfma_f32_16x16x32_bf16 v[102:105], v[86:89], v[192:195], v[102:105]
	v_mfma_f32_16x16x32_bf16 v[98:101], v[114:117], v[192:195], v[98:101]
	v_mfma_f32_16x16x32_bf16 v[78:81], v[86:89], v[200:203], v[78:81]
	v_mfma_f32_16x16x32_bf16 v[74:77], v[114:117], v[200:203], v[74:77]
	v_mfma_f32_16x16x32_bf16 v[142:145], v[90:93], v[166:169], v[142:145]
	v_mfma_f32_16x16x32_bf16 v[138:141], v[118:121], v[166:169], v[138:141]
	v_mfma_f32_16x16x32_bf16 v[126:129], v[90:93], v[188:191], v[126:129]
	v_mfma_f32_16x16x32_bf16 v[122:125], v[118:121], v[188:191], v[122:125]
	v_mfma_f32_16x16x32_bf16 v[102:105], v[90:93], v[196:199], v[102:105]
	v_mfma_f32_16x16x32_bf16 v[98:101], v[118:121], v[196:199], v[98:101]
	v_mfma_f32_16x16x32_bf16 v[78:81], v[90:93], v[204:207], v[78:81]
	v_mfma_f32_16x16x32_bf16 v[74:77], v[118:121], v[204:207], v[74:77]
	v_mfma_f32_16x16x32_bf16 v[134:137], v[146:149], v[162:165], v[134:137]
	v_mfma_f32_16x16x32_bf16 v[130:133], v[154:157], v[162:165], v[130:133]
	v_mfma_f32_16x16x32_bf16 v[110:113], v[146:149], v[184:187], v[110:113]
	v_mfma_f32_16x16x32_bf16 v[106:109], v[154:157], v[184:187], v[106:109]
	v_mfma_f32_16x16x32_bf16 v[94:97], v[146:149], v[192:195], v[94:97]
	v_mfma_f32_16x16x32_bf16 v[82:85], v[154:157], v[192:195], v[82:85]
	v_mfma_f32_16x16x32_bf16 v[70:73], v[146:149], v[200:203], v[70:73]
	v_mfma_f32_16x16x32_bf16 v[66:69], v[154:157], v[200:203], v[66:69]
	v_mfma_f32_16x16x32_bf16 v[134:137], v[150:153], v[166:169], v[134:137]
	v_mfma_f32_16x16x32_bf16 v[130:133], v[158:161], v[166:169], v[130:133]
	v_mfma_f32_16x16x32_bf16 v[110:113], v[150:153], v[188:191], v[110:113]
	v_mfma_f32_16x16x32_bf16 v[106:109], v[158:161], v[188:191], v[106:109]
	v_mfma_f32_16x16x32_bf16 v[94:97], v[150:153], v[196:199], v[94:97]
	v_mfma_f32_16x16x32_bf16 v[82:85], v[158:161], v[196:199], v[82:85]
	v_mfma_f32_16x16x32_bf16 v[70:73], v[150:153], v[204:207], v[70:73]
	v_mfma_f32_16x16x32_bf16 v[66:69], v[158:161], v[204:207], v[66:69]
	s_barrier
	s_setprio 0
	s_add_i32 s64, s60, s49
	v_lshl_add_u64 v[208:209], s[10:11], 0, v[172:173]
	s_mov_b32 m0, s64
	ds_read_b128 v[162:165], v222 offset:16384
	ds_read_b128 v[166:169], v222 offset:17408
	ds_read_b128 v[184:187], v222 offset:18432
	ds_read_b128 v[188:191], v222 offset:19456
	ds_read_b128 v[192:195], v222 offset:20480
	ds_read_b128 v[196:199], v222 offset:21504
	ds_read_b128 v[200:203], v222 offset:22528
	ds_read_b128 v[204:207], v222 offset:23552
	global_load_lds_dwordx4 v[208:209], off
	s_add_i32 m0, s64, 0x2000
	s_add_u32 s64, s10, 0x20000
	v_lshl_add_u64 v[210:211], s[10:11], 0, v[176:177]
	s_addc_u32 s65, s11, 0
	s_add_i32 s66, s61, s49
	global_load_lds_dwordx4 v[210:211], off
	v_lshl_add_u64 v[212:213], s[64:65], 0, v[172:173]
	s_mov_b32 m0, s66
	v_lshl_add_u64 v[214:215], s[12:13], 0, v[174:175]
	global_load_lds_dwordx4 v[212:213], off
	v_lshl_add_u64 v[212:213], s[64:65], 0, v[176:177]
	s_add_i32 m0, s66, 0x2000
	s_nop 0
	global_load_lds_dwordx4 v[212:213], off
	v_lshl_add_u64 v[212:213], s[12:13], 0, v[170:171]
	s_mov_b32 m0, s47
	s_nop 0
	global_load_lds_dwordx4 v[212:213], off
	s_mov_b32 m0, s50
	s_nop 0
	global_load_lds_dwordx4 v[214:215], off
	s_waitcnt vmcnt(8)
	s_waitcnt lgkmcnt(0)
	s_setprio 1
	s_barrier
	v_mfma_f32_16x16x32_bf16 v[62:65], v[86:89], v[162:165], v[62:65]
	v_mfma_f32_16x16x32_bf16 v[58:61], v[114:117], v[162:165], v[58:61]
	v_mfma_f32_16x16x32_bf16 v[46:49], v[86:89], v[184:187], v[46:49]
	v_mfma_f32_16x16x32_bf16 v[42:45], v[114:117], v[184:187], v[42:45]
	v_mfma_f32_16x16x32_bf16 v[30:33], v[86:89], v[192:195], v[30:33]
	v_mfma_f32_16x16x32_bf16 v[26:29], v[114:117], v[192:195], v[26:29]
	v_mfma_f32_16x16x32_bf16 v[14:17], v[86:89], v[200:203], v[14:17]
	v_mfma_f32_16x16x32_bf16 v[10:13], v[114:117], v[200:203], v[10:13]
	v_mfma_f32_16x16x32_bf16 v[62:65], v[90:93], v[166:169], v[62:65]
	v_mfma_f32_16x16x32_bf16 v[58:61], v[118:121], v[166:169], v[58:61]
	v_mfma_f32_16x16x32_bf16 v[46:49], v[90:93], v[188:191], v[46:49]
	v_mfma_f32_16x16x32_bf16 v[42:45], v[118:121], v[188:191], v[42:45]
	v_mfma_f32_16x16x32_bf16 v[30:33], v[90:93], v[196:199], v[30:33]
	v_mfma_f32_16x16x32_bf16 v[26:29], v[118:121], v[196:199], v[26:29]
	v_mfma_f32_16x16x32_bf16 v[14:17], v[90:93], v[204:207], v[14:17]
	v_mfma_f32_16x16x32_bf16 v[10:13], v[118:121], v[204:207], v[10:13]
	v_mfma_f32_16x16x32_bf16 v[54:57], v[146:149], v[162:165], v[54:57]
	v_mfma_f32_16x16x32_bf16 v[50:53], v[154:157], v[162:165], v[50:53]
	v_mfma_f32_16x16x32_bf16 v[38:41], v[146:149], v[184:187], v[38:41]
	v_mfma_f32_16x16x32_bf16 v[34:37], v[154:157], v[184:187], v[34:37]
	v_mfma_f32_16x16x32_bf16 v[22:25], v[146:149], v[192:195], v[22:25]
	v_mfma_f32_16x16x32_bf16 v[18:21], v[154:157], v[192:195], v[18:21]
	v_mfma_f32_16x16x32_bf16 v[6:9], v[146:149], v[200:203], v[6:9]
	v_mfma_f32_16x16x32_bf16 v[2:5], v[154:157], v[200:203], v[2:5]
	v_mfma_f32_16x16x32_bf16 v[54:57], v[150:153], v[166:169], v[54:57]
	v_mfma_f32_16x16x32_bf16 v[50:53], v[158:161], v[166:169], v[50:53]
	v_mfma_f32_16x16x32_bf16 v[38:41], v[150:153], v[188:191], v[38:41]
	v_mfma_f32_16x16x32_bf16 v[34:37], v[158:161], v[188:191], v[34:37]
	v_mfma_f32_16x16x32_bf16 v[22:25], v[150:153], v[196:199], v[22:25]
	v_mfma_f32_16x16x32_bf16 v[18:21], v[158:161], v[196:199], v[18:21]
	v_mfma_f32_16x16x32_bf16 v[6:9], v[150:153], v[204:207], v[6:9]
	v_mfma_f32_16x16x32_bf16 v[2:5], v[158:161], v[204:207], v[2:5]
	s_barrier
	s_setprio 0
	s_add_i32 s64, 0, 0x18000
	s_add_i32 s65, 0, 0x1c000
	v_add_u32_e32 v118, s64, v219
	v_add_u32_e32 v158, s65, v219
	ds_read_b128 v[86:89], v118
	ds_read_b128 v[90:93], v118 offset:1024
	ds_read_b128 v[114:117], v118 offset:2048
	ds_read_b128 v[118:121], v118 offset:3072
	ds_read_b128 v[146:149], v158
	ds_read_b128 v[150:153], v158 offset:1024
	ds_read_b128 v[154:157], v158 offset:2048
	ds_read_b128 v[158:161], v158 offset:3072
	s_add_u32 s12, s12, 0x20000
	s_addc_u32 s13, s13, 0
	s_mov_b32 m0, s51
	v_lshl_add_u64 v[216:217], s[12:13], 0, v[170:171]
	ds_read_b128 v[162:165], v222 offset:32768
	ds_read_b128 v[166:169], v222 offset:33792
	ds_read_b128 v[184:187], v222 offset:34816
	ds_read_b128 v[188:191], v222 offset:35840
	ds_read_b128 v[192:195], v222 offset:36864
	ds_read_b128 v[196:199], v222 offset:37888
	ds_read_b128 v[200:203], v222 offset:38912
	ds_read_b128 v[204:207], v222 offset:39936
	global_load_lds_dwordx4 v[216:217], off
	v_lshl_add_u64 v[216:217], s[12:13], 0, v[174:175]
	s_mov_b32 m0, s52
	s_nop 0
	global_load_lds_dwordx4 v[216:217], off
	s_waitcnt vmcnt(8)
	s_waitcnt lgkmcnt(0)
	s_setprio 1
	s_barrier
	v_mfma_f32_16x16x32_bf16 v[142:145], v[86:89], v[162:165], v[142:145]
	v_mfma_f32_16x16x32_bf16 v[138:141], v[114:117], v[162:165], v[138:141]
	v_mfma_f32_16x16x32_bf16 v[126:129], v[86:89], v[184:187], v[126:129]
	v_mfma_f32_16x16x32_bf16 v[122:125], v[114:117], v[184:187], v[122:125]
	v_mfma_f32_16x16x32_bf16 v[102:105], v[86:89], v[192:195], v[102:105]
	v_mfma_f32_16x16x32_bf16 v[98:101], v[114:117], v[192:195], v[98:101]
	v_mfma_f32_16x16x32_bf16 v[78:81], v[86:89], v[200:203], v[78:81]
	v_mfma_f32_16x16x32_bf16 v[74:77], v[114:117], v[200:203], v[74:77]
	v_mfma_f32_16x16x32_bf16 v[142:145], v[90:93], v[166:169], v[142:145]
	v_mfma_f32_16x16x32_bf16 v[138:141], v[118:121], v[166:169], v[138:141]
	v_mfma_f32_16x16x32_bf16 v[126:129], v[90:93], v[188:191], v[126:129]
	v_mfma_f32_16x16x32_bf16 v[122:125], v[118:121], v[188:191], v[122:125]
	v_mfma_f32_16x16x32_bf16 v[102:105], v[90:93], v[196:199], v[102:105]
	v_mfma_f32_16x16x32_bf16 v[98:101], v[118:121], v[196:199], v[98:101]
	v_mfma_f32_16x16x32_bf16 v[78:81], v[90:93], v[204:207], v[78:81]
	v_mfma_f32_16x16x32_bf16 v[74:77], v[118:121], v[204:207], v[74:77]
	v_mfma_f32_16x16x32_bf16 v[134:137], v[146:149], v[162:165], v[134:137]
	v_mfma_f32_16x16x32_bf16 v[130:133], v[154:157], v[162:165], v[130:133]
	v_mfma_f32_16x16x32_bf16 v[110:113], v[146:149], v[184:187], v[110:113]
	v_mfma_f32_16x16x32_bf16 v[106:109], v[154:157], v[184:187], v[106:109]
	v_mfma_f32_16x16x32_bf16 v[94:97], v[146:149], v[192:195], v[94:97]
	v_mfma_f32_16x16x32_bf16 v[82:85], v[154:157], v[192:195], v[82:85]
	v_mfma_f32_16x16x32_bf16 v[70:73], v[146:149], v[200:203], v[70:73]
	v_mfma_f32_16x16x32_bf16 v[66:69], v[154:157], v[200:203], v[66:69]
	v_mfma_f32_16x16x32_bf16 v[134:137], v[150:153], v[166:169], v[134:137]
	v_mfma_f32_16x16x32_bf16 v[130:133], v[158:161], v[166:169], v[130:133]
	v_mfma_f32_16x16x32_bf16 v[110:113], v[150:153], v[188:191], v[110:113]
	v_mfma_f32_16x16x32_bf16 v[106:109], v[158:161], v[188:191], v[106:109]
	v_mfma_f32_16x16x32_bf16 v[94:97], v[150:153], v[196:199], v[94:97]
	v_mfma_f32_16x16x32_bf16 v[82:85], v[158:161], v[196:199], v[82:85]
	v_mfma_f32_16x16x32_bf16 v[70:73], v[150:153], v[204:207], v[70:73]
	v_mfma_f32_16x16x32_bf16 v[66:69], v[158:161], v[204:207], v[66:69]
	s_barrier
	s_setprio 0
	s_add_i32 s12, s64, s49
	v_lshl_add_u64 v[208:209], v[208:209], 0, s[30:31]
	s_mov_b32 m0, s12
	ds_read_b128 v[162:165], v222 offset:49152
	ds_read_b128 v[166:169], v222 offset:50176
	ds_read_b128 v[184:187], v222 offset:51200
	ds_read_b128 v[188:191], v222 offset:52224
	ds_read_b128 v[192:195], v222 offset:53248
	ds_read_b128 v[196:199], v222 offset:54272
	ds_read_b128 v[200:203], v222 offset:55296
	ds_read_b128 v[204:207], v222 offset:56320
	global_load_lds_dwordx4 v[208:209], off
	s_add_i32 m0, s12, 0x2000
	s_add_u32 s10, s10, 0x20080
	v_lshl_add_u64 v[208:209], v[210:211], 0, s[30:31]
	s_addc_u32 s11, s11, 0
	s_add_i32 s12, s65, s49
	global_load_lds_dwordx4 v[208:209], off
	v_lshl_add_u64 v[208:209], s[10:11], 0, v[172:173]
	s_mov_b32 m0, s12
	s_nop 0
	global_load_lds_dwordx4 v[208:209], off
	v_lshl_add_u64 v[208:209], s[10:11], 0, v[176:177]
	s_add_i32 m0, s12, 0x2000
	s_nop 0
	global_load_lds_dwordx4 v[208:209], off
	v_lshl_add_u64 v[208:209], v[212:213], 0, s[30:31]
	s_mov_b32 m0, s56
	s_nop 0
	global_load_lds_dwordx4 v[208:209], off
	v_lshl_add_u64 v[208:209], v[214:215], 0, s[30:31]
	s_mov_b32 m0, s57
	s_nop 0
	global_load_lds_dwordx4 v[208:209], off
	s_waitcnt vmcnt(8)
	s_waitcnt lgkmcnt(0)
	s_setprio 1
	s_barrier
	v_mfma_f32_16x16x32_bf16 v[62:65], v[86:89], v[162:165], v[62:65]
	v_mfma_f32_16x16x32_bf16 v[58:61], v[114:117], v[162:165], v[58:61]
	v_mfma_f32_16x16x32_bf16 v[46:49], v[86:89], v[184:187], v[46:49]
	v_mfma_f32_16x16x32_bf16 v[42:45], v[114:117], v[184:187], v[42:45]
	v_mfma_f32_16x16x32_bf16 v[30:33], v[86:89], v[192:195], v[30:33]
	v_mfma_f32_16x16x32_bf16 v[26:29], v[114:117], v[192:195], v[26:29]
	v_mfma_f32_16x16x32_bf16 v[14:17], v[86:89], v[200:203], v[14:17]
	v_mfma_f32_16x16x32_bf16 v[10:13], v[114:117], v[200:203], v[10:13]
	v_mfma_f32_16x16x32_bf16 v[62:65], v[90:93], v[166:169], v[62:65]
	v_mfma_f32_16x16x32_bf16 v[58:61], v[118:121], v[166:169], v[58:61]
	v_mfma_f32_16x16x32_bf16 v[46:49], v[90:93], v[188:191], v[46:49]
	v_mfma_f32_16x16x32_bf16 v[42:45], v[118:121], v[188:191], v[42:45]
	v_mfma_f32_16x16x32_bf16 v[30:33], v[90:93], v[196:199], v[30:33]
	v_mfma_f32_16x16x32_bf16 v[26:29], v[118:121], v[196:199], v[26:29]
	v_mfma_f32_16x16x32_bf16 v[14:17], v[90:93], v[204:207], v[14:17]
	v_mfma_f32_16x16x32_bf16 v[10:13], v[118:121], v[204:207], v[10:13]
	v_mfma_f32_16x16x32_bf16 v[54:57], v[146:149], v[162:165], v[54:57]
	v_mfma_f32_16x16x32_bf16 v[50:53], v[154:157], v[162:165], v[50:53]
	v_mfma_f32_16x16x32_bf16 v[38:41], v[146:149], v[184:187], v[38:41]
	v_mfma_f32_16x16x32_bf16 v[34:37], v[154:157], v[184:187], v[34:37]
	v_mfma_f32_16x16x32_bf16 v[22:25], v[146:149], v[192:195], v[22:25]
	v_mfma_f32_16x16x32_bf16 v[18:21], v[154:157], v[192:195], v[18:21]
	v_mfma_f32_16x16x32_bf16 v[6:9], v[146:149], v[200:203], v[6:9]
	v_mfma_f32_16x16x32_bf16 v[2:5], v[154:157], v[200:203], v[2:5]
	v_mfma_f32_16x16x32_bf16 v[54:57], v[150:153], v[166:169], v[54:57]
	v_mfma_f32_16x16x32_bf16 v[50:53], v[158:161], v[166:169], v[50:53]
	v_mfma_f32_16x16x32_bf16 v[38:41], v[150:153], v[188:191], v[38:41]
	v_mfma_f32_16x16x32_bf16 v[34:37], v[158:161], v[188:191], v[34:37]
	v_mfma_f32_16x16x32_bf16 v[22:25], v[150:153], v[196:199], v[22:25]
	v_mfma_f32_16x16x32_bf16 v[18:21], v[158:161], v[196:199], v[18:21]
	v_mfma_f32_16x16x32_bf16 v[6:9], v[150:153], v[204:207], v[6:9]
	v_mfma_f32_16x16x32_bf16 v[2:5], v[158:161], v[204:207], v[2:5]
	s_barrier
	s_setprio 0
	s_add_i32 s63, s63, 2
	s_add_u32 s39, s39, 0x100
	s_addc_u32 s41, s41, 0
	s_add_u32 s8, s8, 0x100
	s_addc_u32 s9, s9, 0
	s_cmp_gt_u32 s63, 5
	s_cbranch_scc0 .LBB0_1681
	s_and_b64 vcc, exec, s[36:37]
	s_cbranch_vccz .LBB0_1684
	s_barrier

.LBB0_1706:
	s_lshl_b32 s10, s10, 5
	s_add_i32 s25, 0, 0x18000
	s_lshl_b32 s9, s11, 6
	s_and_b32 s10, s10, 0x60
	s_lshl_b32 s24, s11, 13
	s_add_i32 s11, s25, s22
	s_mov_b64 s[18:19], 0x80
	s_lshl_b32 s23, s10, 7
	v_lshl_add_u64 v[32:33], v[18:19], 0, s[18:19]
	s_mov_b32 m0, s11
	s_add_i32 s13, s11, 0x2000
	s_add_i32 s12, s20, 0x8000
	s_add_i32 s14, s20, 0xa000
	s_waitcnt vmcnt(2)
	s_barrier
	global_load_lds_dwordx4 v[32:33], off
	v_lshl_add_u64 v[38:39], v[20:21], 0, s[18:19]
	s_mov_b32 m0, s13
	s_add_u32 s4, s4, 0x20080
	global_load_lds_dwordx4 v[38:39], off
	v_lshl_add_u64 v[30:31], v[12:13], 0, s[18:19]
	s_mov_b32 m0, s12
	s_addc_u32 s5, s5, 0
	s_add_i32 s26, 0, 0x1c000
	global_load_lds_dwordx4 v[30:31], off
	v_lshl_add_u64 v[40:41], v[14:15], 0, s[18:19]
	s_mov_b32 m0, s14
	s_add_i32 s18, s26, s22
	global_load_lds_dwordx4 v[40:41], off
	v_lshl_add_u64 v[240:241], s[4:5], 0, v[22:23]
	s_mov_b32 m0, s18
	s_add_i32 s19, s18, 0x2000
	global_load_lds_dwordx4 v[240:241], off
	v_lshl_add_u64 v[242:243], s[4:5], 0, v[24:25]
	s_mov_b32 m0, s19
	v_bfe_u32 v1, v26, 4, 2
	global_load_lds_dwordx4 v[242:243], off
	v_and_b32_e32 v130, 15, v26
	v_lshlrev_b32_e32 v22, 4, v1
	v_lshlrev_b32_e32 v23, 2, v26
	v_lshl_or_b32 v22, v130, 6, v22
	v_and_b32_e32 v23, 32, v23
	v_bitop3_b32 v24, v22, s23, v23 bitop3:0xde
	v_bitop3_b32 v22, v22, s24, v23 bitop3:0xde
	s_add_i32 s23, 0, 0x10000
	s_add_i32 s24, 0, 0x14000
	v_add_u32_e32 v42, s23, v24
	v_add_u32_e32 v58, s24, v24
	s_waitcnt vmcnt(6)
	s_barrier
	v_add_u32_e32 v131, 0, v22
	v_add_u32_e32 v204, s25, v24
	v_add_u32_e32 v220, s26, v24
	ds_read_b128 v[22:25], v42
	ds_read_b128 v[26:29], v42 offset:1024
	ds_read_b128 v[34:37], v42 offset:2048
	ds_read_b128 v[42:45], v42 offset:3072
	ds_read_b128 v[46:49], v58
	ds_read_b128 v[50:53], v58 offset:1024
	ds_read_b128 v[54:57], v58 offset:2048
	ds_read_b128 v[58:61], v58 offset:3072
	s_add_u32 s6, s6, 0x20080
	s_addc_u32 s7, s7, 0
	s_add_i32 s23, s23, s22
	s_add_i32 s22, s24, s22
	s_mov_b32 s4, 0x8000
	s_mov_b32 s5, 0xc000
	s_add_i32 m0, s20, 0xc000
	s_add_i32 s25, s20, 0xe000
	s_add_i32 s26, s23, 0x2000
	s_add_i32 s24, s22, 0x2000
	s_cmpk_gt_u32 s17, 0xff
	v_lshl_add_u64 v[6:7], s[6:7], 0, v[6:7]
	ds_read_b128 v[62:65], v131
	ds_read_b128 v[66:69], v131 offset:1024
	ds_read_b128 v[70:73], v131 offset:2048
	ds_read_b128 v[74:77], v131 offset:3072
	ds_read_b128 v[78:81], v131 offset:4096
	ds_read_b128 v[82:85], v131 offset:5120
	ds_read_b128 v[86:89], v131 offset:6144
	ds_read_b128 v[90:93], v131 offset:7168
	global_load_lds_dwordx4 v[6:7], off
	v_lshl_add_u64 v[6:7], s[6:7], 0, v[8:9]
	s_mov_b32 m0, s25
	s_nop 0
	global_load_lds_dwordx4 v[6:7], off
	s_waitcnt vmcnt(8)
	s_waitcnt lgkmcnt(0)
	s_setprio 1
	s_barrier
	v_mfma_f32_16x16x32_bf16 v[6:9], v[22:25], v[62:65], 0
	v_mfma_f32_16x16x32_bf16 v[94:97], v[34:37], v[62:65], 0
	v_mfma_f32_16x16x32_bf16 v[98:101], v[22:25], v[70:73], 0
	v_mfma_f32_16x16x32_bf16 v[102:105], v[34:37], v[70:73], 0
	v_mfma_f32_16x16x32_bf16 v[106:109], v[22:25], v[78:81], 0
	v_mfma_f32_16x16x32_bf16 v[110:113], v[34:37], v[78:81], 0
	v_mfma_f32_16x16x32_bf16 v[114:117], v[22:25], v[86:89], 0
	v_mfma_f32_16x16x32_bf16 v[118:121], v[34:37], v[86:89], 0
	v_mfma_f32_16x16x32_bf16 v[6:9], v[26:29], v[66:69], v[6:9]
	v_mfma_f32_16x16x32_bf16 v[94:97], v[42:45], v[66:69], v[94:97]
	v_mfma_f32_16x16x32_bf16 v[98:101], v[26:29], v[74:77], v[98:101]
	v_mfma_f32_16x16x32_bf16 v[102:105], v[42:45], v[74:77], v[102:105]
	v_mfma_f32_16x16x32_bf16 v[106:109], v[26:29], v[82:85], v[106:109]
	v_mfma_f32_16x16x32_bf16 v[110:113], v[42:45], v[82:85], v[110:113]
	v_mfma_f32_16x16x32_bf16 v[114:117], v[26:29], v[90:93], v[114:117]
	v_mfma_f32_16x16x32_bf16 v[118:121], v[42:45], v[90:93], v[118:121]
	v_mfma_f32_16x16x32_bf16 v[122:125], v[46:49], v[62:65], 0
	v_mfma_f32_16x16x32_bf16 v[62:65], v[54:57], v[62:65], 0
	v_mfma_f32_16x16x32_bf16 v[122:125], v[50:53], v[66:69], v[122:125]
	v_mfma_f32_16x16x32_bf16 v[62:65], v[58:61], v[66:69], v[62:65]
	v_mfma_f32_16x16x32_bf16 v[66:69], v[46:49], v[70:73], 0
	v_mfma_f32_16x16x32_bf16 v[70:73], v[54:57], v[70:73], 0
	v_mfma_f32_16x16x32_bf16 v[66:69], v[50:53], v[74:77], v[66:69]
	v_mfma_f32_16x16x32_bf16 v[70:73], v[58:61], v[74:77], v[70:73]
	v_mfma_f32_16x16x32_bf16 v[74:77], v[46:49], v[78:81], 0
	v_mfma_f32_16x16x32_bf16 v[78:81], v[54:57], v[78:81], 0
	v_mfma_f32_16x16x32_bf16 v[74:77], v[50:53], v[82:85], v[74:77]
	v_mfma_f32_16x16x32_bf16 v[78:81], v[58:61], v[82:85], v[78:81]
	v_mfma_f32_16x16x32_bf16 v[82:85], v[46:49], v[86:89], 0
	v_mfma_f32_16x16x32_bf16 v[86:89], v[54:57], v[86:89], 0
	v_mfma_f32_16x16x32_bf16 v[82:85], v[50:53], v[90:93], v[82:85]
	v_mfma_f32_16x16x32_bf16 v[86:89], v[58:61], v[90:93], v[86:89]
	s_barrier
	s_setprio 0
	s_mov_b32 m0, s23
	ds_read_b128 v[90:93], v131 offset:16384
	ds_read_b128 v[126:129], v131 offset:17408
	ds_read_b128 v[132:135], v131 offset:18432
	ds_read_b128 v[136:139], v131 offset:19456
	ds_read_b128 v[140:143], v131 offset:20480
	ds_read_b128 v[144:147], v131 offset:21504
	ds_read_b128 v[148:151], v131 offset:22528
	ds_read_b128 v[152:155], v131 offset:23552
	global_load_lds_dwordx4 v[18:19], off
	s_mov_b32 m0, s26
	s_nop 0
	global_load_lds_dwordx4 v[20:21], off
	s_mov_b32 m0, s22
	s_nop 0
	global_load_lds_dwordx4 v[16:17], off
	s_mov_b32 m0, s24
	s_nop 0
	global_load_lds_dwordx4 v[10:11], off
	s_mov_b32 m0, s20
	s_nop 0
	global_load_lds_dwordx4 v[12:13], off
	s_mov_b32 m0, s21
	s_nop 0
	global_load_lds_dwordx4 v[14:15], off
	s_waitcnt vmcnt(8)
	s_waitcnt lgkmcnt(0)
	s_setprio 1
	s_barrier
	v_mfma_f32_16x16x32_bf16 v[10:13], v[22:25], v[90:93], 0
	v_mfma_f32_16x16x32_bf16 v[156:159], v[26:29], v[126:129], v[10:13]
	v_mfma_f32_16x16x32_bf16 v[10:13], v[34:37], v[90:93], 0
	v_mfma_f32_16x16x32_bf16 v[160:163], v[42:45], v[126:129], v[10:13]
	v_mfma_f32_16x16x32_bf16 v[10:13], v[22:25], v[132:135], 0
	v_mfma_f32_16x16x32_bf16 v[164:167], v[26:29], v[136:139], v[10:13]
	v_mfma_f32_16x16x32_bf16 v[10:13], v[34:37], v[132:135], 0
	v_mfma_f32_16x16x32_bf16 v[168:171], v[42:45], v[136:139], v[10:13]
	v_mfma_f32_16x16x32_bf16 v[10:13], v[22:25], v[140:143], 0
	v_mfma_f32_16x16x32_bf16 v[172:175], v[26:29], v[144:147], v[10:13]
	v_mfma_f32_16x16x32_bf16 v[10:13], v[34:37], v[140:143], 0
	v_mfma_f32_16x16x32_bf16 v[176:179], v[42:45], v[144:147], v[10:13]
	v_mfma_f32_16x16x32_bf16 v[10:13], v[22:25], v[148:151], 0
	v_mfma_f32_16x16x32_bf16 v[180:183], v[26:29], v[152:155], v[10:13]
	v_mfma_f32_16x16x32_bf16 v[10:13], v[34:37], v[148:151], 0
	v_mfma_f32_16x16x32_bf16 v[184:187], v[42:45], v[152:155], v[10:13]
	v_mfma_f32_16x16x32_bf16 v[10:13], v[46:49], v[90:93], 0
	v_mfma_f32_16x16x32_bf16 v[188:191], v[50:53], v[126:129], v[10:13]
	v_mfma_f32_16x16x32_bf16 v[10:13], v[54:57], v[90:93], 0
	v_mfma_f32_16x16x32_bf16 v[126:129], v[58:61], v[126:129], v[10:13]
	v_mfma_f32_16x16x32_bf16 v[10:13], v[46:49], v[132:135], 0
	v_mfma_f32_16x16x32_bf16 v[192:195], v[50:53], v[136:139], v[10:13]
	v_mfma_f32_16x16x32_bf16 v[10:13], v[54:57], v[132:135], 0
	v_mfma_f32_16x16x32_bf16 v[132:135], v[58:61], v[136:139], v[10:13]
	v_mfma_f32_16x16x32_bf16 v[10:13], v[46:49], v[140:143], 0
	v_mfma_f32_16x16x32_bf16 v[136:139], v[50:53], v[144:147], v[10:13]
	v_mfma_f32_16x16x32_bf16 v[10:13], v[54:57], v[140:143], 0
	v_mfma_f32_16x16x32_bf16 v[140:143], v[58:61], v[144:147], v[10:13]
	v_mfma_f32_16x16x32_bf16 v[10:13], v[46:49], v[148:151], 0
	v_mfma_f32_16x16x32_bf16 v[144:147], v[50:53], v[152:155], v[10:13]
	v_mfma_f32_16x16x32_bf16 v[10:13], v[54:57], v[148:151], 0
	v_mfma_f32_16x16x32_bf16 v[148:151], v[58:61], v[152:155], v[10:13]
	s_barrier
	s_setprio 0
	ds_read_b128 v[152:155], v204
	ds_read_b128 v[196:199], v204 offset:1024
	ds_read_b128 v[200:203], v204 offset:2048
	ds_read_b128 v[204:207], v204 offset:3072
	ds_read_b128 v[208:211], v220
	ds_read_b128 v[212:215], v220 offset:1024
	ds_read_b128 v[216:219], v220 offset:2048
	ds_read_b128 v[220:223], v220 offset:3072
	s_mov_b32 m0, s15
	ds_read_b128 v[26:29], v131 offset:32768
	ds_read_b128 v[34:37], v131 offset:33792
	ds_read_b128 v[50:53], v131 offset:34816
	ds_read_b128 v[54:57], v131 offset:35840
	ds_read_b128 v[58:61], v131 offset:36864
	ds_read_b128 v[224:227], v131 offset:37888
	ds_read_b128 v[228:231], v131 offset:38912
	ds_read_b128 v[232:235], v131 offset:39936
	global_load_lds_dwordx4 v[2:3], off
	s_mov_b32 m0, s16
	s_nop 0
	global_load_lds_dwordx4 v[4:5], off
	s_waitcnt vmcnt(8)
	s_waitcnt lgkmcnt(0)
	s_setprio 1
	s_barrier
	v_mfma_f32_16x16x32_bf16 v[2:5], v[152:155], v[26:29], v[6:9]
	v_mfma_f32_16x16x32_bf16 v[42:45], v[196:199], v[34:37], v[2:5]
	v_mfma_f32_16x16x32_bf16 v[2:5], v[200:203], v[26:29], v[94:97]
	v_mfma_f32_16x16x32_bf16 v[46:49], v[204:207], v[34:37], v[2:5]
	v_mfma_f32_16x16x32_bf16 v[2:5], v[152:155], v[50:53], v[98:101]
	v_mfma_f32_16x16x32_bf16 v[18:21], v[196:199], v[54:57], v[2:5]
	v_mfma_f32_16x16x32_bf16 v[2:5], v[200:203], v[50:53], v[102:105]
	v_mfma_f32_16x16x32_bf16 v[22:25], v[204:207], v[54:57], v[2:5]
	v_mfma_f32_16x16x32_bf16 v[2:5], v[152:155], v[58:61], v[106:109]
	v_mfma_f32_16x16x32_bf16 v[10:13], v[196:199], v[224:227], v[2:5]
	v_mfma_f32_16x16x32_bf16 v[2:5], v[200:203], v[58:61], v[110:113]
	v_mfma_f32_16x16x32_bf16 v[14:17], v[204:207], v[224:227], v[2:5]
	v_mfma_f32_16x16x32_bf16 v[2:5], v[152:155], v[228:231], v[114:117]
	v_mfma_f32_16x16x32_bf16 v[6:9], v[200:203], v[228:231], v[118:121]
	v_mfma_f32_16x16x32_bf16 v[2:5], v[196:199], v[232:235], v[2:5]
	v_mfma_f32_16x16x32_bf16 v[6:9], v[204:207], v[232:235], v[6:9]
	v_mfma_f32_16x16x32_bf16 v[90:93], v[208:211], v[26:29], v[122:125]
	v_mfma_f32_16x16x32_bf16 v[26:29], v[216:219], v[26:29], v[62:65]
	v_mfma_f32_16x16x32_bf16 v[94:97], v[220:223], v[34:37], v[26:29]
	v_mfma_f32_16x16x32_bf16 v[26:29], v[208:211], v[50:53], v[66:69]
	v_mfma_f32_16x16x32_bf16 v[66:69], v[212:215], v[54:57], v[26:29]
	v_mfma_f32_16x16x32_bf16 v[26:29], v[216:219], v[50:53], v[70:73]
	v_mfma_f32_16x16x32_bf16 v[70:73], v[220:223], v[54:57], v[26:29]
	v_mfma_f32_16x16x32_bf16 v[26:29], v[208:211], v[58:61], v[74:77]
	v_mfma_f32_16x16x32_bf16 v[50:53], v[212:215], v[224:227], v[26:29]
	v_mfma_f32_16x16x32_bf16 v[26:29], v[216:219], v[58:61], v[78:81]
	v_mfma_f32_16x16x32_bf16 v[90:93], v[212:215], v[34:37], v[90:93]
	v_mfma_f32_16x16x32_bf16 v[54:57], v[220:223], v[224:227], v[26:29]
	v_mfma_f32_16x16x32_bf16 v[26:29], v[208:211], v[228:231], v[82:85]
	v_mfma_f32_16x16x32_bf16 v[34:37], v[216:219], v[228:231], v[86:89]
	v_mfma_f32_16x16x32_bf16 v[26:29], v[212:215], v[232:235], v[26:29]
	v_mfma_f32_16x16x32_bf16 v[34:37], v[220:223], v[232:235], v[34:37]
	s_barrier
	s_setprio 0
	s_mov_b32 m0, s11
	ds_read_b128 v[82:85], v131 offset:49152
	ds_read_b128 v[86:89], v131 offset:50176
	ds_read_b128 v[106:109], v131 offset:51200
	ds_read_b128 v[110:113], v131 offset:52224
	ds_read_b128 v[224:227], v131 offset:53248
	ds_read_b128 v[228:231], v131 offset:54272
	ds_read_b128 v[232:235], v131 offset:55296
	ds_read_b128 v[236:239], v131 offset:56320
	global_load_lds_dwordx4 v[32:33], off
	s_mov_b32 m0, s13
	s_nop 0
	global_load_lds_dwordx4 v[38:39], off
	s_mov_b32 m0, s18
	s_nop 0
	global_load_lds_dwordx4 v[240:241], off
	s_mov_b32 m0, s19
	s_nop 0
	global_load_lds_dwordx4 v[242:243], off
	s_mov_b32 m0, s12
	s_nop 0
	global_load_lds_dwordx4 v[30:31], off
	s_mov_b32 m0, s14
	s_nop 0
	global_load_lds_dwordx4 v[40:41], off
	s_waitcnt vmcnt(8)
	s_waitcnt lgkmcnt(0)
	s_setprio 1
	s_barrier
	v_mfma_f32_16x16x32_bf16 v[30:33], v[152:155], v[82:85], v[156:159]
	v_mfma_f32_16x16x32_bf16 v[98:101], v[196:199], v[86:89], v[30:33]
	v_mfma_f32_16x16x32_bf16 v[30:33], v[200:203], v[82:85], v[160:163]
	v_mfma_f32_16x16x32_bf16 v[102:105], v[204:207], v[86:89], v[30:33]
	v_mfma_f32_16x16x32_bf16 v[30:33], v[152:155], v[106:109], v[164:167]
	v_mfma_f32_16x16x32_bf16 v[74:77], v[196:199], v[110:113], v[30:33]
	v_mfma_f32_16x16x32_bf16 v[30:33], v[200:203], v[106:109], v[168:171]
	v_mfma_f32_16x16x32_bf16 v[78:81], v[204:207], v[110:113], v[30:33]
	v_mfma_f32_16x16x32_bf16 v[30:33], v[152:155], v[224:227], v[172:175]
	v_mfma_f32_16x16x32_bf16 v[58:61], v[196:199], v[228:231], v[30:33]
	v_mfma_f32_16x16x32_bf16 v[30:33], v[200:203], v[224:227], v[176:179]
	v_mfma_f32_16x16x32_bf16 v[62:65], v[204:207], v[228:231], v[30:33]
	v_mfma_f32_16x16x32_bf16 v[30:33], v[152:155], v[232:235], v[180:183]
	v_mfma_f32_16x16x32_bf16 v[38:41], v[200:203], v[232:235], v[184:187]
	v_mfma_f32_16x16x32_bf16 v[30:33], v[196:199], v[236:239], v[30:33]
	v_mfma_f32_16x16x32_bf16 v[38:41], v[204:207], v[236:239], v[38:41]
	v_mfma_f32_16x16x32_bf16 v[114:117], v[208:211], v[82:85], v[188:191]
	v_mfma_f32_16x16x32_bf16 v[82:85], v[216:219], v[82:85], v[126:129]
	v_mfma_f32_16x16x32_bf16 v[126:129], v[220:223], v[86:89], v[82:85]
	v_mfma_f32_16x16x32_bf16 v[82:85], v[208:211], v[106:109], v[192:195]
	v_mfma_f32_16x16x32_bf16 v[122:125], v[212:215], v[86:89], v[114:117]
	v_mfma_f32_16x16x32_bf16 v[114:117], v[212:215], v[110:113], v[82:85]
	v_mfma_f32_16x16x32_bf16 v[82:85], v[216:219], v[106:109], v[132:135]
	v_mfma_f32_16x16x32_bf16 v[118:121], v[220:223], v[110:113], v[82:85]
	v_mfma_f32_16x16x32_bf16 v[82:85], v[208:211], v[224:227], v[136:139]
	v_mfma_f32_16x16x32_bf16 v[106:109], v[212:215], v[228:231], v[82:85]
	v_mfma_f32_16x16x32_bf16 v[82:85], v[216:219], v[224:227], v[140:143]
	v_mfma_f32_16x16x32_bf16 v[110:113], v[220:223], v[228:231], v[82:85]
	v_mfma_f32_16x16x32_bf16 v[82:85], v[208:211], v[232:235], v[144:147]
	v_mfma_f32_16x16x32_bf16 v[86:89], v[216:219], v[232:235], v[148:151]
	v_mfma_f32_16x16x32_bf16 v[82:85], v[212:215], v[236:239], v[82:85]
	v_mfma_f32_16x16x32_bf16 v[86:89], v[220:223], v[236:239], v[86:89]
	s_barrier
	s_setprio 0
	s_cbranch_scc1 .LBB0_1708
	s_barrier

.LBB0_1840:
	ds_read_b128 v[146:149], v152
	ds_read_b128 v[156:159], v152 offset:1024
	ds_read_b128 v[160:163], v152 offset:2048
	ds_read_b128 v[164:167], v152 offset:3072
	ds_read_b128 v[168:171], v153
	ds_read_b128 v[172:175], v153 offset:1024
	ds_read_b128 v[176:179], v153 offset:2048
	ds_read_b128 v[180:183], v153 offset:3072
	s_add_u32 s28, s26, 0xfff80080
	s_addc_u32 s29, s27, -1
	s_cmp_eq_u32 s54, 28
	s_cselect_b32 s31, s19, s29
	s_cselect_b32 s30, s50, s28
	s_cselect_b32 s29, s17, s53
	s_cselect_b32 s28, s51, s52
	v_lshl_add_u64 v[216:217], s[26:27], 0, v[140:141]
	s_add_i32 m0, s25, 0xc000
	ds_read_b128 v[184:187], v154
	ds_read_b128 v[188:191], v154 offset:1024
	ds_read_b128 v[192:195], v154 offset:2048
	ds_read_b128 v[196:199], v154 offset:3072
	ds_read_b128 v[200:203], v154 offset:4096
	ds_read_b128 v[204:207], v154 offset:5120
	ds_read_b128 v[208:211], v154 offset:6144
	ds_read_b128 v[212:215], v154 offset:7168
	global_load_lds_dwordx4 v[216:217], off
	v_lshl_add_u64 v[216:217], s[26:27], 0, v[138:139]
	s_add_i32 m0, s25, 0xe000
	s_nop 0
	global_load_lds_dwordx4 v[216:217], off
	s_waitcnt vmcnt(8)
	s_waitcnt lgkmcnt(0)
	s_setprio 1
	s_barrier
	v_mfma_f32_16x16x32_bf16 v[122:125], v[146:149], v[184:187], v[122:125]
	v_mfma_f32_16x16x32_bf16 v[118:121], v[160:163], v[184:187], v[118:121]
	v_mfma_f32_16x16x32_bf16 v[106:109], v[146:149], v[192:195], v[106:109]
	v_mfma_f32_16x16x32_bf16 v[102:105], v[160:163], v[192:195], v[102:105]
	v_mfma_f32_16x16x32_bf16 v[90:93], v[146:149], v[200:203], v[90:93]
	v_mfma_f32_16x16x32_bf16 v[86:89], v[160:163], v[200:203], v[86:89]
	v_mfma_f32_16x16x32_bf16 v[74:77], v[146:149], v[208:211], v[74:77]
	v_mfma_f32_16x16x32_bf16 v[70:73], v[160:163], v[208:211], v[70:73]
	v_mfma_f32_16x16x32_bf16 v[122:125], v[156:159], v[188:191], v[122:125]
	v_mfma_f32_16x16x32_bf16 v[118:121], v[164:167], v[188:191], v[118:121]
	v_mfma_f32_16x16x32_bf16 v[106:109], v[156:159], v[196:199], v[106:109]
	v_mfma_f32_16x16x32_bf16 v[102:105], v[164:167], v[196:199], v[102:105]
	v_mfma_f32_16x16x32_bf16 v[90:93], v[156:159], v[204:207], v[90:93]
	v_mfma_f32_16x16x32_bf16 v[86:89], v[164:167], v[204:207], v[86:89]
	v_mfma_f32_16x16x32_bf16 v[74:77], v[156:159], v[212:215], v[74:77]
	v_mfma_f32_16x16x32_bf16 v[70:73], v[164:167], v[212:215], v[70:73]
	v_mfma_f32_16x16x32_bf16 v[126:129], v[168:171], v[184:187], v[126:129]
	v_mfma_f32_16x16x32_bf16 v[114:117], v[176:179], v[184:187], v[114:117]
	v_mfma_f32_16x16x32_bf16 v[110:113], v[168:171], v[192:195], v[110:113]
	v_mfma_f32_16x16x32_bf16 v[98:101], v[176:179], v[192:195], v[98:101]
	v_mfma_f32_16x16x32_bf16 v[94:97], v[168:171], v[200:203], v[94:97]
	v_mfma_f32_16x16x32_bf16 v[82:85], v[176:179], v[200:203], v[82:85]
	v_mfma_f32_16x16x32_bf16 v[78:81], v[168:171], v[208:211], v[78:81]
	v_mfma_f32_16x16x32_bf16 v[66:69], v[176:179], v[208:211], v[66:69]
	v_mfma_f32_16x16x32_bf16 v[126:129], v[172:175], v[188:191], v[126:129]
	v_mfma_f32_16x16x32_bf16 v[114:117], v[180:183], v[188:191], v[114:117]
	v_mfma_f32_16x16x32_bf16 v[110:113], v[172:175], v[196:199], v[110:113]
	v_mfma_f32_16x16x32_bf16 v[98:101], v[180:183], v[196:199], v[98:101]
	v_mfma_f32_16x16x32_bf16 v[94:97], v[172:175], v[204:207], v[94:97]
	v_mfma_f32_16x16x32_bf16 v[82:85], v[180:183], v[204:207], v[82:85]
	v_mfma_f32_16x16x32_bf16 v[78:81], v[172:175], v[212:215], v[78:81]
	v_mfma_f32_16x16x32_bf16 v[66:69], v[180:183], v[212:215], v[66:69]
	s_barrier
	s_setprio 0
	s_add_i32 s55, s46, s34
	v_lshl_add_u64 v[216:217], s[28:29], 0, v[134:135]
	s_mov_b32 m0, s55
	ds_read_b128 v[184:187], v154 offset:16384
	ds_read_b128 v[188:191], v154 offset:17408
	ds_read_b128 v[192:195], v154 offset:18432
	ds_read_b128 v[196:199], v154 offset:19456
	ds_read_b128 v[200:203], v154 offset:20480
	ds_read_b128 v[204:207], v154 offset:21504
	ds_read_b128 v[208:211], v154 offset:22528
	ds_read_b128 v[212:215], v154 offset:23552
	global_load_lds_dwordx4 v[216:217], off
	s_add_i32 m0, s55, 0x2000
	s_add_u32 s56, s28, 0x80000
	v_lshl_add_u64 v[218:219], s[28:29], 0, v[130:131]
	s_addc_u32 s57, s29, 0
	s_add_i32 s55, s47, s34
	global_load_lds_dwordx4 v[218:219], off
	v_lshl_add_u64 v[220:221], s[56:57], 0, v[134:135]
	s_mov_b32 m0, s55
	v_lshl_add_u64 v[222:223], s[30:31], 0, v[132:133]
	global_load_lds_dwordx4 v[220:221], off
	v_lshl_add_u64 v[220:221], s[56:57], 0, v[130:131]
	s_add_i32 m0, s55, 0x2000
	s_nop 0
	global_load_lds_dwordx4 v[220:221], off
	v_lshl_add_u64 v[220:221], s[30:31], 0, v[136:137]
	s_mov_b32 m0, s25
	s_nop 0
	global_load_lds_dwordx4 v[220:221], off
	s_mov_b32 m0, s37
	s_nop 0
	global_load_lds_dwordx4 v[222:223], off
	s_waitcnt vmcnt(8)
	s_waitcnt lgkmcnt(0)
	s_setprio 1
	s_barrier
	v_mfma_f32_16x16x32_bf16 v[58:61], v[146:149], v[184:187], v[58:61]
	v_mfma_f32_16x16x32_bf16 v[54:57], v[160:163], v[184:187], v[54:57]
	v_mfma_f32_16x16x32_bf16 v[42:45], v[146:149], v[192:195], v[42:45]
	v_mfma_f32_16x16x32_bf16 v[38:41], v[160:163], v[192:195], v[38:41]
	v_mfma_f32_16x16x32_bf16 v[26:29], v[146:149], v[200:203], v[26:29]
	v_mfma_f32_16x16x32_bf16 v[22:25], v[160:163], v[200:203], v[22:25]
	v_mfma_f32_16x16x32_bf16 v[10:13], v[146:149], v[208:211], v[10:13]
	v_mfma_f32_16x16x32_bf16 v[6:9], v[160:163], v[208:211], v[6:9]
	v_mfma_f32_16x16x32_bf16 v[58:61], v[156:159], v[188:191], v[58:61]
	v_mfma_f32_16x16x32_bf16 v[54:57], v[164:167], v[188:191], v[54:57]
	v_mfma_f32_16x16x32_bf16 v[42:45], v[156:159], v[196:199], v[42:45]
	v_mfma_f32_16x16x32_bf16 v[38:41], v[164:167], v[196:199], v[38:41]
	v_mfma_f32_16x16x32_bf16 v[26:29], v[156:159], v[204:207], v[26:29]
	v_mfma_f32_16x16x32_bf16 v[22:25], v[164:167], v[204:207], v[22:25]
	v_mfma_f32_16x16x32_bf16 v[10:13], v[156:159], v[212:215], v[10:13]
	v_mfma_f32_16x16x32_bf16 v[6:9], v[164:167], v[212:215], v[6:9]
	v_mfma_f32_16x16x32_bf16 v[62:65], v[168:171], v[184:187], v[62:65]
	v_mfma_f32_16x16x32_bf16 v[50:53], v[176:179], v[184:187], v[50:53]
	v_mfma_f32_16x16x32_bf16 v[46:49], v[168:171], v[192:195], v[46:49]
	v_mfma_f32_16x16x32_bf16 v[34:37], v[176:179], v[192:195], v[34:37]
	v_mfma_f32_16x16x32_bf16 v[30:33], v[168:171], v[200:203], v[30:33]
	v_mfma_f32_16x16x32_bf16 v[18:21], v[176:179], v[200:203], v[18:21]
	v_mfma_f32_16x16x32_bf16 v[14:17], v[168:171], v[208:211], v[14:17]
	v_mfma_f32_16x16x32_bf16 v[2:5], v[176:179], v[208:211], v[2:5]
	v_mfma_f32_16x16x32_bf16 v[62:65], v[172:175], v[188:191], v[62:65]
	v_mfma_f32_16x16x32_bf16 v[50:53], v[180:183], v[188:191], v[50:53]
	v_mfma_f32_16x16x32_bf16 v[46:49], v[172:175], v[196:199], v[46:49]
	v_mfma_f32_16x16x32_bf16 v[34:37], v[180:183], v[196:199], v[34:37]
	v_mfma_f32_16x16x32_bf16 v[30:33], v[172:175], v[204:207], v[30:33]
	v_mfma_f32_16x16x32_bf16 v[18:21], v[180:183], v[204:207], v[18:21]
	v_mfma_f32_16x16x32_bf16 v[14:17], v[172:175], v[212:215], v[14:17]
	v_mfma_f32_16x16x32_bf16 v[2:5], v[180:183], v[212:215], v[2:5]
	s_barrier
	s_setprio 0
	s_add_i32 s55, 0, 0x18000
	v_add_u32_e32 v155, s55, v151
	s_add_i32 s56, 0, 0x1c000
	ds_read_b128 v[146:149], v155
	ds_read_b128 v[156:159], v155 offset:1024
	ds_read_b128 v[160:163], v155 offset:2048
	ds_read_b128 v[164:167], v155 offset:3072
	v_add_u32_e32 v155, s56, v151
	ds_read_b128 v[168:171], v155
	ds_read_b128 v[172:175], v155 offset:1024
	ds_read_b128 v[176:179], v155 offset:2048
	ds_read_b128 v[180:183], v155 offset:3072
	s_add_u32 s30, s30, 0x80000
	s_addc_u32 s31, s31, 0
	s_mov_b32 m0, s38
	v_lshl_add_u64 v[224:225], s[30:31], 0, v[136:137]
	ds_read_b128 v[184:187], v154 offset:32768
	ds_read_b128 v[188:191], v154 offset:33792
	ds_read_b128 v[192:195], v154 offset:34816
	ds_read_b128 v[196:199], v154 offset:35840
	ds_read_b128 v[200:203], v154 offset:36864
	ds_read_b128 v[204:207], v154 offset:37888
	ds_read_b128 v[208:211], v154 offset:38912
	ds_read_b128 v[212:215], v154 offset:39936
	global_load_lds_dwordx4 v[224:225], off
	v_lshl_add_u64 v[224:225], s[30:31], 0, v[132:133]
	s_mov_b32 m0, s39
	s_nop 0
	global_load_lds_dwordx4 v[224:225], off
	s_waitcnt vmcnt(8)
	s_waitcnt lgkmcnt(0)
	s_setprio 1
	s_barrier
	v_mfma_f32_16x16x32_bf16 v[122:125], v[146:149], v[184:187], v[122:125]
	v_mfma_f32_16x16x32_bf16 v[118:121], v[160:163], v[184:187], v[118:121]
	v_mfma_f32_16x16x32_bf16 v[106:109], v[146:149], v[192:195], v[106:109]
	v_mfma_f32_16x16x32_bf16 v[102:105], v[160:163], v[192:195], v[102:105]
	v_mfma_f32_16x16x32_bf16 v[90:93], v[146:149], v[200:203], v[90:93]
	v_mfma_f32_16x16x32_bf16 v[86:89], v[160:163], v[200:203], v[86:89]
	v_mfma_f32_16x16x32_bf16 v[74:77], v[146:149], v[208:211], v[74:77]
	v_mfma_f32_16x16x32_bf16 v[70:73], v[160:163], v[208:211], v[70:73]
	v_mfma_f32_16x16x32_bf16 v[122:125], v[156:159], v[188:191], v[122:125]
	v_mfma_f32_16x16x32_bf16 v[118:121], v[164:167], v[188:191], v[118:121]
	v_mfma_f32_16x16x32_bf16 v[106:109], v[156:159], v[196:199], v[106:109]
	v_mfma_f32_16x16x32_bf16 v[102:105], v[164:167], v[196:199], v[102:105]
	v_mfma_f32_16x16x32_bf16 v[90:93], v[156:159], v[204:207], v[90:93]
	v_mfma_f32_16x16x32_bf16 v[86:89], v[164:167], v[204:207], v[86:89]
	v_mfma_f32_16x16x32_bf16 v[74:77], v[156:159], v[212:215], v[74:77]
	v_mfma_f32_16x16x32_bf16 v[70:73], v[164:167], v[212:215], v[70:73]
	v_mfma_f32_16x16x32_bf16 v[126:129], v[168:171], v[184:187], v[126:129]
	v_mfma_f32_16x16x32_bf16 v[114:117], v[176:179], v[184:187], v[114:117]
	v_mfma_f32_16x16x32_bf16 v[110:113], v[168:171], v[192:195], v[110:113]
	v_mfma_f32_16x16x32_bf16 v[98:101], v[176:179], v[192:195], v[98:101]
	v_mfma_f32_16x16x32_bf16 v[94:97], v[168:171], v[200:203], v[94:97]
	v_mfma_f32_16x16x32_bf16 v[82:85], v[176:179], v[200:203], v[82:85]
	v_mfma_f32_16x16x32_bf16 v[78:81], v[168:171], v[208:211], v[78:81]
	v_mfma_f32_16x16x32_bf16 v[66:69], v[176:179], v[208:211], v[66:69]
	v_mfma_f32_16x16x32_bf16 v[126:129], v[172:175], v[188:191], v[126:129]
	v_mfma_f32_16x16x32_bf16 v[114:117], v[180:183], v[188:191], v[114:117]
	v_mfma_f32_16x16x32_bf16 v[110:113], v[172:175], v[196:199], v[110:113]
	v_mfma_f32_16x16x32_bf16 v[98:101], v[180:183], v[196:199], v[98:101]
	v_mfma_f32_16x16x32_bf16 v[94:97], v[172:175], v[204:207], v[94:97]
	v_mfma_f32_16x16x32_bf16 v[82:85], v[180:183], v[204:207], v[82:85]
	v_mfma_f32_16x16x32_bf16 v[78:81], v[172:175], v[212:215], v[78:81]
	v_mfma_f32_16x16x32_bf16 v[66:69], v[180:183], v[212:215], v[66:69]
	s_barrier
	s_setprio 0
	s_add_i32 s30, s55, s34
	v_lshl_add_u64 v[216:217], v[216:217], 0, s[12:13]
	s_mov_b32 m0, s30
	ds_read_b128 v[184:187], v154 offset:49152
	ds_read_b128 v[188:191], v154 offset:50176
	ds_read_b128 v[192:195], v154 offset:51200
	ds_read_b128 v[196:199], v154 offset:52224
	ds_read_b128 v[200:203], v154 offset:53248
	ds_read_b128 v[204:207], v154 offset:54272
	ds_read_b128 v[208:211], v154 offset:55296
	ds_read_b128 v[212:215], v154 offset:56320
	global_load_lds_dwordx4 v[216:217], off
	s_add_i32 m0, s30, 0x2000
	s_add_u32 s28, s28, 0x80080
	v_lshl_add_u64 v[216:217], v[218:219], 0, s[12:13]
	s_addc_u32 s29, s29, 0
	s_add_i32 s30, s56, s34
	global_load_lds_dwordx4 v[216:217], off
	v_lshl_add_u64 v[216:217], s[28:29], 0, v[134:135]
	s_mov_b32 m0, s30
	s_nop 0
	global_load_lds_dwordx4 v[216:217], off
	v_lshl_add_u64 v[216:217], s[28:29], 0, v[130:131]
	s_add_i32 m0, s30, 0x2000
	s_nop 0
	global_load_lds_dwordx4 v[216:217], off
	v_lshl_add_u64 v[216:217], v[220:221], 0, s[12:13]
	s_mov_b32 m0, s42
	s_nop 0
	global_load_lds_dwordx4 v[216:217], off
	v_lshl_add_u64 v[216:217], v[222:223], 0, s[12:13]
	s_mov_b32 m0, s43
	s_nop 0
	global_load_lds_dwordx4 v[216:217], off
	s_waitcnt vmcnt(8)
	s_waitcnt lgkmcnt(0)
	s_setprio 1
	s_barrier
	v_mfma_f32_16x16x32_bf16 v[58:61], v[146:149], v[184:187], v[58:61]
	v_mfma_f32_16x16x32_bf16 v[54:57], v[160:163], v[184:187], v[54:57]
	v_mfma_f32_16x16x32_bf16 v[42:45], v[146:149], v[192:195], v[42:45]
	v_mfma_f32_16x16x32_bf16 v[38:41], v[160:163], v[192:195], v[38:41]
	v_mfma_f32_16x16x32_bf16 v[26:29], v[146:149], v[200:203], v[26:29]
	v_mfma_f32_16x16x32_bf16 v[22:25], v[160:163], v[200:203], v[22:25]
	v_mfma_f32_16x16x32_bf16 v[10:13], v[146:149], v[208:211], v[10:13]
	v_mfma_f32_16x16x32_bf16 v[6:9], v[160:163], v[208:211], v[6:9]
	v_mfma_f32_16x16x32_bf16 v[58:61], v[156:159], v[188:191], v[58:61]
	v_mfma_f32_16x16x32_bf16 v[54:57], v[164:167], v[188:191], v[54:57]
	v_mfma_f32_16x16x32_bf16 v[42:45], v[156:159], v[196:199], v[42:45]
	v_mfma_f32_16x16x32_bf16 v[38:41], v[164:167], v[196:199], v[38:41]
	v_mfma_f32_16x16x32_bf16 v[26:29], v[156:159], v[204:207], v[26:29]
	v_mfma_f32_16x16x32_bf16 v[22:25], v[164:167], v[204:207], v[22:25]
	v_mfma_f32_16x16x32_bf16 v[10:13], v[156:159], v[212:215], v[10:13]
	v_mfma_f32_16x16x32_bf16 v[6:9], v[164:167], v[212:215], v[6:9]
	v_mfma_f32_16x16x32_bf16 v[62:65], v[168:171], v[184:187], v[62:65]
	v_mfma_f32_16x16x32_bf16 v[50:53], v[176:179], v[184:187], v[50:53]
	v_mfma_f32_16x16x32_bf16 v[46:49], v[168:171], v[192:195], v[46:49]
	v_mfma_f32_16x16x32_bf16 v[34:37], v[176:179], v[192:195], v[34:37]
	v_mfma_f32_16x16x32_bf16 v[30:33], v[168:171], v[200:203], v[30:33]
	v_mfma_f32_16x16x32_bf16 v[18:21], v[176:179], v[200:203], v[18:21]
	v_mfma_f32_16x16x32_bf16 v[14:17], v[168:171], v[208:211], v[14:17]
	v_mfma_f32_16x16x32_bf16 v[2:5], v[176:179], v[208:211], v[2:5]
	v_mfma_f32_16x16x32_bf16 v[62:65], v[172:175], v[188:191], v[62:65]
	v_mfma_f32_16x16x32_bf16 v[50:53], v[180:183], v[188:191], v[50:53]
	v_mfma_f32_16x16x32_bf16 v[46:49], v[172:175], v[196:199], v[46:49]
	v_mfma_f32_16x16x32_bf16 v[34:37], v[180:183], v[196:199], v[34:37]
	v_mfma_f32_16x16x32_bf16 v[30:33], v[172:175], v[204:207], v[30:33]
	v_mfma_f32_16x16x32_bf16 v[18:21], v[180:183], v[204:207], v[18:21]
	v_mfma_f32_16x16x32_bf16 v[14:17], v[172:175], v[212:215], v[14:17]
	v_mfma_f32_16x16x32_bf16 v[2:5], v[180:183], v[212:215], v[2:5]
	s_barrier
	s_setprio 0
	s_add_i32 s54, s54, 2
	s_add_u32 s52, s52, 0x100
	s_addc_u32 s53, s53, 0
	s_add_u32 s26, s26, 0x100
	s_addc_u32 s27, s27, 0
	s_cmp_gt_u32 s54, 29
	s_cbranch_scc0 .LBB0_1840
	s_and_b64 vcc, exec, s[14:15]
	s_cbranch_vccz .LBB0_1843
	s_barrier

.LBB0_1919:
	ds_read_b128 v[82:85], v220
	ds_read_b128 v[86:89], v220 offset:1024
	ds_read_b128 v[106:109], v220 offset:2048
	ds_read_b128 v[110:113], v220 offset:3072
	ds_read_b128 v[146:149], v221
	ds_read_b128 v[150:153], v221 offset:1024
	ds_read_b128 v[154:157], v221 offset:2048
	ds_read_b128 v[158:161], v221 offset:3072
	s_add_u32 s6, s8, 0x100
	s_addc_u32 s7, s9, 0
	s_cmpk_eq_i32 s61, 0x54
	s_cselect_b32 s13, s39, s7
	s_cselect_b32 s12, s38, s6
	s_cselect_b32 s11, s41, s18
	s_cselect_b32 s10, s40, s15
	v_lshl_add_u64 v[208:209], s[8:9], 0, v[180:181]
	s_add_i32 m0, s44, 0xc000
	ds_read_b128 v[162:165], v222
	ds_read_b128 v[166:169], v222 offset:1024
	ds_read_b128 v[184:187], v222 offset:2048
	ds_read_b128 v[188:191], v222 offset:3072
	ds_read_b128 v[192:195], v222 offset:4096
	ds_read_b128 v[196:199], v222 offset:5120
	ds_read_b128 v[200:203], v222 offset:6144
	ds_read_b128 v[204:207], v222 offset:7168
	global_load_lds_dwordx4 v[208:209], off
	v_lshl_add_u64 v[208:209], s[8:9], 0, v[178:179]
	s_add_i32 m0, s44, 0xe000
	s_nop 0
	global_load_lds_dwordx4 v[208:209], off
	s_waitcnt vmcnt(8)
	s_waitcnt lgkmcnt(0)
	s_setprio 1
	s_barrier
	v_mfma_f32_16x16x32_bf16 v[142:145], v[82:85], v[162:165], v[142:145]
	v_mfma_f32_16x16x32_bf16 v[138:141], v[106:109], v[162:165], v[138:141]
	v_mfma_f32_16x16x32_bf16 v[126:129], v[82:85], v[184:187], v[126:129]
	v_mfma_f32_16x16x32_bf16 v[122:125], v[106:109], v[184:187], v[122:125]
	v_mfma_f32_16x16x32_bf16 v[102:105], v[82:85], v[192:195], v[102:105]
	v_mfma_f32_16x16x32_bf16 v[98:101], v[106:109], v[192:195], v[98:101]
	v_mfma_f32_16x16x32_bf16 v[78:81], v[82:85], v[200:203], v[78:81]
	v_mfma_f32_16x16x32_bf16 v[74:77], v[106:109], v[200:203], v[74:77]
	v_mfma_f32_16x16x32_bf16 v[142:145], v[86:89], v[166:169], v[142:145]
	v_mfma_f32_16x16x32_bf16 v[138:141], v[110:113], v[166:169], v[138:141]
	v_mfma_f32_16x16x32_bf16 v[126:129], v[86:89], v[188:191], v[126:129]
	v_mfma_f32_16x16x32_bf16 v[122:125], v[110:113], v[188:191], v[122:125]
	v_mfma_f32_16x16x32_bf16 v[102:105], v[86:89], v[196:199], v[102:105]
	v_mfma_f32_16x16x32_bf16 v[98:101], v[110:113], v[196:199], v[98:101]
	v_mfma_f32_16x16x32_bf16 v[78:81], v[86:89], v[204:207], v[78:81]
	v_mfma_f32_16x16x32_bf16 v[74:77], v[110:113], v[204:207], v[74:77]
	v_mfma_f32_16x16x32_bf16 v[134:137], v[146:149], v[162:165], v[134:137]
	v_mfma_f32_16x16x32_bf16 v[130:133], v[154:157], v[162:165], v[130:133]
	v_mfma_f32_16x16x32_bf16 v[118:121], v[146:149], v[184:187], v[118:121]
	v_mfma_f32_16x16x32_bf16 v[114:117], v[154:157], v[184:187], v[114:117]
	v_mfma_f32_16x16x32_bf16 v[94:97], v[146:149], v[192:195], v[94:97]
	v_mfma_f32_16x16x32_bf16 v[90:93], v[154:157], v[192:195], v[90:93]
	v_mfma_f32_16x16x32_bf16 v[70:73], v[146:149], v[200:203], v[70:73]
	v_mfma_f32_16x16x32_bf16 v[66:69], v[154:157], v[200:203], v[66:69]
	v_mfma_f32_16x16x32_bf16 v[134:137], v[150:153], v[166:169], v[134:137]
	v_mfma_f32_16x16x32_bf16 v[130:133], v[158:161], v[166:169], v[130:133]
	v_mfma_f32_16x16x32_bf16 v[118:121], v[150:153], v[188:191], v[118:121]
	v_mfma_f32_16x16x32_bf16 v[114:117], v[158:161], v[188:191], v[114:117]
	v_mfma_f32_16x16x32_bf16 v[94:97], v[150:153], v[196:199], v[94:97]
	v_mfma_f32_16x16x32_bf16 v[90:93], v[158:161], v[196:199], v[90:93]
	v_mfma_f32_16x16x32_bf16 v[70:73], v[150:153], v[204:207], v[70:73]
	v_mfma_f32_16x16x32_bf16 v[66:69], v[158:161], v[204:207], v[66:69]
	s_barrier
	s_setprio 0
	s_add_i32 s8, s55, s43
	v_lshl_add_u64 v[208:209], s[10:11], 0, v[172:173]
	s_mov_b32 m0, s8
	ds_read_b128 v[162:165], v222 offset:16384
	ds_read_b128 v[166:169], v222 offset:17408
	ds_read_b128 v[184:187], v222 offset:18432
	ds_read_b128 v[188:191], v222 offset:19456
	ds_read_b128 v[192:195], v222 offset:20480
	ds_read_b128 v[196:199], v222 offset:21504
	ds_read_b128 v[200:203], v222 offset:22528
	ds_read_b128 v[204:207], v222 offset:23552
	global_load_lds_dwordx4 v[208:209], off
	s_add_i32 m0, s8, 0x2000
	s_add_u32 s8, s10, 0x160000
	v_lshl_add_u64 v[210:211], s[10:11], 0, v[176:177]
	s_addc_u32 s9, s11, 0
	s_add_i32 s62, s56, s43
	global_load_lds_dwordx4 v[210:211], off
	v_lshl_add_u64 v[212:213], s[8:9], 0, v[172:173]
	s_mov_b32 m0, s62
	v_lshl_add_u64 v[214:215], s[12:13], 0, v[174:175]
	global_load_lds_dwordx4 v[212:213], off
	v_lshl_add_u64 v[212:213], s[8:9], 0, v[176:177]
	s_add_i32 m0, s62, 0x2000
	s_nop 0
	global_load_lds_dwordx4 v[212:213], off
	v_lshl_add_u64 v[212:213], s[12:13], 0, v[170:171]
	s_mov_b32 m0, s44
	s_nop 0
	global_load_lds_dwordx4 v[212:213], off
	s_mov_b32 m0, s45
	s_nop 0
	global_load_lds_dwordx4 v[214:215], off
	s_waitcnt vmcnt(8)
	s_waitcnt lgkmcnt(0)
	s_setprio 1
	s_barrier
	v_mfma_f32_16x16x32_bf16 v[62:65], v[82:85], v[162:165], v[62:65]
	v_mfma_f32_16x16x32_bf16 v[58:61], v[106:109], v[162:165], v[58:61]
	v_mfma_f32_16x16x32_bf16 v[46:49], v[82:85], v[184:187], v[46:49]
	v_mfma_f32_16x16x32_bf16 v[42:45], v[106:109], v[184:187], v[42:45]
	v_mfma_f32_16x16x32_bf16 v[30:33], v[82:85], v[192:195], v[30:33]
	v_mfma_f32_16x16x32_bf16 v[26:29], v[106:109], v[192:195], v[26:29]
	v_mfma_f32_16x16x32_bf16 v[14:17], v[82:85], v[200:203], v[14:17]
	v_mfma_f32_16x16x32_bf16 v[10:13], v[106:109], v[200:203], v[10:13]
	v_mfma_f32_16x16x32_bf16 v[62:65], v[86:89], v[166:169], v[62:65]
	v_mfma_f32_16x16x32_bf16 v[58:61], v[110:113], v[166:169], v[58:61]
	v_mfma_f32_16x16x32_bf16 v[46:49], v[86:89], v[188:191], v[46:49]
	v_mfma_f32_16x16x32_bf16 v[42:45], v[110:113], v[188:191], v[42:45]
	v_mfma_f32_16x16x32_bf16 v[30:33], v[86:89], v[196:199], v[30:33]
	v_mfma_f32_16x16x32_bf16 v[26:29], v[110:113], v[196:199], v[26:29]
	v_mfma_f32_16x16x32_bf16 v[14:17], v[86:89], v[204:207], v[14:17]
	v_mfma_f32_16x16x32_bf16 v[10:13], v[110:113], v[204:207], v[10:13]
	v_mfma_f32_16x16x32_bf16 v[54:57], v[146:149], v[162:165], v[54:57]
	v_mfma_f32_16x16x32_bf16 v[50:53], v[154:157], v[162:165], v[50:53]
	v_mfma_f32_16x16x32_bf16 v[38:41], v[146:149], v[184:187], v[38:41]
	v_mfma_f32_16x16x32_bf16 v[34:37], v[154:157], v[184:187], v[34:37]
	v_mfma_f32_16x16x32_bf16 v[22:25], v[146:149], v[192:195], v[22:25]
	v_mfma_f32_16x16x32_bf16 v[18:21], v[154:157], v[192:195], v[18:21]
	v_mfma_f32_16x16x32_bf16 v[6:9], v[146:149], v[200:203], v[6:9]
	v_mfma_f32_16x16x32_bf16 v[2:5], v[154:157], v[200:203], v[2:5]
	v_mfma_f32_16x16x32_bf16 v[54:57], v[150:153], v[166:169], v[54:57]
	v_mfma_f32_16x16x32_bf16 v[50:53], v[158:161], v[166:169], v[50:53]
	v_mfma_f32_16x16x32_bf16 v[38:41], v[150:153], v[188:191], v[38:41]
	v_mfma_f32_16x16x32_bf16 v[34:37], v[158:161], v[188:191], v[34:37]
	v_mfma_f32_16x16x32_bf16 v[22:25], v[150:153], v[196:199], v[22:25]
	v_mfma_f32_16x16x32_bf16 v[18:21], v[158:161], v[196:199], v[18:21]
	v_mfma_f32_16x16x32_bf16 v[6:9], v[150:153], v[204:207], v[6:9]
	v_mfma_f32_16x16x32_bf16 v[2:5], v[158:161], v[204:207], v[2:5]
	s_barrier
	s_setprio 0
	s_add_i32 s62, 0, 0x18000
	s_add_i32 s63, 0, 0x1c000
	v_add_u32_e32 v110, s62, v219
	v_add_u32_e32 v158, s63, v219
	ds_read_b128 v[82:85], v110
	ds_read_b128 v[86:89], v110 offset:1024
	ds_read_b128 v[106:109], v110 offset:2048
	ds_read_b128 v[110:113], v110 offset:3072
	ds_read_b128 v[146:149], v158
	ds_read_b128 v[150:153], v158 offset:1024
	ds_read_b128 v[154:157], v158 offset:2048
	ds_read_b128 v[158:161], v158 offset:3072
	s_add_u32 s8, s12, 0x160000
	s_addc_u32 s9, s13, 0
	s_mov_b32 m0, s46
	v_lshl_add_u64 v[216:217], s[8:9], 0, v[170:171]
	ds_read_b128 v[162:165], v222 offset:32768
	ds_read_b128 v[166:169], v222 offset:33792
	ds_read_b128 v[184:187], v222 offset:34816
	ds_read_b128 v[188:191], v222 offset:35840
	ds_read_b128 v[192:195], v222 offset:36864
	ds_read_b128 v[196:199], v222 offset:37888
	ds_read_b128 v[200:203], v222 offset:38912
	ds_read_b128 v[204:207], v222 offset:39936
	global_load_lds_dwordx4 v[216:217], off
	v_lshl_add_u64 v[216:217], s[8:9], 0, v[174:175]
	s_mov_b32 m0, s47
	s_nop 0
	global_load_lds_dwordx4 v[216:217], off
	s_waitcnt vmcnt(8)
	s_waitcnt lgkmcnt(0)
	s_setprio 1
	s_barrier
	v_mfma_f32_16x16x32_bf16 v[142:145], v[82:85], v[162:165], v[142:145]
	v_mfma_f32_16x16x32_bf16 v[138:141], v[106:109], v[162:165], v[138:141]
	v_mfma_f32_16x16x32_bf16 v[126:129], v[82:85], v[184:187], v[126:129]
	v_mfma_f32_16x16x32_bf16 v[122:125], v[106:109], v[184:187], v[122:125]
	v_mfma_f32_16x16x32_bf16 v[102:105], v[82:85], v[192:195], v[102:105]
	v_mfma_f32_16x16x32_bf16 v[98:101], v[106:109], v[192:195], v[98:101]
	v_mfma_f32_16x16x32_bf16 v[78:81], v[82:85], v[200:203], v[78:81]
	v_mfma_f32_16x16x32_bf16 v[74:77], v[106:109], v[200:203], v[74:77]
	v_mfma_f32_16x16x32_bf16 v[142:145], v[86:89], v[166:169], v[142:145]
	v_mfma_f32_16x16x32_bf16 v[138:141], v[110:113], v[166:169], v[138:141]
	v_mfma_f32_16x16x32_bf16 v[126:129], v[86:89], v[188:191], v[126:129]
	v_mfma_f32_16x16x32_bf16 v[122:125], v[110:113], v[188:191], v[122:125]
	v_mfma_f32_16x16x32_bf16 v[102:105], v[86:89], v[196:199], v[102:105]
	v_mfma_f32_16x16x32_bf16 v[98:101], v[110:113], v[196:199], v[98:101]
	v_mfma_f32_16x16x32_bf16 v[78:81], v[86:89], v[204:207], v[78:81]
	v_mfma_f32_16x16x32_bf16 v[74:77], v[110:113], v[204:207], v[74:77]
	v_mfma_f32_16x16x32_bf16 v[134:137], v[146:149], v[162:165], v[134:137]
	v_mfma_f32_16x16x32_bf16 v[130:133], v[154:157], v[162:165], v[130:133]
	v_mfma_f32_16x16x32_bf16 v[118:121], v[146:149], v[184:187], v[118:121]
	v_mfma_f32_16x16x32_bf16 v[114:117], v[154:157], v[184:187], v[114:117]
	v_mfma_f32_16x16x32_bf16 v[94:97], v[146:149], v[192:195], v[94:97]
	v_mfma_f32_16x16x32_bf16 v[90:93], v[154:157], v[192:195], v[90:93]
	v_mfma_f32_16x16x32_bf16 v[70:73], v[146:149], v[200:203], v[70:73]
	v_mfma_f32_16x16x32_bf16 v[66:69], v[154:157], v[200:203], v[66:69]
	v_mfma_f32_16x16x32_bf16 v[134:137], v[150:153], v[166:169], v[134:137]
	v_mfma_f32_16x16x32_bf16 v[130:133], v[158:161], v[166:169], v[130:133]
	v_mfma_f32_16x16x32_bf16 v[118:121], v[150:153], v[188:191], v[118:121]
	v_mfma_f32_16x16x32_bf16 v[114:117], v[158:161], v[188:191], v[114:117]
	v_mfma_f32_16x16x32_bf16 v[94:97], v[150:153], v[196:199], v[94:97]
	v_mfma_f32_16x16x32_bf16 v[90:93], v[158:161], v[196:199], v[90:93]
	v_mfma_f32_16x16x32_bf16 v[70:73], v[150:153], v[204:207], v[70:73]
	v_mfma_f32_16x16x32_bf16 v[66:69], v[158:161], v[204:207], v[66:69]
	s_barrier
	s_setprio 0
	s_add_i32 s8, s62, s43
	v_lshl_add_u64 v[208:209], v[208:209], 0, s[30:31]
	s_mov_b32 m0, s8
	ds_read_b128 v[162:165], v222 offset:49152
	ds_read_b128 v[166:169], v222 offset:50176
	ds_read_b128 v[184:187], v222 offset:51200
	ds_read_b128 v[188:191], v222 offset:52224
	ds_read_b128 v[192:195], v222 offset:53248
	ds_read_b128 v[196:199], v222 offset:54272
	ds_read_b128 v[200:203], v222 offset:55296
	ds_read_b128 v[204:207], v222 offset:56320
	global_load_lds_dwordx4 v[208:209], off
	s_add_i32 m0, s8, 0x2000
	s_add_u32 s8, s10, 0x160080
	v_lshl_add_u64 v[208:209], v[210:211], 0, s[30:31]
	s_addc_u32 s9, s11, 0
	s_add_i32 s10, s63, s43
	global_load_lds_dwordx4 v[208:209], off
	v_lshl_add_u64 v[208:209], s[8:9], 0, v[172:173]
	s_mov_b32 m0, s10
	s_nop 0
	global_load_lds_dwordx4 v[208:209], off
	v_lshl_add_u64 v[208:209], s[8:9], 0, v[176:177]
	s_add_i32 m0, s10, 0x2000
	s_nop 0
	global_load_lds_dwordx4 v[208:209], off
	v_lshl_add_u64 v[208:209], v[212:213], 0, s[30:31]
	s_mov_b32 m0, s51
	s_nop 0
	global_load_lds_dwordx4 v[208:209], off
	v_lshl_add_u64 v[208:209], v[214:215], 0, s[30:31]
	s_mov_b32 m0, s52
	s_nop 0
	global_load_lds_dwordx4 v[208:209], off
	s_waitcnt vmcnt(8)
	s_waitcnt lgkmcnt(0)
	s_setprio 1
	s_barrier
	v_mfma_f32_16x16x32_bf16 v[62:65], v[82:85], v[162:165], v[62:65]
	v_mfma_f32_16x16x32_bf16 v[58:61], v[106:109], v[162:165], v[58:61]
	v_mfma_f32_16x16x32_bf16 v[46:49], v[82:85], v[184:187], v[46:49]
	v_mfma_f32_16x16x32_bf16 v[42:45], v[106:109], v[184:187], v[42:45]
	v_mfma_f32_16x16x32_bf16 v[30:33], v[82:85], v[192:195], v[30:33]
	v_mfma_f32_16x16x32_bf16 v[26:29], v[106:109], v[192:195], v[26:29]
	v_mfma_f32_16x16x32_bf16 v[14:17], v[82:85], v[200:203], v[14:17]
	v_mfma_f32_16x16x32_bf16 v[10:13], v[106:109], v[200:203], v[10:13]
	v_mfma_f32_16x16x32_bf16 v[62:65], v[86:89], v[166:169], v[62:65]
	v_mfma_f32_16x16x32_bf16 v[58:61], v[110:113], v[166:169], v[58:61]
	v_mfma_f32_16x16x32_bf16 v[46:49], v[86:89], v[188:191], v[46:49]
	v_mfma_f32_16x16x32_bf16 v[42:45], v[110:113], v[188:191], v[42:45]
	v_mfma_f32_16x16x32_bf16 v[30:33], v[86:89], v[196:199], v[30:33]
	v_mfma_f32_16x16x32_bf16 v[26:29], v[110:113], v[196:199], v[26:29]
	v_mfma_f32_16x16x32_bf16 v[14:17], v[86:89], v[204:207], v[14:17]
	v_mfma_f32_16x16x32_bf16 v[10:13], v[110:113], v[204:207], v[10:13]
	v_mfma_f32_16x16x32_bf16 v[54:57], v[146:149], v[162:165], v[54:57]
	v_mfma_f32_16x16x32_bf16 v[50:53], v[154:157], v[162:165], v[50:53]
	v_mfma_f32_16x16x32_bf16 v[38:41], v[146:149], v[184:187], v[38:41]
	v_mfma_f32_16x16x32_bf16 v[34:37], v[154:157], v[184:187], v[34:37]
	v_mfma_f32_16x16x32_bf16 v[22:25], v[146:149], v[192:195], v[22:25]
	v_mfma_f32_16x16x32_bf16 v[18:21], v[154:157], v[192:195], v[18:21]
	v_mfma_f32_16x16x32_bf16 v[6:9], v[146:149], v[200:203], v[6:9]
	v_mfma_f32_16x16x32_bf16 v[2:5], v[154:157], v[200:203], v[2:5]
	v_mfma_f32_16x16x32_bf16 v[54:57], v[150:153], v[166:169], v[54:57]
	v_mfma_f32_16x16x32_bf16 v[50:53], v[158:161], v[166:169], v[50:53]
	v_mfma_f32_16x16x32_bf16 v[38:41], v[150:153], v[188:191], v[38:41]
	v_mfma_f32_16x16x32_bf16 v[34:37], v[158:161], v[188:191], v[34:37]
	v_mfma_f32_16x16x32_bf16 v[22:25], v[150:153], v[196:199], v[22:25]
	v_mfma_f32_16x16x32_bf16 v[18:21], v[158:161], v[196:199], v[18:21]
	v_mfma_f32_16x16x32_bf16 v[6:9], v[150:153], v[204:207], v[6:9]
	v_mfma_f32_16x16x32_bf16 v[2:5], v[158:161], v[204:207], v[2:5]
	s_barrier
	s_setprio 0
	s_add_i32 s61, s61, 2
	s_add_u32 s15, s15, 0x100
	s_addc_u32 s18, s18, 0
	s_cmpk_gt_u32 s61, 0x55
	s_mov_b64 s[8:9], s[6:7]
	s_cbranch_scc0 .LBB0_1919
	s_and_b64 vcc, exec, s[36:37]
	s_cbranch_vccz .LBB0_1922
	s_barrier

.LBB0_1945:
	ds_read_b128 v[148:151], v143
	ds_read_b128 v[152:155], v143 offset:1024
	ds_read_b128 v[156:159], v143 offset:2048
	ds_read_b128 v[160:163], v143 offset:3072
	ds_read_b128 v[164:167], v144
	ds_read_b128 v[168:171], v144 offset:1024
	ds_read_b128 v[172:175], v144 offset:2048
	ds_read_b128 v[176:179], v144 offset:3072
	s_add_u32 s10, s8, 0x100
	s_addc_u32 s11, s9, 0
	s_cmp_lg_u32 s27, 18
	s_cselect_b32 s12, s10, 0
	s_cselect_b32 s13, s11, 0
	s_add_u32 s14, s4, s12
	s_addc_u32 s15, s5, s13
	s_add_u32 s12, s2, s12
	s_addc_u32 s13, s3, s13
	s_mov_b32 m0, s28
	v_lshl_add_u64 v[212:213], v[140:141], 0, s[8:9]
	ds_read_b128 v[180:183], v145
	ds_read_b128 v[184:187], v145 offset:1024
	ds_read_b128 v[188:191], v145 offset:2048
	ds_read_b128 v[192:195], v145 offset:3072
	ds_read_b128 v[196:199], v145 offset:4096
	ds_read_b128 v[200:203], v145 offset:5120
	ds_read_b128 v[204:207], v145 offset:6144
	ds_read_b128 v[208:211], v145 offset:7168
	global_load_lds_dwordx4 v[212:213], off
	v_lshl_add_u64 v[212:213], v[138:139], 0, s[8:9]
	s_mov_b32 m0, s29
	s_nop 0
	global_load_lds_dwordx4 v[212:213], off
	s_waitcnt vmcnt(8)
	s_waitcnt lgkmcnt(0)
	s_setprio 1
	s_barrier
	v_mfma_f32_16x16x32_bf16 v[126:129], v[148:151], v[180:183], v[126:129]
	v_mfma_f32_16x16x32_bf16 v[122:125], v[156:159], v[180:183], v[122:125]
	v_mfma_f32_16x16x32_bf16 v[118:121], v[148:151], v[188:191], v[118:121]
	v_mfma_f32_16x16x32_bf16 v[114:117], v[156:159], v[188:191], v[114:117]
	v_mfma_f32_16x16x32_bf16 v[106:109], v[148:151], v[196:199], v[106:109]
	v_mfma_f32_16x16x32_bf16 v[98:101], v[156:159], v[196:199], v[98:101]
	v_mfma_f32_16x16x32_bf16 v[90:93], v[148:151], v[204:207], v[90:93]
	v_mfma_f32_16x16x32_bf16 v[82:85], v[156:159], v[204:207], v[82:85]
	v_mfma_f32_16x16x32_bf16 v[126:129], v[152:155], v[184:187], v[126:129]
	v_mfma_f32_16x16x32_bf16 v[122:125], v[160:163], v[184:187], v[122:125]
	v_mfma_f32_16x16x32_bf16 v[118:121], v[152:155], v[192:195], v[118:121]
	v_mfma_f32_16x16x32_bf16 v[114:117], v[160:163], v[192:195], v[114:117]
	v_mfma_f32_16x16x32_bf16 v[106:109], v[152:155], v[200:203], v[106:109]
	v_mfma_f32_16x16x32_bf16 v[98:101], v[160:163], v[200:203], v[98:101]
	v_mfma_f32_16x16x32_bf16 v[90:93], v[152:155], v[208:211], v[90:93]
	v_mfma_f32_16x16x32_bf16 v[82:85], v[160:163], v[208:211], v[82:85]
	v_mfma_f32_16x16x32_bf16 v[110:113], v[164:167], v[180:183], v[110:113]
	v_mfma_f32_16x16x32_bf16 v[102:105], v[172:175], v[180:183], v[102:105]
	v_mfma_f32_16x16x32_bf16 v[94:97], v[164:167], v[188:191], v[94:97]
	v_mfma_f32_16x16x32_bf16 v[86:89], v[172:175], v[188:191], v[86:89]
	v_mfma_f32_16x16x32_bf16 v[78:81], v[164:167], v[196:199], v[78:81]
	v_mfma_f32_16x16x32_bf16 v[74:77], v[172:175], v[196:199], v[74:77]
	v_mfma_f32_16x16x32_bf16 v[70:73], v[164:167], v[204:207], v[70:73]
	v_mfma_f32_16x16x32_bf16 v[66:69], v[172:175], v[204:207], v[66:69]
	v_mfma_f32_16x16x32_bf16 v[110:113], v[168:171], v[184:187], v[110:113]
	v_mfma_f32_16x16x32_bf16 v[102:105], v[176:179], v[184:187], v[102:105]
	v_mfma_f32_16x16x32_bf16 v[94:97], v[168:171], v[192:195], v[94:97]
	v_mfma_f32_16x16x32_bf16 v[86:89], v[176:179], v[192:195], v[86:89]
	v_mfma_f32_16x16x32_bf16 v[78:81], v[168:171], v[200:203], v[78:81]
	v_mfma_f32_16x16x32_bf16 v[74:77], v[176:179], v[200:203], v[74:77]
	v_mfma_f32_16x16x32_bf16 v[70:73], v[168:171], v[208:211], v[70:73]
	v_mfma_f32_16x16x32_bf16 v[66:69], v[176:179], v[208:211], v[66:69]
	s_barrier
	s_setprio 0
	s_mov_b32 m0, s30
	v_lshl_add_u64 v[212:213], s[12:13], 0, v[132:133]
	s_add_u32 s8, s12, 0x160000
	ds_read_b128 v[180:183], v145 offset:16384
	ds_read_b128 v[184:187], v145 offset:17408
	ds_read_b128 v[188:191], v145 offset:18432
	ds_read_b128 v[192:195], v145 offset:19456
	ds_read_b128 v[196:199], v145 offset:20480
	ds_read_b128 v[200:203], v145 offset:21504
	ds_read_b128 v[204:207], v145 offset:22528
	ds_read_b128 v[208:211], v145 offset:23552
	global_load_lds_dwordx4 v[212:213], off
	v_lshl_add_u64 v[214:215], s[12:13], 0, v[136:137]
	s_mov_b32 m0, s31
	s_addc_u32 s9, s13, 0
	global_load_lds_dwordx4 v[214:215], off
	v_lshl_add_u64 v[216:217], s[8:9], 0, v[132:133]
	s_mov_b32 m0, s33
	v_lshl_add_u64 v[218:219], s[14:15], 0, v[134:135]
	global_load_lds_dwordx4 v[216:217], off
	v_lshl_add_u64 v[216:217], s[8:9], 0, v[136:137]
	s_mov_b32 m0, s34
	s_nop 0
	global_load_lds_dwordx4 v[216:217], off
	v_lshl_add_u64 v[216:217], s[14:15], 0, v[130:131]
	s_mov_b32 m0, s19
	s_nop 0
	global_load_lds_dwordx4 v[216:217], off
	s_mov_b32 m0, s20
	s_nop 0
	global_load_lds_dwordx4 v[218:219], off
	s_waitcnt vmcnt(8)
	s_waitcnt lgkmcnt(0)
	s_setprio 1
	s_barrier
	v_mfma_f32_16x16x32_bf16 v[62:65], v[148:151], v[180:183], v[62:65]
	v_mfma_f32_16x16x32_bf16 v[58:61], v[156:159], v[180:183], v[58:61]
	v_mfma_f32_16x16x32_bf16 v[54:57], v[148:151], v[188:191], v[54:57]
	v_mfma_f32_16x16x32_bf16 v[50:53], v[156:159], v[188:191], v[50:53]
	v_mfma_f32_16x16x32_bf16 v[42:45], v[148:151], v[196:199], v[42:45]
	v_mfma_f32_16x16x32_bf16 v[34:37], v[156:159], v[196:199], v[34:37]
	v_mfma_f32_16x16x32_bf16 v[26:29], v[148:151], v[204:207], v[26:29]
	v_mfma_f32_16x16x32_bf16 v[18:21], v[156:159], v[204:207], v[18:21]
	v_mfma_f32_16x16x32_bf16 v[62:65], v[152:155], v[184:187], v[62:65]
	v_mfma_f32_16x16x32_bf16 v[58:61], v[160:163], v[184:187], v[58:61]
	v_mfma_f32_16x16x32_bf16 v[54:57], v[152:155], v[192:195], v[54:57]
	v_mfma_f32_16x16x32_bf16 v[50:53], v[160:163], v[192:195], v[50:53]
	v_mfma_f32_16x16x32_bf16 v[42:45], v[152:155], v[200:203], v[42:45]
	v_mfma_f32_16x16x32_bf16 v[34:37], v[160:163], v[200:203], v[34:37]
	v_mfma_f32_16x16x32_bf16 v[26:29], v[152:155], v[208:211], v[26:29]
	v_mfma_f32_16x16x32_bf16 v[18:21], v[160:163], v[208:211], v[18:21]
	v_mfma_f32_16x16x32_bf16 v[46:49], v[164:167], v[180:183], v[46:49]
	v_mfma_f32_16x16x32_bf16 v[38:41], v[172:175], v[180:183], v[38:41]
	v_mfma_f32_16x16x32_bf16 v[30:33], v[164:167], v[188:191], v[30:33]
	v_mfma_f32_16x16x32_bf16 v[22:25], v[172:175], v[188:191], v[22:25]
	v_mfma_f32_16x16x32_bf16 v[14:17], v[164:167], v[196:199], v[14:17]
	v_mfma_f32_16x16x32_bf16 v[10:13], v[172:175], v[196:199], v[10:13]
	v_mfma_f32_16x16x32_bf16 v[6:9], v[164:167], v[204:207], v[6:9]
	v_mfma_f32_16x16x32_bf16 v[2:5], v[172:175], v[204:207], v[2:5]
	v_mfma_f32_16x16x32_bf16 v[46:49], v[168:171], v[184:187], v[46:49]
	v_mfma_f32_16x16x32_bf16 v[38:41], v[176:179], v[184:187], v[38:41]
	v_mfma_f32_16x16x32_bf16 v[30:33], v[168:171], v[192:195], v[30:33]
	v_mfma_f32_16x16x32_bf16 v[22:25], v[176:179], v[192:195], v[22:25]
	v_mfma_f32_16x16x32_bf16 v[14:17], v[168:171], v[200:203], v[14:17]
	v_mfma_f32_16x16x32_bf16 v[10:13], v[176:179], v[200:203], v[10:13]
	v_mfma_f32_16x16x32_bf16 v[6:9], v[168:171], v[208:211], v[6:9]
	v_mfma_f32_16x16x32_bf16 v[2:5], v[176:179], v[208:211], v[2:5]
	s_barrier
	s_setprio 0
	ds_read_b128 v[148:151], v146
	ds_read_b128 v[152:155], v146 offset:1024
	ds_read_b128 v[156:159], v146 offset:2048
	ds_read_b128 v[160:163], v146 offset:3072
	ds_read_b128 v[164:167], v147
	ds_read_b128 v[168:171], v147 offset:1024
	ds_read_b128 v[172:175], v147 offset:2048
	ds_read_b128 v[176:179], v147 offset:3072
	s_add_u32 s8, s14, 0x160000
	s_addc_u32 s9, s15, 0
	s_mov_b32 m0, s21
	v_lshl_add_u64 v[220:221], s[8:9], 0, v[130:131]
	ds_read_b128 v[180:183], v145 offset:32768
	ds_read_b128 v[184:187], v145 offset:33792
	ds_read_b128 v[188:191], v145 offset:34816
	ds_read_b128 v[192:195], v145 offset:35840
	ds_read_b128 v[196:199], v145 offset:36864
	ds_read_b128 v[200:203], v145 offset:37888
	ds_read_b128 v[204:207], v145 offset:38912
	ds_read_b128 v[208:211], v145 offset:39936
	global_load_lds_dwordx4 v[220:221], off
	v_lshl_add_u64 v[220:221], s[8:9], 0, v[134:135]
	s_mov_b32 m0, s23
	s_nop 0
	global_load_lds_dwordx4 v[220:221], off
	s_waitcnt vmcnt(8)
	s_waitcnt lgkmcnt(0)
	s_setprio 1
	s_barrier
	v_mfma_f32_16x16x32_bf16 v[126:129], v[148:151], v[180:183], v[126:129]
	v_mfma_f32_16x16x32_bf16 v[122:125], v[156:159], v[180:183], v[122:125]
	v_mfma_f32_16x16x32_bf16 v[118:121], v[148:151], v[188:191], v[118:121]
	v_mfma_f32_16x16x32_bf16 v[114:117], v[156:159], v[188:191], v[114:117]
	v_mfma_f32_16x16x32_bf16 v[106:109], v[148:151], v[196:199], v[106:109]
	v_mfma_f32_16x16x32_bf16 v[98:101], v[156:159], v[196:199], v[98:101]
	v_mfma_f32_16x16x32_bf16 v[90:93], v[148:151], v[204:207], v[90:93]
	v_mfma_f32_16x16x32_bf16 v[82:85], v[156:159], v[204:207], v[82:85]
	v_mfma_f32_16x16x32_bf16 v[126:129], v[152:155], v[184:187], v[126:129]
	v_mfma_f32_16x16x32_bf16 v[122:125], v[160:163], v[184:187], v[122:125]
	v_mfma_f32_16x16x32_bf16 v[118:121], v[152:155], v[192:195], v[118:121]
	v_mfma_f32_16x16x32_bf16 v[114:117], v[160:163], v[192:195], v[114:117]
	v_mfma_f32_16x16x32_bf16 v[106:109], v[152:155], v[200:203], v[106:109]
	v_mfma_f32_16x16x32_bf16 v[98:101], v[160:163], v[200:203], v[98:101]
	v_mfma_f32_16x16x32_bf16 v[90:93], v[152:155], v[208:211], v[90:93]
	v_mfma_f32_16x16x32_bf16 v[82:85], v[160:163], v[208:211], v[82:85]
	v_mfma_f32_16x16x32_bf16 v[110:113], v[164:167], v[180:183], v[110:113]
	v_mfma_f32_16x16x32_bf16 v[102:105], v[172:175], v[180:183], v[102:105]
	v_mfma_f32_16x16x32_bf16 v[94:97], v[164:167], v[188:191], v[94:97]
	v_mfma_f32_16x16x32_bf16 v[86:89], v[172:175], v[188:191], v[86:89]
	v_mfma_f32_16x16x32_bf16 v[78:81], v[164:167], v[196:199], v[78:81]
	v_mfma_f32_16x16x32_bf16 v[74:77], v[172:175], v[196:199], v[74:77]
	v_mfma_f32_16x16x32_bf16 v[70:73], v[164:167], v[204:207], v[70:73]
	v_mfma_f32_16x16x32_bf16 v[66:69], v[172:175], v[204:207], v[66:69]
	v_mfma_f32_16x16x32_bf16 v[110:113], v[168:171], v[184:187], v[110:113]
	v_mfma_f32_16x16x32_bf16 v[102:105], v[176:179], v[184:187], v[102:105]
	v_mfma_f32_16x16x32_bf16 v[94:97], v[168:171], v[192:195], v[94:97]
	v_mfma_f32_16x16x32_bf16 v[86:89], v[176:179], v[192:195], v[86:89]
	v_mfma_f32_16x16x32_bf16 v[78:81], v[168:171], v[200:203], v[78:81]
	v_mfma_f32_16x16x32_bf16 v[74:77], v[176:179], v[200:203], v[74:77]
	v_mfma_f32_16x16x32_bf16 v[70:73], v[168:171], v[208:211], v[70:73]
	v_mfma_f32_16x16x32_bf16 v[66:69], v[176:179], v[208:211], v[66:69]
	s_barrier
	s_setprio 0
	s_mov_b32 m0, s35
	v_lshl_add_u64 v[212:213], v[212:213], 0, s[6:7]
	s_add_u32 s8, s12, 0x160080
	ds_read_b128 v[180:183], v145 offset:49152
	ds_read_b128 v[184:187], v145 offset:50176
	ds_read_b128 v[188:191], v145 offset:51200
	ds_read_b128 v[192:195], v145 offset:52224
	ds_read_b128 v[196:199], v145 offset:53248
	ds_read_b128 v[200:203], v145 offset:54272
	ds_read_b128 v[204:207], v145 offset:55296
	ds_read_b128 v[208:211], v145 offset:56320
	global_load_lds_dwordx4 v[212:213], off
	v_lshl_add_u64 v[212:213], v[214:215], 0, s[6:7]
	s_mov_b32 m0, s36
	s_addc_u32 s9, s13, 0
	global_load_lds_dwordx4 v[212:213], off
	v_lshl_add_u64 v[212:213], s[8:9], 0, v[132:133]
	s_mov_b32 m0, s37
	s_nop 0
	global_load_lds_dwordx4 v[212:213], off
	v_lshl_add_u64 v[212:213], s[8:9], 0, v[136:137]
	s_mov_b32 m0, s38
	s_nop 0
	global_load_lds_dwordx4 v[212:213], off
	v_lshl_add_u64 v[212:213], v[216:217], 0, s[6:7]
	s_mov_b32 m0, s25
	s_nop 0
	global_load_lds_dwordx4 v[212:213], off
	v_lshl_add_u64 v[212:213], v[218:219], 0, s[6:7]
	s_mov_b32 m0, s26
	s_nop 0
	global_load_lds_dwordx4 v[212:213], off
	s_waitcnt vmcnt(8)
	s_waitcnt lgkmcnt(0)
	s_setprio 1
	s_barrier
	v_mfma_f32_16x16x32_bf16 v[62:65], v[148:151], v[180:183], v[62:65]
	v_mfma_f32_16x16x32_bf16 v[58:61], v[156:159], v[180:183], v[58:61]
	v_mfma_f32_16x16x32_bf16 v[54:57], v[148:151], v[188:191], v[54:57]
	v_mfma_f32_16x16x32_bf16 v[50:53], v[156:159], v[188:191], v[50:53]
	v_mfma_f32_16x16x32_bf16 v[42:45], v[148:151], v[196:199], v[42:45]
	v_mfma_f32_16x16x32_bf16 v[34:37], v[156:159], v[196:199], v[34:37]
	v_mfma_f32_16x16x32_bf16 v[26:29], v[148:151], v[204:207], v[26:29]
	v_mfma_f32_16x16x32_bf16 v[18:21], v[156:159], v[204:207], v[18:21]
	v_mfma_f32_16x16x32_bf16 v[62:65], v[152:155], v[184:187], v[62:65]
	v_mfma_f32_16x16x32_bf16 v[58:61], v[160:163], v[184:187], v[58:61]
	v_mfma_f32_16x16x32_bf16 v[54:57], v[152:155], v[192:195], v[54:57]
	v_mfma_f32_16x16x32_bf16 v[50:53], v[160:163], v[192:195], v[50:53]
	v_mfma_f32_16x16x32_bf16 v[42:45], v[152:155], v[200:203], v[42:45]
	v_mfma_f32_16x16x32_bf16 v[34:37], v[160:163], v[200:203], v[34:37]
	v_mfma_f32_16x16x32_bf16 v[26:29], v[152:155], v[208:211], v[26:29]
	v_mfma_f32_16x16x32_bf16 v[18:21], v[160:163], v[208:211], v[18:21]
	v_mfma_f32_16x16x32_bf16 v[46:49], v[164:167], v[180:183], v[46:49]
	v_mfma_f32_16x16x32_bf16 v[38:41], v[172:175], v[180:183], v[38:41]
	v_mfma_f32_16x16x32_bf16 v[30:33], v[164:167], v[188:191], v[30:33]
	v_mfma_f32_16x16x32_bf16 v[22:25], v[172:175], v[188:191], v[22:25]
	v_mfma_f32_16x16x32_bf16 v[14:17], v[164:167], v[196:199], v[14:17]
	v_mfma_f32_16x16x32_bf16 v[10:13], v[172:175], v[196:199], v[10:13]
	v_mfma_f32_16x16x32_bf16 v[6:9], v[164:167], v[204:207], v[6:9]
	v_mfma_f32_16x16x32_bf16 v[2:5], v[172:175], v[204:207], v[2:5]
	v_mfma_f32_16x16x32_bf16 v[46:49], v[168:171], v[184:187], v[46:49]
	v_mfma_f32_16x16x32_bf16 v[38:41], v[176:179], v[184:187], v[38:41]
	v_mfma_f32_16x16x32_bf16 v[30:33], v[168:171], v[192:195], v[30:33]
	v_mfma_f32_16x16x32_bf16 v[22:25], v[176:179], v[192:195], v[22:25]
	v_mfma_f32_16x16x32_bf16 v[14:17], v[168:171], v[200:203], v[14:17]
	v_mfma_f32_16x16x32_bf16 v[10:13], v[176:179], v[200:203], v[10:13]
	v_mfma_f32_16x16x32_bf16 v[6:9], v[168:171], v[208:211], v[6:9]
	v_mfma_f32_16x16x32_bf16 v[2:5], v[176:179], v[208:211], v[2:5]
	s_barrier
	s_setprio 0
	s_add_i32 s27, s27, 2
	s_cmp_gt_u32 s27, 19
	s_mov_b64 s[8:9], s[10:11]
	s_cbranch_scc0 .LBB0_1945
	s_cmpk_lt_u32 s18, 0x100
	s_cbranch_scc0 .LBB0_1948
	s_barrier
